# cross attention: both 128-query items of a workgroup in one pass (K/V fragments shared by two MFMAs) + first grid barrier: 16 counter loads issued together
# speedup vs baseline: 1.0140x; 1.0089x over previous
; #define LAS __attribute__((address_space(3)))
; __device__ __forceinline__ int opaque_tid() { int t = (int)threadIdx.x; asm volatile("" : "+v"(t)); return t; }
; __device__ __forceinline__ f32x4 mfma16(bf16x8 a, bf16x8 b, f32x4 c) { return __builtin_amdgcn_mfma_f32_16x16x32_bf16(a, b, c, 0, 0, 0); }
; #define LDS_BARRIER() do { asm volatile("s_waitcnt lgkmcnt(0)" ::: "memory"); __builtin_amdgcn_s_barrier(); asm volatile("" ::: "memory"); } while (0)
; __device__ void cross_items(const Params& p, LAS unsigned char* lds) {
;     const int tid = opaque_tid(), lane = tid & 63, w = __builtin_amdgcn_readfirstlane(tid >> 6), idx = lane & 15, g = lane >> 4;
;     unsigned char* ws = p.ws;
;     bf16_t* oc = (bf16_t*)(ws + OFF_OC);
;     const unsigned lbase = (unsigned)(size_t)lds;
;     const int piece = tid & 15, srow = tid >> 4;
;     const int G = (int)gridDim.x;
;     u32x4 pre[8];
;     ...
;     const int pmx = 8 * ((int)blockIdx.x & 7) + ((int)blockIdx.x >> 5), hdx = ((int)blockIdx.x >> 3) & 3;
;     const int item0 = (pmx >> 4) * 128 + hdx * 32 + 2 * (pmx & 15);
;     { const bf16_t* kvb0 = (const bf16_t*)(ws + OFF_MKV) + (size_t)((item0 >> 7) * 256) * 4096 + ((item0 >> 5) & 3) * 512; XLOAD(kvb0, 0); }
;     for (int item = item0; item < item0 + 2; ++item) {
;         const int b = item >> 7, head = (item >> 5) & 3, qb = item & 31;
;         const size_t tok = (size_t)(b * SEQ + qb * 128 + 16 * w + idx);
;         const bf16_t* qrow = (const bf16_t*)(ws + OFF_B1) + tok * DM + head * 512 + 8 * g;
;         const bf16_t* kvb = (const bf16_t*)(ws + OFF_MKV) + (size_t)(b * 256) * 4096 + head * 512;
;         f32x4 sc[16];
; #pragma unroll
;         for (int kt = 0; kt < 16; ++kt) sc[kt] = (f32x4){0.f, 0.f, 0.f, 0.f};
;         for (int c = 0; c < 4; ++c) {
;             LAS unsigned char* buf = lds + (c & 1) * KV_BUF;
;             XSTORE(buf);
;             bf16x8 qf[4];
; #pragma unroll
;             for (int ks = 0; ks < 4; ++ks) qf[ks] = *(const bf16x8*)(qrow + c * 128 + 32 * ks);
;             XLOAD(kvb, c + 1);
;             LDS_BARRIER();
; #pragma unroll
;             for (int kt = 0; kt < 16; ++kt)
; #pragma unroll
;                 for (int ks = 0; ks < 4; ++ks) sc[kt] = mfma16(frag_row(buf, KV_STRIDE, 16 * kt, 32 * ks, idx, g), qf[ks], sc[kt]);
.LBB0_391:
	s_or_b64 exec, exec, s[0:1]
	v_mov_b32_e32 v40, v212
	s_waitcnt vmcnt(0) lgkmcnt(0)
	s_barrier
	v_readlane_b32 s0, v254, 29
	v_and_b32_e32 v243, 63, v212
	v_lshrrev_b32_e32 v242, 6, v212
	s_nop 1
	v_readfirstlane_b32 s4, v242
	s_lshr_b32 s0, s0, 9
	s_and_b32 s1, s0, 7
	s_lshl_b32 s1, s1, 3
	s_lshr_b32 s2, s0, 5
	s_add_i32 s1, s1, s2
	s_lshr_b32 s2, s0, 3
	s_and_b32 s2, s2, 3
	s_lshr_b32 s3, s1, 4
	s_add_u32 s6, s92, 0x1000
	s_addc_u32 s7, s93, 0
	v_and_b32_e32 v4, 15, v243
	v_lshrrev_b32_e32 v5, 4, v243
	v_and_b32_e32 v6, 15, v212
	v_lshrrev_b32_e32 v7, 4, v212
	v_mul_u32_u24_e32 v0, 0x110, v7
	v_lshl_add_u32 v0, v6, 4, v0
	v_add_u32_e32 v1, 0x11000, v0
	v_mul_u32_u24_e32 v2, 0x110, v4
	v_lshl_add_u32 v2, v5, 4, v2
	v_add_u32_e32 v208, 0x11000, v2
	v_lshrrev_b32_e32 v8, 2, v4
	v_lshl_add_u32 v8, v5, 2, v8
	v_mul_u32_u24_e32 v8, 0x110, v8
	v_and_b32_e32 v9, 3, v4
	v_lshl_add_u32 v209, v9, 3, v8
	v_add_u32_e32 v210, 0x11000, v209
	s_lshl_b32 s5, s1, 20
	s_lshl_b32 s8, s4, 16
	s_add_i32 s5, s5, s8
	s_lshl_b32 s8, s2, 10
	s_add_i32 s5, s5, s8
	v_lshlrev_b32_e32 v246, 12, v4
	v_add_u32_e32 v246, s5, v246
	v_lshl_add_u32 v248, v5, 3, v246
	v_add_u32_e32 v248, 0xd100000, v248
	v_add_u32_e32 v249, 0x80000, v248
	v_lshl_add_u32 v246, v5, 4, v246
	v_add_u32_e32 v247, 0x80000, v246
	s_lshl_b32 s5, s3, 21
	s_add_i32 s5, s5, s8
	s_add_i32 s5, s5, 0xc400000
	v_lshlrev_b32_e32 v242, 13, v7
	v_lshl_add_u32 v242, v6, 4, v242
	v_add_u32_e32 v242, s5, v242
	global_load_dwordx4 v[164:167], v242, s[92:93]
	v_add_u32_e32 v243, 0x40000, v242
	global_load_dwordx4 v[168:171], v243, s[92:93]
	v_add_u32_e32 v243, 0x80000, v242
	global_load_dwordx4 v[172:175], v243, s[92:93]
	v_add_u32_e32 v243, 0xc0000, v242
	global_load_dwordx4 v[176:179], v243, s[92:93]
	v_add_u32_e32 v243, 0x100000, v242
	global_load_dwordx4 v[180:183], v243, s[92:93]
	v_add_u32_e32 v243, 0x140000, v242
	global_load_dwordx4 v[184:187], v243, s[92:93]
	v_add_u32_e32 v243, 0x180000, v242
	global_load_dwordx4 v[188:191], v243, s[92:93]
	v_add_u32_e32 v243, 0x1c0000, v242
	global_load_dwordx4 v[192:195], v243, s[92:93]
	s_waitcnt vmcnt(7)
	ds_write_b128 v0, v[164:167]
	s_waitcnt vmcnt(6)
	ds_write_b128 v0, v[168:171] offset:8704
	s_waitcnt vmcnt(5)
	ds_write_b128 v0, v[172:175] offset:17408
	s_waitcnt vmcnt(4)
	ds_write_b128 v0, v[176:179] offset:26112
	s_waitcnt vmcnt(3)
	ds_write_b128 v0, v[180:183] offset:34816
	s_waitcnt vmcnt(2)
	ds_write_b128 v0, v[184:187] offset:43520
	s_waitcnt vmcnt(1)
	ds_write_b128 v0, v[188:191] offset:52224
	s_waitcnt vmcnt(0)
	ds_write_b128 v0, v[192:195] offset:60928
	global_load_dwordx4 v[132:135], v246, s[92:93] offset:0
	global_load_dwordx4 v[136:139], v246, s[92:93] offset:64
	global_load_dwordx4 v[140:143], v246, s[92:93] offset:128
	global_load_dwordx4 v[144:147], v246, s[92:93] offset:192
	global_load_dwordx4 v[148:151], v247, s[92:93] offset:0
	global_load_dwordx4 v[152:155], v247, s[92:93] offset:64
	global_load_dwordx4 v[156:159], v247, s[92:93] offset:128
	global_load_dwordx4 v[160:163], v247, s[92:93] offset:192
	global_load_dwordx4 v[164:167], v242, s[92:93] offset:256
	v_add_u32_e32 v243, 0x40000, v242
	global_load_dwordx4 v[168:171], v243, s[92:93] offset:256
	v_add_u32_e32 v243, 0x80000, v242
	global_load_dwordx4 v[172:175], v243, s[92:93] offset:256
	v_add_u32_e32 v243, 0xc0000, v242
	global_load_dwordx4 v[176:179], v243, s[92:93] offset:256
	v_add_u32_e32 v243, 0x100000, v242
	global_load_dwordx4 v[180:183], v243, s[92:93] offset:256
	v_add_u32_e32 v243, 0x140000, v242
	global_load_dwordx4 v[184:187], v243, s[92:93] offset:256
	v_add_u32_e32 v243, 0x180000, v242
	global_load_dwordx4 v[188:191], v243, s[92:93] offset:256
	v_add_u32_e32 v243, 0x1c0000, v242
	global_load_dwordx4 v[192:195], v243, s[92:93] offset:256
	s_waitcnt lgkmcnt(0)
	s_barrier
	ds_read_b128 v[196:199], v2
	ds_read_b128 v[200:203], v2 offset:4352
	ds_read_b128 v[204:207], v2 offset:64
	ds_read_b128 v[220:223], v2 offset:4416
	ds_read_b128 v[230:233], v2 offset:128
	ds_read_b128 v[234:237], v2 offset:4480
	ds_read_b128 v[238:241], v2 offset:192
	s_waitcnt vmcnt(8) lgkmcnt(6)
	v_mfma_f32_16x16x32_bf16 v[4:7], v[196:199], v[132:135], 0
	v_mfma_f32_16x16x32_bf16 v[68:71], v[196:199], v[148:151], 0
	ds_read_b128 v[196:199], v2 offset:4544
	s_waitcnt lgkmcnt(6)
	v_mfma_f32_16x16x32_bf16 v[8:11], v[200:203], v[132:135], 0
	v_mfma_f32_16x16x32_bf16 v[72:75], v[200:203], v[148:151], 0
	ds_read_b128 v[200:203], v2 offset:8704
	s_waitcnt lgkmcnt(6)
	v_mfma_f32_16x16x32_bf16 v[4:7], v[204:207], v[136:139], v[4:7]
	v_mfma_f32_16x16x32_bf16 v[68:71], v[204:207], v[152:155], v[68:71]
	ds_read_b128 v[204:207], v2 offset:13056
	s_waitcnt lgkmcnt(6)
	v_mfma_f32_16x16x32_bf16 v[8:11], v[220:223], v[136:139], v[8:11]
	v_mfma_f32_16x16x32_bf16 v[72:75], v[220:223], v[152:155], v[72:75]
	ds_read_b128 v[220:223], v2 offset:8768
	s_waitcnt lgkmcnt(6)
	v_mfma_f32_16x16x32_bf16 v[4:7], v[230:233], v[140:143], v[4:7]
	v_mfma_f32_16x16x32_bf16 v[68:71], v[230:233], v[156:159], v[68:71]
	ds_read_b128 v[230:233], v2 offset:13120
	s_waitcnt lgkmcnt(6)
	v_mfma_f32_16x16x32_bf16 v[8:11], v[234:237], v[140:143], v[8:11]
	v_mfma_f32_16x16x32_bf16 v[72:75], v[234:237], v[156:159], v[72:75]
	ds_read_b128 v[234:237], v2 offset:8832
	s_waitcnt lgkmcnt(6)
	v_mfma_f32_16x16x32_bf16 v[4:7], v[238:241], v[144:147], v[4:7]
	v_mfma_f32_16x16x32_bf16 v[68:71], v[238:241], v[160:163], v[68:71]
	ds_read_b128 v[238:241], v2 offset:13184
	s_waitcnt lgkmcnt(6)
	v_mfma_f32_16x16x32_bf16 v[8:11], v[196:199], v[144:147], v[8:11]
	v_mfma_f32_16x16x32_bf16 v[72:75], v[196:199], v[160:163], v[72:75]
	ds_read_b128 v[196:199], v2 offset:8896
	s_waitcnt lgkmcnt(6)
; __device__ __forceinline__ f32x4 mfma16(bf16x8 a, bf16x8 b, f32x4 c) { return __builtin_amdgcn_mfma_f32_16x16x32_bf16(a, b, c, 0, 0, 0); }
; __device__ void cross_items(const Params& p, LAS unsigned char* lds) {
;     ...
; #pragma unroll
;             for (int kt = 0; kt < 16; ++kt)
; #pragma unroll
;                 for (int ks = 0; ks < 4; ++ks) sc[kt] = mfma16(frag_row(buf, KV_STRIDE, 16 * kt, 32 * ks, idx, g), qf[ks], sc[kt]);
	v_mfma_f32_16x16x32_bf16 v[12:15], v[200:203], v[132:135], 0
	v_mfma_f32_16x16x32_bf16 v[76:79], v[200:203], v[148:151], 0
	ds_read_b128 v[200:203], v2 offset:13248
	s_waitcnt lgkmcnt(6)
	v_mfma_f32_16x16x32_bf16 v[16:19], v[204:207], v[132:135], 0
	v_mfma_f32_16x16x32_bf16 v[80:83], v[204:207], v[148:151], 0
	ds_read_b128 v[204:207], v2 offset:17408
	s_waitcnt lgkmcnt(6)
	v_mfma_f32_16x16x32_bf16 v[12:15], v[220:223], v[136:139], v[12:15]
	v_mfma_f32_16x16x32_bf16 v[76:79], v[220:223], v[152:155], v[76:79]
	ds_read_b128 v[220:223], v2 offset:21760
	s_waitcnt lgkmcnt(6)
	v_mfma_f32_16x16x32_bf16 v[16:19], v[230:233], v[136:139], v[16:19]
	v_mfma_f32_16x16x32_bf16 v[80:83], v[230:233], v[152:155], v[80:83]
	ds_read_b128 v[230:233], v2 offset:17472
	s_waitcnt lgkmcnt(6)
	v_mfma_f32_16x16x32_bf16 v[12:15], v[234:237], v[140:143], v[12:15]
	v_mfma_f32_16x16x32_bf16 v[76:79], v[234:237], v[156:159], v[76:79]
	ds_read_b128 v[234:237], v2 offset:21824
	s_waitcnt lgkmcnt(6)
	v_mfma_f32_16x16x32_bf16 v[16:19], v[238:241], v[140:143], v[16:19]
	v_mfma_f32_16x16x32_bf16 v[80:83], v[238:241], v[156:159], v[80:83]
	ds_read_b128 v[238:241], v2 offset:17536
	s_waitcnt lgkmcnt(6)
	v_mfma_f32_16x16x32_bf16 v[12:15], v[196:199], v[144:147], v[12:15]
	v_mfma_f32_16x16x32_bf16 v[76:79], v[196:199], v[160:163], v[76:79]
	ds_read_b128 v[196:199], v2 offset:21888
	s_waitcnt lgkmcnt(6)
	v_mfma_f32_16x16x32_bf16 v[16:19], v[200:203], v[144:147], v[16:19]
	v_mfma_f32_16x16x32_bf16 v[80:83], v[200:203], v[160:163], v[80:83]
	ds_read_b128 v[200:203], v2 offset:17600
	s_waitcnt lgkmcnt(6)
	v_mfma_f32_16x16x32_bf16 v[20:23], v[204:207], v[132:135], 0
	v_mfma_f32_16x16x32_bf16 v[84:87], v[204:207], v[148:151], 0
	ds_read_b128 v[204:207], v2 offset:21952
	s_waitcnt lgkmcnt(6)
	v_mfma_f32_16x16x32_bf16 v[24:27], v[220:223], v[132:135], 0
	v_mfma_f32_16x16x32_bf16 v[88:91], v[220:223], v[148:151], 0
	ds_read_b128 v[220:223], v2 offset:26112
	s_waitcnt lgkmcnt(6)
	v_mfma_f32_16x16x32_bf16 v[20:23], v[230:233], v[136:139], v[20:23]
	v_mfma_f32_16x16x32_bf16 v[84:87], v[230:233], v[152:155], v[84:87]
	ds_read_b128 v[230:233], v2 offset:30464
	s_waitcnt lgkmcnt(6)
	v_mfma_f32_16x16x32_bf16 v[24:27], v[234:237], v[136:139], v[24:27]
	v_mfma_f32_16x16x32_bf16 v[88:91], v[234:237], v[152:155], v[88:91]
	ds_read_b128 v[234:237], v2 offset:26176
	s_waitcnt lgkmcnt(6)
	v_mfma_f32_16x16x32_bf16 v[20:23], v[238:241], v[140:143], v[20:23]
	v_mfma_f32_16x16x32_bf16 v[84:87], v[238:241], v[156:159], v[84:87]
	ds_read_b128 v[238:241], v2 offset:30528
	s_waitcnt lgkmcnt(6)
	v_mfma_f32_16x16x32_bf16 v[24:27], v[196:199], v[140:143], v[24:27]
	v_mfma_f32_16x16x32_bf16 v[88:91], v[196:199], v[156:159], v[88:91]
	ds_read_b128 v[196:199], v2 offset:26240
	s_waitcnt lgkmcnt(6)
	v_mfma_f32_16x16x32_bf16 v[20:23], v[200:203], v[144:147], v[20:23]
	v_mfma_f32_16x16x32_bf16 v[84:87], v[200:203], v[160:163], v[84:87]
	ds_read_b128 v[200:203], v2 offset:30592
	s_waitcnt lgkmcnt(6)
	v_mfma_f32_16x16x32_bf16 v[24:27], v[204:207], v[144:147], v[24:27]
	v_mfma_f32_16x16x32_bf16 v[88:91], v[204:207], v[160:163], v[88:91]
	ds_read_b128 v[204:207], v2 offset:26304
	s_waitcnt lgkmcnt(6)
	v_mfma_f32_16x16x32_bf16 v[28:31], v[220:223], v[132:135], 0
	v_mfma_f32_16x16x32_bf16 v[92:95], v[220:223], v[148:151], 0
	ds_read_b128 v[220:223], v2 offset:30656
	s_waitcnt lgkmcnt(6)
	v_mfma_f32_16x16x32_bf16 v[32:35], v[230:233], v[132:135], 0
	v_mfma_f32_16x16x32_bf16 v[96:99], v[230:233], v[148:151], 0
	ds_read_b128 v[230:233], v2 offset:34816
	s_waitcnt lgkmcnt(6)
	v_mfma_f32_16x16x32_bf16 v[28:31], v[234:237], v[136:139], v[28:31]
	v_mfma_f32_16x16x32_bf16 v[92:95], v[234:237], v[152:155], v[92:95]
	ds_read_b128 v[234:237], v2 offset:39168
	s_waitcnt lgkmcnt(6)
	v_mfma_f32_16x16x32_bf16 v[32:35], v[238:241], v[136:139], v[32:35]
	v_mfma_f32_16x16x32_bf16 v[96:99], v[238:241], v[152:155], v[96:99]
	ds_read_b128 v[238:241], v2 offset:34880
	s_waitcnt lgkmcnt(6)
	v_mfma_f32_16x16x32_bf16 v[28:31], v[196:199], v[140:143], v[28:31]
	v_mfma_f32_16x16x32_bf16 v[92:95], v[196:199], v[156:159], v[92:95]
	ds_read_b128 v[196:199], v2 offset:39232
	s_waitcnt lgkmcnt(6)
	v_mfma_f32_16x16x32_bf16 v[32:35], v[200:203], v[140:143], v[32:35]
	v_mfma_f32_16x16x32_bf16 v[96:99], v[200:203], v[156:159], v[96:99]
	ds_read_b128 v[200:203], v2 offset:34944
	s_waitcnt lgkmcnt(6)
	v_mfma_f32_16x16x32_bf16 v[28:31], v[204:207], v[144:147], v[28:31]
	v_mfma_f32_16x16x32_bf16 v[92:95], v[204:207], v[160:163], v[92:95]
	ds_read_b128 v[204:207], v2 offset:39296
	s_waitcnt lgkmcnt(6)
	v_mfma_f32_16x16x32_bf16 v[32:35], v[220:223], v[144:147], v[32:35]
	v_mfma_f32_16x16x32_bf16 v[96:99], v[220:223], v[160:163], v[96:99]
	ds_read_b128 v[220:223], v2 offset:35008
	s_waitcnt lgkmcnt(6)
	v_mfma_f32_16x16x32_bf16 v[36:39], v[230:233], v[132:135], 0
	v_mfma_f32_16x16x32_bf16 v[100:103], v[230:233], v[148:151], 0
	ds_read_b128 v[230:233], v2 offset:39360
	s_waitcnt lgkmcnt(6)
	v_mfma_f32_16x16x32_bf16 v[40:43], v[234:237], v[132:135], 0
	v_mfma_f32_16x16x32_bf16 v[104:107], v[234:237], v[148:151], 0
	ds_read_b128 v[234:237], v2 offset:43520
	s_waitcnt lgkmcnt(6)
	v_mfma_f32_16x16x32_bf16 v[36:39], v[238:241], v[136:139], v[36:39]
	v_mfma_f32_16x16x32_bf16 v[100:103], v[238:241], v[152:155], v[100:103]
	ds_read_b128 v[238:241], v2 offset:47872
	s_waitcnt lgkmcnt(6)
	v_mfma_f32_16x16x32_bf16 v[40:43], v[196:199], v[136:139], v[40:43]
	v_mfma_f32_16x16x32_bf16 v[104:107], v[196:199], v[152:155], v[104:107]
	ds_read_b128 v[196:199], v2 offset:43584
	s_waitcnt lgkmcnt(6)
; #define LAS __attribute__((address_space(3)))
; __device__ __forceinline__ f32x4 mfma16(bf16x8 a, bf16x8 b, f32x4 c) { return __builtin_amdgcn_mfma_f32_16x16x32_bf16(a, b, c, 0, 0, 0); }
; #define LDS_BARRIER() do { asm volatile("s_waitcnt lgkmcnt(0)" ::: "memory"); __builtin_amdgcn_s_barrier(); asm volatile("" ::: "memory"); } while (0)
; #define XLOAD(kvbase, c8) do { const bf16_t* _src = (kvbase) + (((c8) >= 4) ? 2048 : 0) + ((c8) & 3) * 128 + piece * 8; \
;         _Pragma("unroll") for (int _it = 0; _it < 8; ++_it) pre[_it] = *(const u32x4*)(_src + (size_t)(srow + 32 * _it) * 4096); } while (0)
; #define XSTORE(buf) do { _Pragma("unroll") for (int _it = 0; _it < 8; ++_it) *(LAS u32x4*)((buf) + (srow + 32 * _it) * KV_STRIDE + piece * 16) = pre[_it]; } while (0)
; __device__ void cross_items(const Params& p, LAS unsigned char* lds) {
;     ...
;         for (int c = 0; c < 4; ++c) {
;             LAS unsigned char* buf = lds + (c & 1) * KV_BUF;
;             XSTORE(buf);
;             bf16x8 qf[4];
; #pragma unroll
;             for (int ks = 0; ks < 4; ++ks) qf[ks] = *(const bf16x8*)(qrow + c * 128 + 32 * ks);
;             XLOAD(kvb, c + 1);
;             LDS_BARRIER();
; #pragma unroll
;             for (int kt = 0; kt < 16; ++kt)
; #pragma unroll
;                 for (int ks = 0; ks < 4; ++ks) sc[kt] = mfma16(frag_row(buf, KV_STRIDE, 16 * kt, 32 * ks, idx, g), qf[ks], sc[kt]);
	v_mfma_f32_16x16x32_bf16 v[36:39], v[200:203], v[140:143], v[36:39]
	v_mfma_f32_16x16x32_bf16 v[100:103], v[200:203], v[156:159], v[100:103]
	ds_read_b128 v[200:203], v2 offset:47936
	s_waitcnt lgkmcnt(6)
	v_mfma_f32_16x16x32_bf16 v[40:43], v[204:207], v[140:143], v[40:43]
	v_mfma_f32_16x16x32_bf16 v[104:107], v[204:207], v[156:159], v[104:107]
	ds_read_b128 v[204:207], v2 offset:43648
	s_waitcnt lgkmcnt(6)
	v_mfma_f32_16x16x32_bf16 v[36:39], v[220:223], v[144:147], v[36:39]
	v_mfma_f32_16x16x32_bf16 v[100:103], v[220:223], v[160:163], v[100:103]
	ds_read_b128 v[220:223], v2 offset:48000
	s_waitcnt lgkmcnt(6)
	v_mfma_f32_16x16x32_bf16 v[40:43], v[230:233], v[144:147], v[40:43]
	v_mfma_f32_16x16x32_bf16 v[104:107], v[230:233], v[160:163], v[104:107]
	ds_read_b128 v[230:233], v2 offset:43712
	s_waitcnt lgkmcnt(6)
	v_mfma_f32_16x16x32_bf16 v[44:47], v[234:237], v[132:135], 0
	v_mfma_f32_16x16x32_bf16 v[108:111], v[234:237], v[148:151], 0
	ds_read_b128 v[234:237], v2 offset:48064
	s_waitcnt lgkmcnt(6)
	v_mfma_f32_16x16x32_bf16 v[48:51], v[238:241], v[132:135], 0
	v_mfma_f32_16x16x32_bf16 v[112:115], v[238:241], v[148:151], 0
	ds_read_b128 v[238:241], v2 offset:52224
	s_waitcnt lgkmcnt(6)
	v_mfma_f32_16x16x32_bf16 v[44:47], v[196:199], v[136:139], v[44:47]
	v_mfma_f32_16x16x32_bf16 v[108:111], v[196:199], v[152:155], v[108:111]
	ds_read_b128 v[196:199], v2 offset:56576
	s_waitcnt lgkmcnt(6)
	v_mfma_f32_16x16x32_bf16 v[48:51], v[200:203], v[136:139], v[48:51]
	v_mfma_f32_16x16x32_bf16 v[112:115], v[200:203], v[152:155], v[112:115]
	ds_read_b128 v[200:203], v2 offset:52288
	s_waitcnt lgkmcnt(6)
	v_mfma_f32_16x16x32_bf16 v[44:47], v[204:207], v[140:143], v[44:47]
	v_mfma_f32_16x16x32_bf16 v[108:111], v[204:207], v[156:159], v[108:111]
	ds_read_b128 v[204:207], v2 offset:56640
	s_waitcnt lgkmcnt(6)
	v_mfma_f32_16x16x32_bf16 v[48:51], v[220:223], v[140:143], v[48:51]
	v_mfma_f32_16x16x32_bf16 v[112:115], v[220:223], v[156:159], v[112:115]
	ds_read_b128 v[220:223], v2 offset:52352
	s_waitcnt lgkmcnt(6)
	v_mfma_f32_16x16x32_bf16 v[44:47], v[230:233], v[144:147], v[44:47]
	v_mfma_f32_16x16x32_bf16 v[108:111], v[230:233], v[160:163], v[108:111]
	ds_read_b128 v[230:233], v2 offset:56704
	s_waitcnt lgkmcnt(6)
	v_mfma_f32_16x16x32_bf16 v[48:51], v[234:237], v[144:147], v[48:51]
	v_mfma_f32_16x16x32_bf16 v[112:115], v[234:237], v[160:163], v[112:115]
	ds_read_b128 v[234:237], v2 offset:52416
	s_waitcnt lgkmcnt(6)
	v_mfma_f32_16x16x32_bf16 v[52:55], v[238:241], v[132:135], 0
	v_mfma_f32_16x16x32_bf16 v[116:119], v[238:241], v[148:151], 0
	ds_read_b128 v[238:241], v2 offset:56768
	s_waitcnt lgkmcnt(6)
	v_mfma_f32_16x16x32_bf16 v[56:59], v[196:199], v[132:135], 0
	v_mfma_f32_16x16x32_bf16 v[120:123], v[196:199], v[148:151], 0
	ds_read_b128 v[196:199], v2 offset:60928
	s_waitcnt lgkmcnt(6)
	v_mfma_f32_16x16x32_bf16 v[52:55], v[200:203], v[136:139], v[52:55]
	v_mfma_f32_16x16x32_bf16 v[116:119], v[200:203], v[152:155], v[116:119]
	ds_read_b128 v[200:203], v2 offset:65280
	s_waitcnt lgkmcnt(6)
	v_mfma_f32_16x16x32_bf16 v[56:59], v[204:207], v[136:139], v[56:59]
	v_mfma_f32_16x16x32_bf16 v[120:123], v[204:207], v[152:155], v[120:123]
	ds_read_b128 v[204:207], v2 offset:60992
	s_waitcnt lgkmcnt(6)
	v_mfma_f32_16x16x32_bf16 v[52:55], v[220:223], v[140:143], v[52:55]
	v_mfma_f32_16x16x32_bf16 v[116:119], v[220:223], v[156:159], v[116:119]
	ds_read_b128 v[220:223], v2 offset:65344
	s_waitcnt lgkmcnt(6)
	v_mfma_f32_16x16x32_bf16 v[56:59], v[230:233], v[140:143], v[56:59]
	v_mfma_f32_16x16x32_bf16 v[120:123], v[230:233], v[156:159], v[120:123]
	ds_read_b128 v[230:233], v2 offset:61056
	s_waitcnt lgkmcnt(6)
	v_mfma_f32_16x16x32_bf16 v[52:55], v[234:237], v[144:147], v[52:55]
	v_mfma_f32_16x16x32_bf16 v[116:119], v[234:237], v[160:163], v[116:119]
	ds_read_b128 v[234:237], v2 offset:65408
	s_waitcnt lgkmcnt(6)
	v_mfma_f32_16x16x32_bf16 v[56:59], v[238:241], v[144:147], v[56:59]
	v_mfma_f32_16x16x32_bf16 v[120:123], v[238:241], v[160:163], v[120:123]
	ds_read_b128 v[238:241], v2 offset:61120
	s_waitcnt lgkmcnt(6)
	v_mfma_f32_16x16x32_bf16 v[60:63], v[196:199], v[132:135], 0
	v_mfma_f32_16x16x32_bf16 v[124:127], v[196:199], v[148:151], 0
	ds_read_b128 v[196:199], v2 offset:65472
	s_waitcnt lgkmcnt(6)
	v_mfma_f32_16x16x32_bf16 v[64:67], v[200:203], v[132:135], 0
	v_mfma_f32_16x16x32_bf16 v[128:131], v[200:203], v[148:151], 0
	s_waitcnt lgkmcnt(5)
	v_mfma_f32_16x16x32_bf16 v[60:63], v[204:207], v[136:139], v[60:63]
	v_mfma_f32_16x16x32_bf16 v[124:127], v[204:207], v[152:155], v[124:127]
	s_waitcnt lgkmcnt(4)
	v_mfma_f32_16x16x32_bf16 v[64:67], v[220:223], v[136:139], v[64:67]
	v_mfma_f32_16x16x32_bf16 v[128:131], v[220:223], v[152:155], v[128:131]
	s_waitcnt lgkmcnt(3)
	v_mfma_f32_16x16x32_bf16 v[60:63], v[230:233], v[140:143], v[60:63]
	v_mfma_f32_16x16x32_bf16 v[124:127], v[230:233], v[156:159], v[124:127]
	s_waitcnt lgkmcnt(2)
	v_mfma_f32_16x16x32_bf16 v[64:67], v[234:237], v[140:143], v[64:67]
	v_mfma_f32_16x16x32_bf16 v[128:131], v[234:237], v[156:159], v[128:131]
	s_waitcnt lgkmcnt(1)
	v_mfma_f32_16x16x32_bf16 v[60:63], v[238:241], v[144:147], v[60:63]
	v_mfma_f32_16x16x32_bf16 v[124:127], v[238:241], v[160:163], v[124:127]
	s_waitcnt lgkmcnt(0)
	v_mfma_f32_16x16x32_bf16 v[64:67], v[196:199], v[144:147], v[64:67]
	v_mfma_f32_16x16x32_bf16 v[128:131], v[196:199], v[160:163], v[128:131]
	s_waitcnt vmcnt(7)
	ds_write_b128 v1, v[164:167]
	s_waitcnt vmcnt(6)
	ds_write_b128 v1, v[168:171] offset:8704
	s_waitcnt vmcnt(5)
	ds_write_b128 v1, v[172:175] offset:17408
	s_waitcnt vmcnt(4)
	ds_write_b128 v1, v[176:179] offset:26112
	s_waitcnt vmcnt(3)
; #define LAS __attribute__((address_space(3)))
; __device__ __forceinline__ f32x4 mfma16(bf16x8 a, bf16x8 b, f32x4 c) { return __builtin_amdgcn_mfma_f32_16x16x32_bf16(a, b, c, 0, 0, 0); }
; #define LDS_BARRIER() do { asm volatile("s_waitcnt lgkmcnt(0)" ::: "memory"); __builtin_amdgcn_s_barrier(); asm volatile("" ::: "memory"); } while (0)
; #define XLOAD(kvbase, c8) do { const bf16_t* _src = (kvbase) + (((c8) >= 4) ? 2048 : 0) + ((c8) & 3) * 128 + piece * 8; \
;         _Pragma("unroll") for (int _it = 0; _it < 8; ++_it) pre[_it] = *(const u32x4*)(_src + (size_t)(srow + 32 * _it) * 4096); } while (0)
; #define XSTORE(buf) do { _Pragma("unroll") for (int _it = 0; _it < 8; ++_it) *(LAS u32x4*)((buf) + (srow + 32 * _it) * KV_STRIDE + piece * 16) = pre[_it]; } while (0)
; __device__ void cross_items(const Params& p, LAS unsigned char* lds) {
;     ...
;         for (int c = 0; c < 4; ++c) {
;             LAS unsigned char* buf = lds + (c & 1) * KV_BUF;
;             XSTORE(buf);
;             bf16x8 qf[4];
; #pragma unroll
;             for (int ks = 0; ks < 4; ++ks) qf[ks] = *(const bf16x8*)(qrow + c * 128 + 32 * ks);
;             XLOAD(kvb, c + 1);
;             LDS_BARRIER();
; #pragma unroll
;             for (int kt = 0; kt < 16; ++kt)
; #pragma unroll
;                 for (int ks = 0; ks < 4; ++ks) sc[kt] = mfma16(frag_row(buf, KV_STRIDE, 16 * kt, 32 * ks, idx, g), qf[ks], sc[kt]);
	ds_write_b128 v1, v[180:183] offset:34816
	s_waitcnt vmcnt(2)
	ds_write_b128 v1, v[184:187] offset:43520
	s_waitcnt vmcnt(1)
	ds_write_b128 v1, v[188:191] offset:52224
	s_waitcnt vmcnt(0)
	ds_write_b128 v1, v[192:195] offset:60928
	global_load_dwordx4 v[132:135], v246, s[92:93] offset:256
	global_load_dwordx4 v[136:139], v246, s[92:93] offset:320
	global_load_dwordx4 v[140:143], v246, s[92:93] offset:384
	global_load_dwordx4 v[144:147], v246, s[92:93] offset:448
	global_load_dwordx4 v[148:151], v247, s[92:93] offset:256
	global_load_dwordx4 v[152:155], v247, s[92:93] offset:320
	global_load_dwordx4 v[156:159], v247, s[92:93] offset:384
	global_load_dwordx4 v[160:163], v247, s[92:93] offset:448
	global_load_dwordx4 v[164:167], v242, s[92:93] offset:512
	v_add_u32_e32 v243, 0x40000, v242
	global_load_dwordx4 v[168:171], v243, s[92:93] offset:512
	v_add_u32_e32 v243, 0x80000, v242
	global_load_dwordx4 v[172:175], v243, s[92:93] offset:512
	v_add_u32_e32 v243, 0xc0000, v242
	global_load_dwordx4 v[176:179], v243, s[92:93] offset:512
	v_add_u32_e32 v243, 0x100000, v242
	global_load_dwordx4 v[180:183], v243, s[92:93] offset:512
	v_add_u32_e32 v243, 0x140000, v242
	global_load_dwordx4 v[184:187], v243, s[92:93] offset:512
	v_add_u32_e32 v243, 0x180000, v242
	global_load_dwordx4 v[188:191], v243, s[92:93] offset:512
	v_add_u32_e32 v243, 0x1c0000, v242
	global_load_dwordx4 v[192:195], v243, s[92:93] offset:512
	s_waitcnt lgkmcnt(0)
	s_barrier
	ds_read_b128 v[196:199], v208
	ds_read_b128 v[200:203], v208 offset:4352
	ds_read_b128 v[204:207], v208 offset:64
	ds_read_b128 v[220:223], v208 offset:4416
	ds_read_b128 v[230:233], v208 offset:128
	ds_read_b128 v[234:237], v208 offset:4480
	ds_read_b128 v[238:241], v208 offset:192
	s_waitcnt vmcnt(8) lgkmcnt(6)
	v_mfma_f32_16x16x32_bf16 v[4:7], v[196:199], v[132:135], v[4:7]
	v_mfma_f32_16x16x32_bf16 v[68:71], v[196:199], v[148:151], v[68:71]
	ds_read_b128 v[196:199], v208 offset:4544
	s_waitcnt lgkmcnt(6)
	v_mfma_f32_16x16x32_bf16 v[8:11], v[200:203], v[132:135], v[8:11]
	v_mfma_f32_16x16x32_bf16 v[72:75], v[200:203], v[148:151], v[72:75]
	ds_read_b128 v[200:203], v208 offset:8704
	s_waitcnt lgkmcnt(6)
	v_mfma_f32_16x16x32_bf16 v[4:7], v[204:207], v[136:139], v[4:7]
	v_mfma_f32_16x16x32_bf16 v[68:71], v[204:207], v[152:155], v[68:71]
	ds_read_b128 v[204:207], v208 offset:13056
	s_waitcnt lgkmcnt(6)
	v_mfma_f32_16x16x32_bf16 v[8:11], v[220:223], v[136:139], v[8:11]
	v_mfma_f32_16x16x32_bf16 v[72:75], v[220:223], v[152:155], v[72:75]
	ds_read_b128 v[220:223], v208 offset:8768
	s_waitcnt lgkmcnt(6)
	v_mfma_f32_16x16x32_bf16 v[4:7], v[230:233], v[140:143], v[4:7]
	v_mfma_f32_16x16x32_bf16 v[68:71], v[230:233], v[156:159], v[68:71]
	ds_read_b128 v[230:233], v208 offset:13120
	s_waitcnt lgkmcnt(6)
	v_mfma_f32_16x16x32_bf16 v[8:11], v[234:237], v[140:143], v[8:11]
	v_mfma_f32_16x16x32_bf16 v[72:75], v[234:237], v[156:159], v[72:75]
	ds_read_b128 v[234:237], v208 offset:8832
	s_waitcnt lgkmcnt(6)
	v_mfma_f32_16x16x32_bf16 v[4:7], v[238:241], v[144:147], v[4:7]
	v_mfma_f32_16x16x32_bf16 v[68:71], v[238:241], v[160:163], v[68:71]
	ds_read_b128 v[238:241], v208 offset:13184
	s_waitcnt lgkmcnt(6)
	v_mfma_f32_16x16x32_bf16 v[8:11], v[196:199], v[144:147], v[8:11]
	v_mfma_f32_16x16x32_bf16 v[72:75], v[196:199], v[160:163], v[72:75]
	ds_read_b128 v[196:199], v208 offset:8896
	s_waitcnt lgkmcnt(6)
	v_mfma_f32_16x16x32_bf16 v[12:15], v[200:203], v[132:135], v[12:15]
	v_mfma_f32_16x16x32_bf16 v[76:79], v[200:203], v[148:151], v[76:79]
	ds_read_b128 v[200:203], v208 offset:13248
	s_waitcnt lgkmcnt(6)
	v_mfma_f32_16x16x32_bf16 v[16:19], v[204:207], v[132:135], v[16:19]
	v_mfma_f32_16x16x32_bf16 v[80:83], v[204:207], v[148:151], v[80:83]
	ds_read_b128 v[204:207], v208 offset:17408
	s_waitcnt lgkmcnt(6)
	v_mfma_f32_16x16x32_bf16 v[12:15], v[220:223], v[136:139], v[12:15]
	v_mfma_f32_16x16x32_bf16 v[76:79], v[220:223], v[152:155], v[76:79]
	ds_read_b128 v[220:223], v208 offset:21760
	s_waitcnt lgkmcnt(6)
	v_mfma_f32_16x16x32_bf16 v[16:19], v[230:233], v[136:139], v[16:19]
	v_mfma_f32_16x16x32_bf16 v[80:83], v[230:233], v[152:155], v[80:83]
	ds_read_b128 v[230:233], v208 offset:17472
	s_waitcnt lgkmcnt(6)
	v_mfma_f32_16x16x32_bf16 v[12:15], v[234:237], v[140:143], v[12:15]
	v_mfma_f32_16x16x32_bf16 v[76:79], v[234:237], v[156:159], v[76:79]
	ds_read_b128 v[234:237], v208 offset:21824
	s_waitcnt lgkmcnt(6)
	v_mfma_f32_16x16x32_bf16 v[16:19], v[238:241], v[140:143], v[16:19]
	v_mfma_f32_16x16x32_bf16 v[80:83], v[238:241], v[156:159], v[80:83]
	ds_read_b128 v[238:241], v208 offset:17536
	s_waitcnt lgkmcnt(6)
	v_mfma_f32_16x16x32_bf16 v[12:15], v[196:199], v[144:147], v[12:15]
	v_mfma_f32_16x16x32_bf16 v[76:79], v[196:199], v[160:163], v[76:79]
	ds_read_b128 v[196:199], v208 offset:21888
	s_waitcnt lgkmcnt(6)
	v_mfma_f32_16x16x32_bf16 v[16:19], v[200:203], v[144:147], v[16:19]
	v_mfma_f32_16x16x32_bf16 v[80:83], v[200:203], v[160:163], v[80:83]
	ds_read_b128 v[200:203], v208 offset:17600
	s_waitcnt lgkmcnt(6)
	v_mfma_f32_16x16x32_bf16 v[20:23], v[204:207], v[132:135], v[20:23]
	v_mfma_f32_16x16x32_bf16 v[84:87], v[204:207], v[148:151], v[84:87]
	ds_read_b128 v[204:207], v208 offset:21952
	s_waitcnt lgkmcnt(6)
	v_mfma_f32_16x16x32_bf16 v[24:27], v[220:223], v[132:135], v[24:27]
	v_mfma_f32_16x16x32_bf16 v[88:91], v[220:223], v[148:151], v[88:91]
	ds_read_b128 v[220:223], v208 offset:26112
	s_waitcnt lgkmcnt(6)
	v_mfma_f32_16x16x32_bf16 v[20:23], v[230:233], v[136:139], v[20:23]
	v_mfma_f32_16x16x32_bf16 v[84:87], v[230:233], v[152:155], v[84:87]
	ds_read_b128 v[230:233], v208 offset:30464
	s_waitcnt lgkmcnt(6)
; __device__ __forceinline__ f32x4 mfma16(bf16x8 a, bf16x8 b, f32x4 c) { return __builtin_amdgcn_mfma_f32_16x16x32_bf16(a, b, c, 0, 0, 0); }
; __device__ void cross_items(const Params& p, LAS unsigned char* lds) {
;     ...
; #pragma unroll
;             for (int kt = 0; kt < 16; ++kt)
; #pragma unroll
;                 for (int ks = 0; ks < 4; ++ks) sc[kt] = mfma16(frag_row(buf, KV_STRIDE, 16 * kt, 32 * ks, idx, g), qf[ks], sc[kt]);
	v_mfma_f32_16x16x32_bf16 v[24:27], v[234:237], v[136:139], v[24:27]
	v_mfma_f32_16x16x32_bf16 v[88:91], v[234:237], v[152:155], v[88:91]
	ds_read_b128 v[234:237], v208 offset:26176
	s_waitcnt lgkmcnt(6)
	v_mfma_f32_16x16x32_bf16 v[20:23], v[238:241], v[140:143], v[20:23]
	v_mfma_f32_16x16x32_bf16 v[84:87], v[238:241], v[156:159], v[84:87]
	ds_read_b128 v[238:241], v208 offset:30528
	s_waitcnt lgkmcnt(6)
	v_mfma_f32_16x16x32_bf16 v[24:27], v[196:199], v[140:143], v[24:27]
	v_mfma_f32_16x16x32_bf16 v[88:91], v[196:199], v[156:159], v[88:91]
	ds_read_b128 v[196:199], v208 offset:26240
	s_waitcnt lgkmcnt(6)
	v_mfma_f32_16x16x32_bf16 v[20:23], v[200:203], v[144:147], v[20:23]
	v_mfma_f32_16x16x32_bf16 v[84:87], v[200:203], v[160:163], v[84:87]
	ds_read_b128 v[200:203], v208 offset:30592
	s_waitcnt lgkmcnt(6)
	v_mfma_f32_16x16x32_bf16 v[24:27], v[204:207], v[144:147], v[24:27]
	v_mfma_f32_16x16x32_bf16 v[88:91], v[204:207], v[160:163], v[88:91]
	ds_read_b128 v[204:207], v208 offset:26304
	s_waitcnt lgkmcnt(6)
	v_mfma_f32_16x16x32_bf16 v[28:31], v[220:223], v[132:135], v[28:31]
	v_mfma_f32_16x16x32_bf16 v[92:95], v[220:223], v[148:151], v[92:95]
	ds_read_b128 v[220:223], v208 offset:30656
	s_waitcnt lgkmcnt(6)
	v_mfma_f32_16x16x32_bf16 v[32:35], v[230:233], v[132:135], v[32:35]
	v_mfma_f32_16x16x32_bf16 v[96:99], v[230:233], v[148:151], v[96:99]
	ds_read_b128 v[230:233], v208 offset:34816
	s_waitcnt lgkmcnt(6)
	v_mfma_f32_16x16x32_bf16 v[28:31], v[234:237], v[136:139], v[28:31]
	v_mfma_f32_16x16x32_bf16 v[92:95], v[234:237], v[152:155], v[92:95]
	ds_read_b128 v[234:237], v208 offset:39168
	s_waitcnt lgkmcnt(6)
	v_mfma_f32_16x16x32_bf16 v[32:35], v[238:241], v[136:139], v[32:35]
	v_mfma_f32_16x16x32_bf16 v[96:99], v[238:241], v[152:155], v[96:99]
	ds_read_b128 v[238:241], v208 offset:34880
	s_waitcnt lgkmcnt(6)
	v_mfma_f32_16x16x32_bf16 v[28:31], v[196:199], v[140:143], v[28:31]
	v_mfma_f32_16x16x32_bf16 v[92:95], v[196:199], v[156:159], v[92:95]
	ds_read_b128 v[196:199], v208 offset:39232
	s_waitcnt lgkmcnt(6)
	v_mfma_f32_16x16x32_bf16 v[32:35], v[200:203], v[140:143], v[32:35]
	v_mfma_f32_16x16x32_bf16 v[96:99], v[200:203], v[156:159], v[96:99]
	ds_read_b128 v[200:203], v208 offset:34944
	s_waitcnt lgkmcnt(6)
	v_mfma_f32_16x16x32_bf16 v[28:31], v[204:207], v[144:147], v[28:31]
	v_mfma_f32_16x16x32_bf16 v[92:95], v[204:207], v[160:163], v[92:95]
	ds_read_b128 v[204:207], v208 offset:39296
	s_waitcnt lgkmcnt(6)
	v_mfma_f32_16x16x32_bf16 v[32:35], v[220:223], v[144:147], v[32:35]
	v_mfma_f32_16x16x32_bf16 v[96:99], v[220:223], v[160:163], v[96:99]
	ds_read_b128 v[220:223], v208 offset:35008
	s_waitcnt lgkmcnt(6)
	v_mfma_f32_16x16x32_bf16 v[36:39], v[230:233], v[132:135], v[36:39]
	v_mfma_f32_16x16x32_bf16 v[100:103], v[230:233], v[148:151], v[100:103]
	ds_read_b128 v[230:233], v208 offset:39360
	s_waitcnt lgkmcnt(6)
	v_mfma_f32_16x16x32_bf16 v[40:43], v[234:237], v[132:135], v[40:43]
	v_mfma_f32_16x16x32_bf16 v[104:107], v[234:237], v[148:151], v[104:107]
	ds_read_b128 v[234:237], v208 offset:43520
	s_waitcnt lgkmcnt(6)
	v_mfma_f32_16x16x32_bf16 v[36:39], v[238:241], v[136:139], v[36:39]
	v_mfma_f32_16x16x32_bf16 v[100:103], v[238:241], v[152:155], v[100:103]
	ds_read_b128 v[238:241], v208 offset:47872
	s_waitcnt lgkmcnt(6)
	v_mfma_f32_16x16x32_bf16 v[40:43], v[196:199], v[136:139], v[40:43]
	v_mfma_f32_16x16x32_bf16 v[104:107], v[196:199], v[152:155], v[104:107]
	ds_read_b128 v[196:199], v208 offset:43584
	s_waitcnt lgkmcnt(6)
	v_mfma_f32_16x16x32_bf16 v[36:39], v[200:203], v[140:143], v[36:39]
	v_mfma_f32_16x16x32_bf16 v[100:103], v[200:203], v[156:159], v[100:103]
	ds_read_b128 v[200:203], v208 offset:47936
	s_waitcnt lgkmcnt(6)
	v_mfma_f32_16x16x32_bf16 v[40:43], v[204:207], v[140:143], v[40:43]
	v_mfma_f32_16x16x32_bf16 v[104:107], v[204:207], v[156:159], v[104:107]
	ds_read_b128 v[204:207], v208 offset:43648
	s_waitcnt lgkmcnt(6)
	v_mfma_f32_16x16x32_bf16 v[36:39], v[220:223], v[144:147], v[36:39]
	v_mfma_f32_16x16x32_bf16 v[100:103], v[220:223], v[160:163], v[100:103]
	ds_read_b128 v[220:223], v208 offset:48000
	s_waitcnt lgkmcnt(6)
	v_mfma_f32_16x16x32_bf16 v[40:43], v[230:233], v[144:147], v[40:43]
	v_mfma_f32_16x16x32_bf16 v[104:107], v[230:233], v[160:163], v[104:107]
	ds_read_b128 v[230:233], v208 offset:43712
	s_waitcnt lgkmcnt(6)
	v_mfma_f32_16x16x32_bf16 v[44:47], v[234:237], v[132:135], v[44:47]
	v_mfma_f32_16x16x32_bf16 v[108:111], v[234:237], v[148:151], v[108:111]
	ds_read_b128 v[234:237], v208 offset:48064
	s_waitcnt lgkmcnt(6)
	v_mfma_f32_16x16x32_bf16 v[48:51], v[238:241], v[132:135], v[48:51]
	v_mfma_f32_16x16x32_bf16 v[112:115], v[238:241], v[148:151], v[112:115]
	ds_read_b128 v[238:241], v208 offset:52224
	s_waitcnt lgkmcnt(6)
	v_mfma_f32_16x16x32_bf16 v[44:47], v[196:199], v[136:139], v[44:47]
	v_mfma_f32_16x16x32_bf16 v[108:111], v[196:199], v[152:155], v[108:111]
	ds_read_b128 v[196:199], v208 offset:56576
	s_waitcnt lgkmcnt(6)
	v_mfma_f32_16x16x32_bf16 v[48:51], v[200:203], v[136:139], v[48:51]
	v_mfma_f32_16x16x32_bf16 v[112:115], v[200:203], v[152:155], v[112:115]
	ds_read_b128 v[200:203], v208 offset:52288
	s_waitcnt lgkmcnt(6)
	v_mfma_f32_16x16x32_bf16 v[44:47], v[204:207], v[140:143], v[44:47]
	v_mfma_f32_16x16x32_bf16 v[108:111], v[204:207], v[156:159], v[108:111]
	ds_read_b128 v[204:207], v208 offset:56640
	s_waitcnt lgkmcnt(6)
	v_mfma_f32_16x16x32_bf16 v[48:51], v[220:223], v[140:143], v[48:51]
	v_mfma_f32_16x16x32_bf16 v[112:115], v[220:223], v[156:159], v[112:115]
	ds_read_b128 v[220:223], v208 offset:52352
	s_waitcnt lgkmcnt(6)
; #define LAS __attribute__((address_space(3)))
; __device__ __forceinline__ f32x4 mfma16(bf16x8 a, bf16x8 b, f32x4 c) { return __builtin_amdgcn_mfma_f32_16x16x32_bf16(a, b, c, 0, 0, 0); }
; #define LDS_BARRIER() do { asm volatile("s_waitcnt lgkmcnt(0)" ::: "memory"); __builtin_amdgcn_s_barrier(); asm volatile("" ::: "memory"); } while (0)
; #define XLOAD(kvbase, c8) do { const bf16_t* _src = (kvbase) + (((c8) >= 4) ? 2048 : 0) + ((c8) & 3) * 128 + piece * 8; \
;         _Pragma("unroll") for (int _it = 0; _it < 8; ++_it) pre[_it] = *(const u32x4*)(_src + (size_t)(srow + 32 * _it) * 4096); } while (0)
; #define XSTORE(buf) do { _Pragma("unroll") for (int _it = 0; _it < 8; ++_it) *(LAS u32x4*)((buf) + (srow + 32 * _it) * KV_STRIDE + piece * 16) = pre[_it]; } while (0)
; __device__ void cross_items(const Params& p, LAS unsigned char* lds) {
;     ...
;         for (int c = 0; c < 4; ++c) {
;             LAS unsigned char* buf = lds + (c & 1) * KV_BUF;
;             XSTORE(buf);
;             bf16x8 qf[4];
; #pragma unroll
;             for (int ks = 0; ks < 4; ++ks) qf[ks] = *(const bf16x8*)(qrow + c * 128 + 32 * ks);
;             XLOAD(kvb, c + 1);
;             LDS_BARRIER();
; #pragma unroll
;             for (int kt = 0; kt < 16; ++kt)
; #pragma unroll
;                 for (int ks = 0; ks < 4; ++ks) sc[kt] = mfma16(frag_row(buf, KV_STRIDE, 16 * kt, 32 * ks, idx, g), qf[ks], sc[kt]);
	v_mfma_f32_16x16x32_bf16 v[44:47], v[230:233], v[144:147], v[44:47]
	v_mfma_f32_16x16x32_bf16 v[108:111], v[230:233], v[160:163], v[108:111]
	ds_read_b128 v[230:233], v208 offset:56704
	s_waitcnt lgkmcnt(6)
	v_mfma_f32_16x16x32_bf16 v[48:51], v[234:237], v[144:147], v[48:51]
	v_mfma_f32_16x16x32_bf16 v[112:115], v[234:237], v[160:163], v[112:115]
	ds_read_b128 v[234:237], v208 offset:52416
	s_waitcnt lgkmcnt(6)
	v_mfma_f32_16x16x32_bf16 v[52:55], v[238:241], v[132:135], v[52:55]
	v_mfma_f32_16x16x32_bf16 v[116:119], v[238:241], v[148:151], v[116:119]
	ds_read_b128 v[238:241], v208 offset:56768
	s_waitcnt lgkmcnt(6)
	v_mfma_f32_16x16x32_bf16 v[56:59], v[196:199], v[132:135], v[56:59]
	v_mfma_f32_16x16x32_bf16 v[120:123], v[196:199], v[148:151], v[120:123]
	ds_read_b128 v[196:199], v208 offset:60928
	s_waitcnt lgkmcnt(6)
	v_mfma_f32_16x16x32_bf16 v[52:55], v[200:203], v[136:139], v[52:55]
	v_mfma_f32_16x16x32_bf16 v[116:119], v[200:203], v[152:155], v[116:119]
	ds_read_b128 v[200:203], v208 offset:65280
	s_waitcnt lgkmcnt(6)
	v_mfma_f32_16x16x32_bf16 v[56:59], v[204:207], v[136:139], v[56:59]
	v_mfma_f32_16x16x32_bf16 v[120:123], v[204:207], v[152:155], v[120:123]
	ds_read_b128 v[204:207], v208 offset:60992
	s_waitcnt lgkmcnt(6)
	v_mfma_f32_16x16x32_bf16 v[52:55], v[220:223], v[140:143], v[52:55]
	v_mfma_f32_16x16x32_bf16 v[116:119], v[220:223], v[156:159], v[116:119]
	ds_read_b128 v[220:223], v208 offset:65344
	s_waitcnt lgkmcnt(6)
	v_mfma_f32_16x16x32_bf16 v[56:59], v[230:233], v[140:143], v[56:59]
	v_mfma_f32_16x16x32_bf16 v[120:123], v[230:233], v[156:159], v[120:123]
	ds_read_b128 v[230:233], v208 offset:61056
	s_waitcnt lgkmcnt(6)
	v_mfma_f32_16x16x32_bf16 v[52:55], v[234:237], v[144:147], v[52:55]
	v_mfma_f32_16x16x32_bf16 v[116:119], v[234:237], v[160:163], v[116:119]
	ds_read_b128 v[234:237], v208 offset:65408
	s_waitcnt lgkmcnt(6)
	v_mfma_f32_16x16x32_bf16 v[56:59], v[238:241], v[144:147], v[56:59]
	v_mfma_f32_16x16x32_bf16 v[120:123], v[238:241], v[160:163], v[120:123]
	ds_read_b128 v[238:241], v208 offset:61120
	s_waitcnt lgkmcnt(6)
	v_mfma_f32_16x16x32_bf16 v[60:63], v[196:199], v[132:135], v[60:63]
	v_mfma_f32_16x16x32_bf16 v[124:127], v[196:199], v[148:151], v[124:127]
	ds_read_b128 v[196:199], v208 offset:65472
	s_waitcnt lgkmcnt(6)
	v_mfma_f32_16x16x32_bf16 v[64:67], v[200:203], v[132:135], v[64:67]
	v_mfma_f32_16x16x32_bf16 v[128:131], v[200:203], v[148:151], v[128:131]
	s_waitcnt lgkmcnt(5)
	v_mfma_f32_16x16x32_bf16 v[60:63], v[204:207], v[136:139], v[60:63]
	v_mfma_f32_16x16x32_bf16 v[124:127], v[204:207], v[152:155], v[124:127]
	s_waitcnt lgkmcnt(4)
	v_mfma_f32_16x16x32_bf16 v[64:67], v[220:223], v[136:139], v[64:67]
	v_mfma_f32_16x16x32_bf16 v[128:131], v[220:223], v[152:155], v[128:131]
	s_waitcnt lgkmcnt(3)
	v_mfma_f32_16x16x32_bf16 v[60:63], v[230:233], v[140:143], v[60:63]
	v_mfma_f32_16x16x32_bf16 v[124:127], v[230:233], v[156:159], v[124:127]
	s_waitcnt lgkmcnt(2)
	v_mfma_f32_16x16x32_bf16 v[64:67], v[234:237], v[140:143], v[64:67]
	v_mfma_f32_16x16x32_bf16 v[128:131], v[234:237], v[156:159], v[128:131]
	s_waitcnt lgkmcnt(1)
	v_mfma_f32_16x16x32_bf16 v[60:63], v[238:241], v[144:147], v[60:63]
	v_mfma_f32_16x16x32_bf16 v[124:127], v[238:241], v[160:163], v[124:127]
	s_waitcnt lgkmcnt(0)
	v_mfma_f32_16x16x32_bf16 v[64:67], v[196:199], v[144:147], v[64:67]
	v_mfma_f32_16x16x32_bf16 v[128:131], v[196:199], v[160:163], v[128:131]
	s_waitcnt vmcnt(7)
	ds_write_b128 v0, v[164:167]
	s_waitcnt vmcnt(6)
	ds_write_b128 v0, v[168:171] offset:8704
	s_waitcnt vmcnt(5)
	ds_write_b128 v0, v[172:175] offset:17408
	s_waitcnt vmcnt(4)
	ds_write_b128 v0, v[176:179] offset:26112
	s_waitcnt vmcnt(3)
	ds_write_b128 v0, v[180:183] offset:34816
	s_waitcnt vmcnt(2)
	ds_write_b128 v0, v[184:187] offset:43520
	s_waitcnt vmcnt(1)
	ds_write_b128 v0, v[188:191] offset:52224
	s_waitcnt vmcnt(0)
	ds_write_b128 v0, v[192:195] offset:60928
	global_load_dwordx4 v[132:135], v246, s[92:93] offset:512
	global_load_dwordx4 v[136:139], v246, s[92:93] offset:576
	global_load_dwordx4 v[140:143], v246, s[92:93] offset:640
	global_load_dwordx4 v[144:147], v246, s[92:93] offset:704
	global_load_dwordx4 v[148:151], v247, s[92:93] offset:512
	global_load_dwordx4 v[152:155], v247, s[92:93] offset:576
	global_load_dwordx4 v[156:159], v247, s[92:93] offset:640
	global_load_dwordx4 v[160:163], v247, s[92:93] offset:704
	global_load_dwordx4 v[164:167], v242, s[92:93] offset:768
	v_add_u32_e32 v243, 0x40000, v242
	global_load_dwordx4 v[168:171], v243, s[92:93] offset:768
	v_add_u32_e32 v243, 0x80000, v242
	global_load_dwordx4 v[172:175], v243, s[92:93] offset:768
	v_add_u32_e32 v243, 0xc0000, v242
	global_load_dwordx4 v[176:179], v243, s[92:93] offset:768
	v_add_u32_e32 v243, 0x100000, v242
	global_load_dwordx4 v[180:183], v243, s[92:93] offset:768
	v_add_u32_e32 v243, 0x140000, v242
	global_load_dwordx4 v[184:187], v243, s[92:93] offset:768
	v_add_u32_e32 v243, 0x180000, v242
	global_load_dwordx4 v[188:191], v243, s[92:93] offset:768
	v_add_u32_e32 v243, 0x1c0000, v242
	global_load_dwordx4 v[192:195], v243, s[92:93] offset:768
	s_waitcnt lgkmcnt(0)
	s_barrier
; __device__ __forceinline__ f32x4 mfma16(bf16x8 a, bf16x8 b, f32x4 c) { return __builtin_amdgcn_mfma_f32_16x16x32_bf16(a, b, c, 0, 0, 0); }
; __device__ void cross_items(const Params& p, LAS unsigned char* lds) {
;     ...
; #pragma unroll
;             for (int kt = 0; kt < 16; ++kt)
; #pragma unroll
;                 for (int ks = 0; ks < 4; ++ks) sc[kt] = mfma16(frag_row(buf, KV_STRIDE, 16 * kt, 32 * ks, idx, g), qf[ks], sc[kt]);
	ds_read_b128 v[196:199], v2
	ds_read_b128 v[200:203], v2 offset:4352
	ds_read_b128 v[204:207], v2 offset:64
	ds_read_b128 v[220:223], v2 offset:4416
	ds_read_b128 v[230:233], v2 offset:128
	ds_read_b128 v[234:237], v2 offset:4480
	ds_read_b128 v[238:241], v2 offset:192
	s_waitcnt vmcnt(8) lgkmcnt(6)
	v_mfma_f32_16x16x32_bf16 v[4:7], v[196:199], v[132:135], v[4:7]
	v_mfma_f32_16x16x32_bf16 v[68:71], v[196:199], v[148:151], v[68:71]
	ds_read_b128 v[196:199], v2 offset:4544
	s_waitcnt lgkmcnt(6)
	v_mfma_f32_16x16x32_bf16 v[8:11], v[200:203], v[132:135], v[8:11]
	v_mfma_f32_16x16x32_bf16 v[72:75], v[200:203], v[148:151], v[72:75]
	ds_read_b128 v[200:203], v2 offset:8704
	s_waitcnt lgkmcnt(6)
	v_mfma_f32_16x16x32_bf16 v[4:7], v[204:207], v[136:139], v[4:7]
	v_mfma_f32_16x16x32_bf16 v[68:71], v[204:207], v[152:155], v[68:71]
	ds_read_b128 v[204:207], v2 offset:13056
	s_waitcnt lgkmcnt(6)
	v_mfma_f32_16x16x32_bf16 v[8:11], v[220:223], v[136:139], v[8:11]
	v_mfma_f32_16x16x32_bf16 v[72:75], v[220:223], v[152:155], v[72:75]
	ds_read_b128 v[220:223], v2 offset:8768
	s_waitcnt lgkmcnt(6)
	v_mfma_f32_16x16x32_bf16 v[4:7], v[230:233], v[140:143], v[4:7]
	v_mfma_f32_16x16x32_bf16 v[68:71], v[230:233], v[156:159], v[68:71]
	ds_read_b128 v[230:233], v2 offset:13120
	s_waitcnt lgkmcnt(6)
	v_mfma_f32_16x16x32_bf16 v[8:11], v[234:237], v[140:143], v[8:11]
	v_mfma_f32_16x16x32_bf16 v[72:75], v[234:237], v[156:159], v[72:75]
	ds_read_b128 v[234:237], v2 offset:8832
	s_waitcnt lgkmcnt(6)
	v_mfma_f32_16x16x32_bf16 v[4:7], v[238:241], v[144:147], v[4:7]
	v_mfma_f32_16x16x32_bf16 v[68:71], v[238:241], v[160:163], v[68:71]
	ds_read_b128 v[238:241], v2 offset:13184
	s_waitcnt lgkmcnt(6)
	v_mfma_f32_16x16x32_bf16 v[8:11], v[196:199], v[144:147], v[8:11]
	v_mfma_f32_16x16x32_bf16 v[72:75], v[196:199], v[160:163], v[72:75]
	ds_read_b128 v[196:199], v2 offset:8896
	s_waitcnt lgkmcnt(6)
	v_mfma_f32_16x16x32_bf16 v[12:15], v[200:203], v[132:135], v[12:15]
	v_mfma_f32_16x16x32_bf16 v[76:79], v[200:203], v[148:151], v[76:79]
	ds_read_b128 v[200:203], v2 offset:13248
	s_waitcnt lgkmcnt(6)
	v_mfma_f32_16x16x32_bf16 v[16:19], v[204:207], v[132:135], v[16:19]
	v_mfma_f32_16x16x32_bf16 v[80:83], v[204:207], v[148:151], v[80:83]
	ds_read_b128 v[204:207], v2 offset:17408
	s_waitcnt lgkmcnt(6)
	v_mfma_f32_16x16x32_bf16 v[12:15], v[220:223], v[136:139], v[12:15]
	v_mfma_f32_16x16x32_bf16 v[76:79], v[220:223], v[152:155], v[76:79]
	ds_read_b128 v[220:223], v2 offset:21760
	s_waitcnt lgkmcnt(6)
	v_mfma_f32_16x16x32_bf16 v[16:19], v[230:233], v[136:139], v[16:19]
	v_mfma_f32_16x16x32_bf16 v[80:83], v[230:233], v[152:155], v[80:83]
	ds_read_b128 v[230:233], v2 offset:17472
	s_waitcnt lgkmcnt(6)
	v_mfma_f32_16x16x32_bf16 v[12:15], v[234:237], v[140:143], v[12:15]
	v_mfma_f32_16x16x32_bf16 v[76:79], v[234:237], v[156:159], v[76:79]
	ds_read_b128 v[234:237], v2 offset:21824
	s_waitcnt lgkmcnt(6)
	v_mfma_f32_16x16x32_bf16 v[16:19], v[238:241], v[140:143], v[16:19]
	v_mfma_f32_16x16x32_bf16 v[80:83], v[238:241], v[156:159], v[80:83]
	ds_read_b128 v[238:241], v2 offset:17536
	s_waitcnt lgkmcnt(6)
	v_mfma_f32_16x16x32_bf16 v[12:15], v[196:199], v[144:147], v[12:15]
	v_mfma_f32_16x16x32_bf16 v[76:79], v[196:199], v[160:163], v[76:79]
	ds_read_b128 v[196:199], v2 offset:21888
	s_waitcnt lgkmcnt(6)
	v_mfma_f32_16x16x32_bf16 v[16:19], v[200:203], v[144:147], v[16:19]
	v_mfma_f32_16x16x32_bf16 v[80:83], v[200:203], v[160:163], v[80:83]
	ds_read_b128 v[200:203], v2 offset:17600
	s_waitcnt lgkmcnt(6)
	v_mfma_f32_16x16x32_bf16 v[20:23], v[204:207], v[132:135], v[20:23]
	v_mfma_f32_16x16x32_bf16 v[84:87], v[204:207], v[148:151], v[84:87]
	ds_read_b128 v[204:207], v2 offset:21952
	s_waitcnt lgkmcnt(6)
	v_mfma_f32_16x16x32_bf16 v[24:27], v[220:223], v[132:135], v[24:27]
	v_mfma_f32_16x16x32_bf16 v[88:91], v[220:223], v[148:151], v[88:91]
	ds_read_b128 v[220:223], v2 offset:26112
	s_waitcnt lgkmcnt(6)
	v_mfma_f32_16x16x32_bf16 v[20:23], v[230:233], v[136:139], v[20:23]
	v_mfma_f32_16x16x32_bf16 v[84:87], v[230:233], v[152:155], v[84:87]
	ds_read_b128 v[230:233], v2 offset:30464
	s_waitcnt lgkmcnt(6)
	v_mfma_f32_16x16x32_bf16 v[24:27], v[234:237], v[136:139], v[24:27]
	v_mfma_f32_16x16x32_bf16 v[88:91], v[234:237], v[152:155], v[88:91]
	ds_read_b128 v[234:237], v2 offset:26176
	s_waitcnt lgkmcnt(6)
	v_mfma_f32_16x16x32_bf16 v[20:23], v[238:241], v[140:143], v[20:23]
	v_mfma_f32_16x16x32_bf16 v[84:87], v[238:241], v[156:159], v[84:87]
	ds_read_b128 v[238:241], v2 offset:30528
	s_waitcnt lgkmcnt(6)
	v_mfma_f32_16x16x32_bf16 v[24:27], v[196:199], v[140:143], v[24:27]
	v_mfma_f32_16x16x32_bf16 v[88:91], v[196:199], v[156:159], v[88:91]
	ds_read_b128 v[196:199], v2 offset:26240
	s_waitcnt lgkmcnt(6)
	v_mfma_f32_16x16x32_bf16 v[20:23], v[200:203], v[144:147], v[20:23]
	v_mfma_f32_16x16x32_bf16 v[84:87], v[200:203], v[160:163], v[84:87]
	ds_read_b128 v[200:203], v2 offset:30592
	s_waitcnt lgkmcnt(6)
	v_mfma_f32_16x16x32_bf16 v[24:27], v[204:207], v[144:147], v[24:27]
	v_mfma_f32_16x16x32_bf16 v[88:91], v[204:207], v[160:163], v[88:91]
	ds_read_b128 v[204:207], v2 offset:26304
	s_waitcnt lgkmcnt(6)
	v_mfma_f32_16x16x32_bf16 v[28:31], v[220:223], v[132:135], v[28:31]
	v_mfma_f32_16x16x32_bf16 v[92:95], v[220:223], v[148:151], v[92:95]
	ds_read_b128 v[220:223], v2 offset:30656
	s_waitcnt lgkmcnt(6)
	v_mfma_f32_16x16x32_bf16 v[32:35], v[230:233], v[132:135], v[32:35]
	v_mfma_f32_16x16x32_bf16 v[96:99], v[230:233], v[148:151], v[96:99]
	ds_read_b128 v[230:233], v2 offset:34816
	s_waitcnt lgkmcnt(6)
	v_mfma_f32_16x16x32_bf16 v[28:31], v[234:237], v[136:139], v[28:31]
	v_mfma_f32_16x16x32_bf16 v[92:95], v[234:237], v[152:155], v[92:95]
	ds_read_b128 v[234:237], v2 offset:39168
	s_waitcnt lgkmcnt(6)
; __device__ __forceinline__ f32x4 mfma16(bf16x8 a, bf16x8 b, f32x4 c) { return __builtin_amdgcn_mfma_f32_16x16x32_bf16(a, b, c, 0, 0, 0); }
; __device__ void cross_items(const Params& p, LAS unsigned char* lds) {
;     ...
; #pragma unroll
;             for (int kt = 0; kt < 16; ++kt)
; #pragma unroll
;                 for (int ks = 0; ks < 4; ++ks) sc[kt] = mfma16(frag_row(buf, KV_STRIDE, 16 * kt, 32 * ks, idx, g), qf[ks], sc[kt]);
	v_mfma_f32_16x16x32_bf16 v[32:35], v[238:241], v[136:139], v[32:35]
	v_mfma_f32_16x16x32_bf16 v[96:99], v[238:241], v[152:155], v[96:99]
	ds_read_b128 v[238:241], v2 offset:34880
	s_waitcnt lgkmcnt(6)
	v_mfma_f32_16x16x32_bf16 v[28:31], v[196:199], v[140:143], v[28:31]
	v_mfma_f32_16x16x32_bf16 v[92:95], v[196:199], v[156:159], v[92:95]
	ds_read_b128 v[196:199], v2 offset:39232
	s_waitcnt lgkmcnt(6)
	v_mfma_f32_16x16x32_bf16 v[32:35], v[200:203], v[140:143], v[32:35]
	v_mfma_f32_16x16x32_bf16 v[96:99], v[200:203], v[156:159], v[96:99]
	ds_read_b128 v[200:203], v2 offset:34944
	s_waitcnt lgkmcnt(6)
	v_mfma_f32_16x16x32_bf16 v[28:31], v[204:207], v[144:147], v[28:31]
	v_mfma_f32_16x16x32_bf16 v[92:95], v[204:207], v[160:163], v[92:95]
	ds_read_b128 v[204:207], v2 offset:39296
	s_waitcnt lgkmcnt(6)
	v_mfma_f32_16x16x32_bf16 v[32:35], v[220:223], v[144:147], v[32:35]
	v_mfma_f32_16x16x32_bf16 v[96:99], v[220:223], v[160:163], v[96:99]
	ds_read_b128 v[220:223], v2 offset:35008
	s_waitcnt lgkmcnt(6)
	v_mfma_f32_16x16x32_bf16 v[36:39], v[230:233], v[132:135], v[36:39]
	v_mfma_f32_16x16x32_bf16 v[100:103], v[230:233], v[148:151], v[100:103]
	ds_read_b128 v[230:233], v2 offset:39360
	s_waitcnt lgkmcnt(6)
	v_mfma_f32_16x16x32_bf16 v[40:43], v[234:237], v[132:135], v[40:43]
	v_mfma_f32_16x16x32_bf16 v[104:107], v[234:237], v[148:151], v[104:107]
	ds_read_b128 v[234:237], v2 offset:43520
	s_waitcnt lgkmcnt(6)
	v_mfma_f32_16x16x32_bf16 v[36:39], v[238:241], v[136:139], v[36:39]
	v_mfma_f32_16x16x32_bf16 v[100:103], v[238:241], v[152:155], v[100:103]
	ds_read_b128 v[238:241], v2 offset:47872
	s_waitcnt lgkmcnt(6)
	v_mfma_f32_16x16x32_bf16 v[40:43], v[196:199], v[136:139], v[40:43]
	v_mfma_f32_16x16x32_bf16 v[104:107], v[196:199], v[152:155], v[104:107]
	ds_read_b128 v[196:199], v2 offset:43584
	s_waitcnt lgkmcnt(6)
	v_mfma_f32_16x16x32_bf16 v[36:39], v[200:203], v[140:143], v[36:39]
	v_mfma_f32_16x16x32_bf16 v[100:103], v[200:203], v[156:159], v[100:103]
	ds_read_b128 v[200:203], v2 offset:47936
	s_waitcnt lgkmcnt(6)
	v_mfma_f32_16x16x32_bf16 v[40:43], v[204:207], v[140:143], v[40:43]
	v_mfma_f32_16x16x32_bf16 v[104:107], v[204:207], v[156:159], v[104:107]
	ds_read_b128 v[204:207], v2 offset:43648
	s_waitcnt lgkmcnt(6)
	v_mfma_f32_16x16x32_bf16 v[36:39], v[220:223], v[144:147], v[36:39]
	v_mfma_f32_16x16x32_bf16 v[100:103], v[220:223], v[160:163], v[100:103]
	ds_read_b128 v[220:223], v2 offset:48000
	s_waitcnt lgkmcnt(6)
	v_mfma_f32_16x16x32_bf16 v[40:43], v[230:233], v[144:147], v[40:43]
	v_mfma_f32_16x16x32_bf16 v[104:107], v[230:233], v[160:163], v[104:107]
	ds_read_b128 v[230:233], v2 offset:43712
	s_waitcnt lgkmcnt(6)
	v_mfma_f32_16x16x32_bf16 v[44:47], v[234:237], v[132:135], v[44:47]
	v_mfma_f32_16x16x32_bf16 v[108:111], v[234:237], v[148:151], v[108:111]
	ds_read_b128 v[234:237], v2 offset:48064
	s_waitcnt lgkmcnt(6)
	v_mfma_f32_16x16x32_bf16 v[48:51], v[238:241], v[132:135], v[48:51]
	v_mfma_f32_16x16x32_bf16 v[112:115], v[238:241], v[148:151], v[112:115]
	ds_read_b128 v[238:241], v2 offset:52224
	s_waitcnt lgkmcnt(6)
	v_mfma_f32_16x16x32_bf16 v[44:47], v[196:199], v[136:139], v[44:47]
	v_mfma_f32_16x16x32_bf16 v[108:111], v[196:199], v[152:155], v[108:111]
	ds_read_b128 v[196:199], v2 offset:56576
	s_waitcnt lgkmcnt(6)
	v_mfma_f32_16x16x32_bf16 v[48:51], v[200:203], v[136:139], v[48:51]
	v_mfma_f32_16x16x32_bf16 v[112:115], v[200:203], v[152:155], v[112:115]
	ds_read_b128 v[200:203], v2 offset:52288
	s_waitcnt lgkmcnt(6)
	v_mfma_f32_16x16x32_bf16 v[44:47], v[204:207], v[140:143], v[44:47]
	v_mfma_f32_16x16x32_bf16 v[108:111], v[204:207], v[156:159], v[108:111]
	ds_read_b128 v[204:207], v2 offset:56640
	s_waitcnt lgkmcnt(6)
	v_mfma_f32_16x16x32_bf16 v[48:51], v[220:223], v[140:143], v[48:51]
	v_mfma_f32_16x16x32_bf16 v[112:115], v[220:223], v[156:159], v[112:115]
	ds_read_b128 v[220:223], v2 offset:52352
	s_waitcnt lgkmcnt(6)
	v_mfma_f32_16x16x32_bf16 v[44:47], v[230:233], v[144:147], v[44:47]
	v_mfma_f32_16x16x32_bf16 v[108:111], v[230:233], v[160:163], v[108:111]
	ds_read_b128 v[230:233], v2 offset:56704
	s_waitcnt lgkmcnt(6)
	v_mfma_f32_16x16x32_bf16 v[48:51], v[234:237], v[144:147], v[48:51]
	v_mfma_f32_16x16x32_bf16 v[112:115], v[234:237], v[160:163], v[112:115]
	ds_read_b128 v[234:237], v2 offset:52416
	s_waitcnt lgkmcnt(6)
	v_mfma_f32_16x16x32_bf16 v[52:55], v[238:241], v[132:135], v[52:55]
	v_mfma_f32_16x16x32_bf16 v[116:119], v[238:241], v[148:151], v[116:119]
	ds_read_b128 v[238:241], v2 offset:56768
	s_waitcnt lgkmcnt(6)
	v_mfma_f32_16x16x32_bf16 v[56:59], v[196:199], v[132:135], v[56:59]
	v_mfma_f32_16x16x32_bf16 v[120:123], v[196:199], v[148:151], v[120:123]
	ds_read_b128 v[196:199], v2 offset:60928
	s_waitcnt lgkmcnt(6)
	v_mfma_f32_16x16x32_bf16 v[52:55], v[200:203], v[136:139], v[52:55]
	v_mfma_f32_16x16x32_bf16 v[116:119], v[200:203], v[152:155], v[116:119]
	ds_read_b128 v[200:203], v2 offset:65280
	s_waitcnt lgkmcnt(6)
	v_mfma_f32_16x16x32_bf16 v[56:59], v[204:207], v[136:139], v[56:59]
	v_mfma_f32_16x16x32_bf16 v[120:123], v[204:207], v[152:155], v[120:123]
	ds_read_b128 v[204:207], v2 offset:60992
	s_waitcnt lgkmcnt(6)
	v_mfma_f32_16x16x32_bf16 v[52:55], v[220:223], v[140:143], v[52:55]
	v_mfma_f32_16x16x32_bf16 v[116:119], v[220:223], v[156:159], v[116:119]
	ds_read_b128 v[220:223], v2 offset:65344
	s_waitcnt lgkmcnt(6)
	v_mfma_f32_16x16x32_bf16 v[56:59], v[230:233], v[140:143], v[56:59]
	v_mfma_f32_16x16x32_bf16 v[120:123], v[230:233], v[156:159], v[120:123]
	ds_read_b128 v[230:233], v2 offset:61056
	s_waitcnt lgkmcnt(6)
; #define LAS __attribute__((address_space(3)))
; __device__ __forceinline__ f32x4 mfma16(bf16x8 a, bf16x8 b, f32x4 c) { return __builtin_amdgcn_mfma_f32_16x16x32_bf16(a, b, c, 0, 0, 0); }
; #define LDS_BARRIER() do { asm volatile("s_waitcnt lgkmcnt(0)" ::: "memory"); __builtin_amdgcn_s_barrier(); asm volatile("" ::: "memory"); } while (0)
; #define XLOAD(kvbase, c8) do { const bf16_t* _src = (kvbase) + (((c8) >= 4) ? 2048 : 0) + ((c8) & 3) * 128 + piece * 8; \
;         _Pragma("unroll") for (int _it = 0; _it < 8; ++_it) pre[_it] = *(const u32x4*)(_src + (size_t)(srow + 32 * _it) * 4096); } while (0)
; #define XSTORE(buf) do { _Pragma("unroll") for (int _it = 0; _it < 8; ++_it) *(LAS u32x4*)((buf) + (srow + 32 * _it) * KV_STRIDE + piece * 16) = pre[_it]; } while (0)
; __device__ void cross_items(const Params& p, LAS unsigned char* lds) {
;     ...
;         for (int c = 0; c < 4; ++c) {
;             LAS unsigned char* buf = lds + (c & 1) * KV_BUF;
;             XSTORE(buf);
;             bf16x8 qf[4];
; #pragma unroll
;             for (int ks = 0; ks < 4; ++ks) qf[ks] = *(const bf16x8*)(qrow + c * 128 + 32 * ks);
;             XLOAD(kvb, c + 1);
;             LDS_BARRIER();
; #pragma unroll
;             for (int kt = 0; kt < 16; ++kt)
; #pragma unroll
;                 for (int ks = 0; ks < 4; ++ks) sc[kt] = mfma16(frag_row(buf, KV_STRIDE, 16 * kt, 32 * ks, idx, g), qf[ks], sc[kt]);
	v_mfma_f32_16x16x32_bf16 v[52:55], v[234:237], v[144:147], v[52:55]
	v_mfma_f32_16x16x32_bf16 v[116:119], v[234:237], v[160:163], v[116:119]
	ds_read_b128 v[234:237], v2 offset:65408
	s_waitcnt lgkmcnt(6)
	v_mfma_f32_16x16x32_bf16 v[56:59], v[238:241], v[144:147], v[56:59]
	v_mfma_f32_16x16x32_bf16 v[120:123], v[238:241], v[160:163], v[120:123]
	ds_read_b128 v[238:241], v2 offset:61120
	s_waitcnt lgkmcnt(6)
	v_mfma_f32_16x16x32_bf16 v[60:63], v[196:199], v[132:135], v[60:63]
	v_mfma_f32_16x16x32_bf16 v[124:127], v[196:199], v[148:151], v[124:127]
	ds_read_b128 v[196:199], v2 offset:65472
	s_waitcnt lgkmcnt(6)
	v_mfma_f32_16x16x32_bf16 v[64:67], v[200:203], v[132:135], v[64:67]
	v_mfma_f32_16x16x32_bf16 v[128:131], v[200:203], v[148:151], v[128:131]
	s_waitcnt lgkmcnt(5)
	v_mfma_f32_16x16x32_bf16 v[60:63], v[204:207], v[136:139], v[60:63]
	v_mfma_f32_16x16x32_bf16 v[124:127], v[204:207], v[152:155], v[124:127]
	s_waitcnt lgkmcnt(4)
	v_mfma_f32_16x16x32_bf16 v[64:67], v[220:223], v[136:139], v[64:67]
	v_mfma_f32_16x16x32_bf16 v[128:131], v[220:223], v[152:155], v[128:131]
	s_waitcnt lgkmcnt(3)
	v_mfma_f32_16x16x32_bf16 v[60:63], v[230:233], v[140:143], v[60:63]
	v_mfma_f32_16x16x32_bf16 v[124:127], v[230:233], v[156:159], v[124:127]
	s_waitcnt lgkmcnt(2)
	v_mfma_f32_16x16x32_bf16 v[64:67], v[234:237], v[140:143], v[64:67]
	v_mfma_f32_16x16x32_bf16 v[128:131], v[234:237], v[156:159], v[128:131]
	s_waitcnt lgkmcnt(1)
	v_mfma_f32_16x16x32_bf16 v[60:63], v[238:241], v[144:147], v[60:63]
	v_mfma_f32_16x16x32_bf16 v[124:127], v[238:241], v[160:163], v[124:127]
	s_waitcnt lgkmcnt(0)
	v_mfma_f32_16x16x32_bf16 v[64:67], v[196:199], v[144:147], v[64:67]
	v_mfma_f32_16x16x32_bf16 v[128:131], v[196:199], v[160:163], v[128:131]
	s_waitcnt vmcnt(7)
	ds_write_b128 v1, v[164:167]
	s_waitcnt vmcnt(6)
	ds_write_b128 v1, v[168:171] offset:8704
	s_waitcnt vmcnt(5)
	ds_write_b128 v1, v[172:175] offset:17408
	s_waitcnt vmcnt(4)
	ds_write_b128 v1, v[176:179] offset:26112
	s_waitcnt vmcnt(3)
	ds_write_b128 v1, v[180:183] offset:34816
	s_waitcnt vmcnt(2)
	ds_write_b128 v1, v[184:187] offset:43520
	s_waitcnt vmcnt(1)
	ds_write_b128 v1, v[188:191] offset:52224
	s_waitcnt vmcnt(0)
	ds_write_b128 v1, v[192:195] offset:60928
	global_load_dwordx4 v[132:135], v246, s[92:93] offset:768
	global_load_dwordx4 v[136:139], v246, s[92:93] offset:832
	global_load_dwordx4 v[140:143], v246, s[92:93] offset:896
	global_load_dwordx4 v[144:147], v246, s[92:93] offset:960
	global_load_dwordx4 v[148:151], v247, s[92:93] offset:768
	global_load_dwordx4 v[152:155], v247, s[92:93] offset:832
	global_load_dwordx4 v[156:159], v247, s[92:93] offset:896
	global_load_dwordx4 v[160:163], v247, s[92:93] offset:960
	global_load_dwordx4 v[164:167], v242, s[6:7]
	v_add_u32_e32 v243, 0x40000, v242
	global_load_dwordx4 v[168:171], v243, s[6:7]
	v_add_u32_e32 v243, 0x80000, v242
	global_load_dwordx4 v[172:175], v243, s[6:7]
	v_add_u32_e32 v243, 0xc0000, v242
	global_load_dwordx4 v[176:179], v243, s[6:7]
	v_add_u32_e32 v243, 0x100000, v242
	global_load_dwordx4 v[180:183], v243, s[6:7]
	v_add_u32_e32 v243, 0x140000, v242
	global_load_dwordx4 v[184:187], v243, s[6:7]
	v_add_u32_e32 v243, 0x180000, v242
	global_load_dwordx4 v[188:191], v243, s[6:7]
	v_add_u32_e32 v243, 0x1c0000, v242
	global_load_dwordx4 v[192:195], v243, s[6:7]
	s_waitcnt lgkmcnt(0)
	s_barrier
	ds_read_b128 v[196:199], v208
	ds_read_b128 v[200:203], v208 offset:4352
	ds_read_b128 v[204:207], v208 offset:64
	ds_read_b128 v[220:223], v208 offset:4416
	ds_read_b128 v[230:233], v208 offset:128
	ds_read_b128 v[234:237], v208 offset:4480
	ds_read_b128 v[238:241], v208 offset:192
	s_waitcnt vmcnt(8) lgkmcnt(6)
	v_mfma_f32_16x16x32_bf16 v[4:7], v[196:199], v[132:135], v[4:7]
	v_mfma_f32_16x16x32_bf16 v[68:71], v[196:199], v[148:151], v[68:71]
	ds_read_b128 v[196:199], v208 offset:4544
	s_waitcnt lgkmcnt(6)
	v_mfma_f32_16x16x32_bf16 v[8:11], v[200:203], v[132:135], v[8:11]
	v_mfma_f32_16x16x32_bf16 v[72:75], v[200:203], v[148:151], v[72:75]
	ds_read_b128 v[200:203], v208 offset:8704
	s_waitcnt lgkmcnt(6)
	v_mfma_f32_16x16x32_bf16 v[4:7], v[204:207], v[136:139], v[4:7]
	v_mfma_f32_16x16x32_bf16 v[68:71], v[204:207], v[152:155], v[68:71]
	ds_read_b128 v[204:207], v208 offset:13056
	s_waitcnt lgkmcnt(6)
	v_mfma_f32_16x16x32_bf16 v[8:11], v[220:223], v[136:139], v[8:11]
	v_mfma_f32_16x16x32_bf16 v[72:75], v[220:223], v[152:155], v[72:75]
	ds_read_b128 v[220:223], v208 offset:8768
	s_waitcnt lgkmcnt(6)
	v_mfma_f32_16x16x32_bf16 v[4:7], v[230:233], v[140:143], v[4:7]
	v_mfma_f32_16x16x32_bf16 v[68:71], v[230:233], v[156:159], v[68:71]
	ds_read_b128 v[230:233], v208 offset:13120
	s_waitcnt lgkmcnt(6)
	v_mfma_f32_16x16x32_bf16 v[8:11], v[234:237], v[140:143], v[8:11]
	v_mfma_f32_16x16x32_bf16 v[72:75], v[234:237], v[156:159], v[72:75]
	ds_read_b128 v[234:237], v208 offset:8832
	s_waitcnt lgkmcnt(6)
	v_mfma_f32_16x16x32_bf16 v[4:7], v[238:241], v[144:147], v[4:7]
	v_mfma_f32_16x16x32_bf16 v[68:71], v[238:241], v[160:163], v[68:71]
	ds_read_b128 v[238:241], v208 offset:13184
	s_waitcnt lgkmcnt(6)
	v_mfma_f32_16x16x32_bf16 v[8:11], v[196:199], v[144:147], v[8:11]
	v_mfma_f32_16x16x32_bf16 v[72:75], v[196:199], v[160:163], v[72:75]
	ds_read_b128 v[196:199], v208 offset:8896
	s_waitcnt lgkmcnt(6)
	v_mfma_f32_16x16x32_bf16 v[12:15], v[200:203], v[132:135], v[12:15]
	v_mfma_f32_16x16x32_bf16 v[76:79], v[200:203], v[148:151], v[76:79]
	ds_read_b128 v[200:203], v208 offset:13248
	s_waitcnt lgkmcnt(6)
	v_mfma_f32_16x16x32_bf16 v[16:19], v[204:207], v[132:135], v[16:19]
	v_mfma_f32_16x16x32_bf16 v[80:83], v[204:207], v[148:151], v[80:83]
	ds_read_b128 v[204:207], v208 offset:17408
	s_waitcnt lgkmcnt(6)
; __device__ __forceinline__ f32x4 mfma16(bf16x8 a, bf16x8 b, f32x4 c) { return __builtin_amdgcn_mfma_f32_16x16x32_bf16(a, b, c, 0, 0, 0); }
; __device__ void cross_items(const Params& p, LAS unsigned char* lds) {
;     ...
; #pragma unroll
;             for (int kt = 0; kt < 16; ++kt)
; #pragma unroll
;                 for (int ks = 0; ks < 4; ++ks) sc[kt] = mfma16(frag_row(buf, KV_STRIDE, 16 * kt, 32 * ks, idx, g), qf[ks], sc[kt]);
	v_mfma_f32_16x16x32_bf16 v[12:15], v[220:223], v[136:139], v[12:15]
	v_mfma_f32_16x16x32_bf16 v[76:79], v[220:223], v[152:155], v[76:79]
	ds_read_b128 v[220:223], v208 offset:21760
	s_waitcnt lgkmcnt(6)
	v_mfma_f32_16x16x32_bf16 v[16:19], v[230:233], v[136:139], v[16:19]
	v_mfma_f32_16x16x32_bf16 v[80:83], v[230:233], v[152:155], v[80:83]
	ds_read_b128 v[230:233], v208 offset:17472
	s_waitcnt lgkmcnt(6)
	v_mfma_f32_16x16x32_bf16 v[12:15], v[234:237], v[140:143], v[12:15]
	v_mfma_f32_16x16x32_bf16 v[76:79], v[234:237], v[156:159], v[76:79]
	ds_read_b128 v[234:237], v208 offset:21824
	s_waitcnt lgkmcnt(6)
	v_mfma_f32_16x16x32_bf16 v[16:19], v[238:241], v[140:143], v[16:19]
	v_mfma_f32_16x16x32_bf16 v[80:83], v[238:241], v[156:159], v[80:83]
	ds_read_b128 v[238:241], v208 offset:17536
	s_waitcnt lgkmcnt(6)
	v_mfma_f32_16x16x32_bf16 v[12:15], v[196:199], v[144:147], v[12:15]
	v_mfma_f32_16x16x32_bf16 v[76:79], v[196:199], v[160:163], v[76:79]
	ds_read_b128 v[196:199], v208 offset:21888
	s_waitcnt lgkmcnt(6)
	v_mfma_f32_16x16x32_bf16 v[16:19], v[200:203], v[144:147], v[16:19]
	v_mfma_f32_16x16x32_bf16 v[80:83], v[200:203], v[160:163], v[80:83]
	ds_read_b128 v[200:203], v208 offset:17600
	s_waitcnt lgkmcnt(6)
	v_mfma_f32_16x16x32_bf16 v[20:23], v[204:207], v[132:135], v[20:23]
	v_mfma_f32_16x16x32_bf16 v[84:87], v[204:207], v[148:151], v[84:87]
	ds_read_b128 v[204:207], v208 offset:21952
	s_waitcnt lgkmcnt(6)
	v_mfma_f32_16x16x32_bf16 v[24:27], v[220:223], v[132:135], v[24:27]
	v_mfma_f32_16x16x32_bf16 v[88:91], v[220:223], v[148:151], v[88:91]
	ds_read_b128 v[220:223], v208 offset:26112
	s_waitcnt lgkmcnt(6)
	v_mfma_f32_16x16x32_bf16 v[20:23], v[230:233], v[136:139], v[20:23]
	v_mfma_f32_16x16x32_bf16 v[84:87], v[230:233], v[152:155], v[84:87]
	ds_read_b128 v[230:233], v208 offset:30464
	s_waitcnt lgkmcnt(6)
	v_mfma_f32_16x16x32_bf16 v[24:27], v[234:237], v[136:139], v[24:27]
	v_mfma_f32_16x16x32_bf16 v[88:91], v[234:237], v[152:155], v[88:91]
	ds_read_b128 v[234:237], v208 offset:26176
	s_waitcnt lgkmcnt(6)
	v_mfma_f32_16x16x32_bf16 v[20:23], v[238:241], v[140:143], v[20:23]
	v_mfma_f32_16x16x32_bf16 v[84:87], v[238:241], v[156:159], v[84:87]
	ds_read_b128 v[238:241], v208 offset:30528
	s_waitcnt lgkmcnt(6)
	v_mfma_f32_16x16x32_bf16 v[24:27], v[196:199], v[140:143], v[24:27]
	v_mfma_f32_16x16x32_bf16 v[88:91], v[196:199], v[156:159], v[88:91]
	ds_read_b128 v[196:199], v208 offset:26240
	s_waitcnt lgkmcnt(6)
	v_mfma_f32_16x16x32_bf16 v[20:23], v[200:203], v[144:147], v[20:23]
	v_mfma_f32_16x16x32_bf16 v[84:87], v[200:203], v[160:163], v[84:87]
	ds_read_b128 v[200:203], v208 offset:30592
	s_waitcnt lgkmcnt(6)
	v_mfma_f32_16x16x32_bf16 v[24:27], v[204:207], v[144:147], v[24:27]
	v_mfma_f32_16x16x32_bf16 v[88:91], v[204:207], v[160:163], v[88:91]
	ds_read_b128 v[204:207], v208 offset:26304
	s_waitcnt lgkmcnt(6)
	v_mfma_f32_16x16x32_bf16 v[28:31], v[220:223], v[132:135], v[28:31]
	v_mfma_f32_16x16x32_bf16 v[92:95], v[220:223], v[148:151], v[92:95]
	ds_read_b128 v[220:223], v208 offset:30656
	s_waitcnt lgkmcnt(6)
	v_mfma_f32_16x16x32_bf16 v[32:35], v[230:233], v[132:135], v[32:35]
	v_mfma_f32_16x16x32_bf16 v[96:99], v[230:233], v[148:151], v[96:99]
	ds_read_b128 v[230:233], v208 offset:34816
	s_waitcnt lgkmcnt(6)
	v_mfma_f32_16x16x32_bf16 v[28:31], v[234:237], v[136:139], v[28:31]
	v_mfma_f32_16x16x32_bf16 v[92:95], v[234:237], v[152:155], v[92:95]
	ds_read_b128 v[234:237], v208 offset:39168
	s_waitcnt lgkmcnt(6)
	v_mfma_f32_16x16x32_bf16 v[32:35], v[238:241], v[136:139], v[32:35]
	v_mfma_f32_16x16x32_bf16 v[96:99], v[238:241], v[152:155], v[96:99]
	ds_read_b128 v[238:241], v208 offset:34880
	s_waitcnt lgkmcnt(6)
	v_mfma_f32_16x16x32_bf16 v[28:31], v[196:199], v[140:143], v[28:31]
	v_mfma_f32_16x16x32_bf16 v[92:95], v[196:199], v[156:159], v[92:95]
	ds_read_b128 v[196:199], v208 offset:39232
	s_waitcnt lgkmcnt(6)
	v_mfma_f32_16x16x32_bf16 v[32:35], v[200:203], v[140:143], v[32:35]
	v_mfma_f32_16x16x32_bf16 v[96:99], v[200:203], v[156:159], v[96:99]
	ds_read_b128 v[200:203], v208 offset:34944
	s_waitcnt lgkmcnt(6)
	v_mfma_f32_16x16x32_bf16 v[28:31], v[204:207], v[144:147], v[28:31]
	v_mfma_f32_16x16x32_bf16 v[92:95], v[204:207], v[160:163], v[92:95]
	ds_read_b128 v[204:207], v208 offset:39296
	s_waitcnt lgkmcnt(6)
	v_mfma_f32_16x16x32_bf16 v[32:35], v[220:223], v[144:147], v[32:35]
	v_mfma_f32_16x16x32_bf16 v[96:99], v[220:223], v[160:163], v[96:99]
	ds_read_b128 v[220:223], v208 offset:35008
	s_waitcnt lgkmcnt(6)
	v_mfma_f32_16x16x32_bf16 v[36:39], v[230:233], v[132:135], v[36:39]
	v_mfma_f32_16x16x32_bf16 v[100:103], v[230:233], v[148:151], v[100:103]
	ds_read_b128 v[230:233], v208 offset:39360
	s_waitcnt lgkmcnt(6)
	v_mfma_f32_16x16x32_bf16 v[40:43], v[234:237], v[132:135], v[40:43]
	v_mfma_f32_16x16x32_bf16 v[104:107], v[234:237], v[148:151], v[104:107]
	ds_read_b128 v[234:237], v208 offset:43520
	s_waitcnt lgkmcnt(6)
	v_mfma_f32_16x16x32_bf16 v[36:39], v[238:241], v[136:139], v[36:39]
	v_mfma_f32_16x16x32_bf16 v[100:103], v[238:241], v[152:155], v[100:103]
	ds_read_b128 v[238:241], v208 offset:47872
	s_waitcnt lgkmcnt(6)
	v_mfma_f32_16x16x32_bf16 v[40:43], v[196:199], v[136:139], v[40:43]
	v_mfma_f32_16x16x32_bf16 v[104:107], v[196:199], v[152:155], v[104:107]
	ds_read_b128 v[196:199], v208 offset:43584
	s_waitcnt lgkmcnt(6)
	v_mfma_f32_16x16x32_bf16 v[36:39], v[200:203], v[140:143], v[36:39]
	v_mfma_f32_16x16x32_bf16 v[100:103], v[200:203], v[156:159], v[100:103]
	ds_read_b128 v[200:203], v208 offset:47936
	s_waitcnt lgkmcnt(6)
	v_mfma_f32_16x16x32_bf16 v[40:43], v[204:207], v[140:143], v[40:43]
	v_mfma_f32_16x16x32_bf16 v[104:107], v[204:207], v[156:159], v[104:107]
	ds_read_b128 v[204:207], v208 offset:43648
	s_waitcnt lgkmcnt(6)
; __device__ __forceinline__ f32x4 mfma16(bf16x8 a, bf16x8 b, f32x4 c) { return __builtin_amdgcn_mfma_f32_16x16x32_bf16(a, b, c, 0, 0, 0); }
; __device__ void cross_items(const Params& p, LAS unsigned char* lds) {
;     ...
; #pragma unroll
;             for (int kt = 0; kt < 16; ++kt)
; #pragma unroll
;                 for (int ks = 0; ks < 4; ++ks) sc[kt] = mfma16(frag_row(buf, KV_STRIDE, 16 * kt, 32 * ks, idx, g), qf[ks], sc[kt]);
	v_mfma_f32_16x16x32_bf16 v[36:39], v[220:223], v[144:147], v[36:39]
	v_mfma_f32_16x16x32_bf16 v[100:103], v[220:223], v[160:163], v[100:103]
	ds_read_b128 v[220:223], v208 offset:48000
	s_waitcnt lgkmcnt(6)
	v_mfma_f32_16x16x32_bf16 v[40:43], v[230:233], v[144:147], v[40:43]
	v_mfma_f32_16x16x32_bf16 v[104:107], v[230:233], v[160:163], v[104:107]
	ds_read_b128 v[230:233], v208 offset:43712
	s_waitcnt lgkmcnt(6)
	v_mfma_f32_16x16x32_bf16 v[44:47], v[234:237], v[132:135], v[44:47]
	v_mfma_f32_16x16x32_bf16 v[108:111], v[234:237], v[148:151], v[108:111]
	ds_read_b128 v[234:237], v208 offset:48064
	s_waitcnt lgkmcnt(6)
	v_mfma_f32_16x16x32_bf16 v[48:51], v[238:241], v[132:135], v[48:51]
	v_mfma_f32_16x16x32_bf16 v[112:115], v[238:241], v[148:151], v[112:115]
	ds_read_b128 v[238:241], v208 offset:52224
	s_waitcnt lgkmcnt(6)
	v_mfma_f32_16x16x32_bf16 v[44:47], v[196:199], v[136:139], v[44:47]
	v_mfma_f32_16x16x32_bf16 v[108:111], v[196:199], v[152:155], v[108:111]
	ds_read_b128 v[196:199], v208 offset:56576
	s_waitcnt lgkmcnt(6)
	v_mfma_f32_16x16x32_bf16 v[48:51], v[200:203], v[136:139], v[48:51]
	v_mfma_f32_16x16x32_bf16 v[112:115], v[200:203], v[152:155], v[112:115]
	ds_read_b128 v[200:203], v208 offset:52288
	s_waitcnt lgkmcnt(6)
	v_mfma_f32_16x16x32_bf16 v[44:47], v[204:207], v[140:143], v[44:47]
	v_mfma_f32_16x16x32_bf16 v[108:111], v[204:207], v[156:159], v[108:111]
	ds_read_b128 v[204:207], v208 offset:56640
	s_waitcnt lgkmcnt(6)
	v_mfma_f32_16x16x32_bf16 v[48:51], v[220:223], v[140:143], v[48:51]
	v_mfma_f32_16x16x32_bf16 v[112:115], v[220:223], v[156:159], v[112:115]
	ds_read_b128 v[220:223], v208 offset:52352
	s_waitcnt lgkmcnt(6)
	v_mfma_f32_16x16x32_bf16 v[44:47], v[230:233], v[144:147], v[44:47]
	v_mfma_f32_16x16x32_bf16 v[108:111], v[230:233], v[160:163], v[108:111]
	ds_read_b128 v[230:233], v208 offset:56704
	s_waitcnt lgkmcnt(6)
	v_mfma_f32_16x16x32_bf16 v[48:51], v[234:237], v[144:147], v[48:51]
	v_mfma_f32_16x16x32_bf16 v[112:115], v[234:237], v[160:163], v[112:115]
	ds_read_b128 v[234:237], v208 offset:52416
	s_waitcnt lgkmcnt(6)
	v_mfma_f32_16x16x32_bf16 v[52:55], v[238:241], v[132:135], v[52:55]
	v_mfma_f32_16x16x32_bf16 v[116:119], v[238:241], v[148:151], v[116:119]
	ds_read_b128 v[238:241], v208 offset:56768
	s_waitcnt lgkmcnt(6)
	v_mfma_f32_16x16x32_bf16 v[56:59], v[196:199], v[132:135], v[56:59]
	v_mfma_f32_16x16x32_bf16 v[120:123], v[196:199], v[148:151], v[120:123]
	ds_read_b128 v[196:199], v208 offset:60928
	s_waitcnt lgkmcnt(6)
	v_mfma_f32_16x16x32_bf16 v[52:55], v[200:203], v[136:139], v[52:55]
	v_mfma_f32_16x16x32_bf16 v[116:119], v[200:203], v[152:155], v[116:119]
	ds_read_b128 v[200:203], v208 offset:65280
	s_waitcnt lgkmcnt(6)
	v_mfma_f32_16x16x32_bf16 v[56:59], v[204:207], v[136:139], v[56:59]
	v_mfma_f32_16x16x32_bf16 v[120:123], v[204:207], v[152:155], v[120:123]
	ds_read_b128 v[204:207], v208 offset:60992
	s_waitcnt lgkmcnt(6)
	v_mfma_f32_16x16x32_bf16 v[52:55], v[220:223], v[140:143], v[52:55]
	v_mfma_f32_16x16x32_bf16 v[116:119], v[220:223], v[156:159], v[116:119]
	ds_read_b128 v[220:223], v208 offset:65344
	s_waitcnt lgkmcnt(6)
	v_mfma_f32_16x16x32_bf16 v[56:59], v[230:233], v[140:143], v[56:59]
	v_mfma_f32_16x16x32_bf16 v[120:123], v[230:233], v[156:159], v[120:123]
	ds_read_b128 v[230:233], v208 offset:61056
	s_waitcnt lgkmcnt(6)
	v_mfma_f32_16x16x32_bf16 v[52:55], v[234:237], v[144:147], v[52:55]
	v_mfma_f32_16x16x32_bf16 v[116:119], v[234:237], v[160:163], v[116:119]
	ds_read_b128 v[234:237], v208 offset:65408
	s_waitcnt lgkmcnt(6)
	v_mfma_f32_16x16x32_bf16 v[56:59], v[238:241], v[144:147], v[56:59]
	v_mfma_f32_16x16x32_bf16 v[120:123], v[238:241], v[160:163], v[120:123]
	ds_read_b128 v[238:241], v208 offset:61120
	s_waitcnt lgkmcnt(6)
	v_mfma_f32_16x16x32_bf16 v[60:63], v[196:199], v[132:135], v[60:63]
	v_mfma_f32_16x16x32_bf16 v[124:127], v[196:199], v[148:151], v[124:127]
	ds_read_b128 v[196:199], v208 offset:65472
	s_waitcnt lgkmcnt(6)
	v_mfma_f32_16x16x32_bf16 v[64:67], v[200:203], v[132:135], v[64:67]
	v_mfma_f32_16x16x32_bf16 v[128:131], v[200:203], v[148:151], v[128:131]
	s_waitcnt lgkmcnt(5)
	v_mfma_f32_16x16x32_bf16 v[60:63], v[204:207], v[136:139], v[60:63]
	v_mfma_f32_16x16x32_bf16 v[124:127], v[204:207], v[152:155], v[124:127]
	s_waitcnt lgkmcnt(4)
	v_mfma_f32_16x16x32_bf16 v[64:67], v[220:223], v[136:139], v[64:67]
	v_mfma_f32_16x16x32_bf16 v[128:131], v[220:223], v[152:155], v[128:131]
	s_waitcnt lgkmcnt(3)
	v_mfma_f32_16x16x32_bf16 v[60:63], v[230:233], v[140:143], v[60:63]
	v_mfma_f32_16x16x32_bf16 v[124:127], v[230:233], v[156:159], v[124:127]
	s_waitcnt lgkmcnt(2)
	v_mfma_f32_16x16x32_bf16 v[64:67], v[234:237], v[140:143], v[64:67]
	v_mfma_f32_16x16x32_bf16 v[128:131], v[234:237], v[156:159], v[128:131]
	s_waitcnt lgkmcnt(1)
	v_mfma_f32_16x16x32_bf16 v[60:63], v[238:241], v[144:147], v[60:63]
	v_mfma_f32_16x16x32_bf16 v[124:127], v[238:241], v[160:163], v[124:127]
	s_waitcnt lgkmcnt(0)
; __device__ __forceinline__ f32x4 mfma16(bf16x8 a, bf16x8 b, f32x4 c) { return __builtin_amdgcn_mfma_f32_16x16x32_bf16(a, b, c, 0, 0, 0); }
; __device__ void cross_items(const Params& p, LAS unsigned char* lds) {
;     ...
;             for (int kt = 0; kt < 16; ++kt)
; #pragma unroll
;                 for (int ks = 0; ks < 4; ++ks) sc[kt] = mfma16(frag_row(buf, KV_STRIDE, 16 * kt, 32 * ks, idx, g), qf[ks], sc[kt]);
;     ...
;         const float scl = 0.04419417382415922f * LOG2E;
;         float mx = -1e30f;
; #pragma unroll
;         for (int kt = 0; kt < 16; ++kt)
; #pragma unroll
;             for (int rr = 0; rr < 4; ++rr) { const float sv = sc[kt][rr] * scl; sc[kt][rr] = sv; mx = fmaxf(mx, sv); }
;         mx = fmaxf(mx, __shfl_xor(mx, 16)); mx = fmaxf(mx, __shfl_xor(mx, 32));
	v_mfma_f32_16x16x32_bf16 v[64:67], v[196:199], v[144:147], v[64:67]
	v_mfma_f32_16x16x32_bf16 v[128:131], v[196:199], v[160:163], v[128:131]
	s_nop 7
	s_nop 7
	v_and_b32_e32 v199, 63, v212
	v_xor_b32_e32 v196, 16, v199
	v_lshlrev_b32_e32 v196, 2, v196
	v_xor_b32_e32 v197, 32, v199
	v_lshlrev_b32_e32 v197, 2, v197
	s_mov_b32 s5, 0x3d8293ee
	v_mov_b32_e32 v198, 0xf149f2ca
	v_mul_f32_e32 v199, 0x3d8293ee, v4
	v_mul_f32_e32 v200, 0x3d8293ee, v5
	v_max3_f32 v198, v198, v199, v200
	v_mul_f32_e32 v199, 0x3d8293ee, v6
	v_mul_f32_e32 v200, 0x3d8293ee, v7
	v_max3_f32 v198, v198, v199, v200
	v_mul_f32_e32 v199, 0x3d8293ee, v8
	v_mul_f32_e32 v200, 0x3d8293ee, v9
	v_max3_f32 v198, v198, v199, v200
	v_mul_f32_e32 v199, 0x3d8293ee, v10
	v_mul_f32_e32 v200, 0x3d8293ee, v11
	v_max3_f32 v198, v198, v199, v200
	v_mul_f32_e32 v199, 0x3d8293ee, v12
	v_mul_f32_e32 v200, 0x3d8293ee, v13
	v_max3_f32 v198, v198, v199, v200
	v_mul_f32_e32 v199, 0x3d8293ee, v14
	v_mul_f32_e32 v200, 0x3d8293ee, v15
	v_max3_f32 v198, v198, v199, v200
	v_mul_f32_e32 v199, 0x3d8293ee, v16
	v_mul_f32_e32 v200, 0x3d8293ee, v17
	v_max3_f32 v198, v198, v199, v200
	v_mul_f32_e32 v199, 0x3d8293ee, v18
	v_mul_f32_e32 v200, 0x3d8293ee, v19
	v_max3_f32 v198, v198, v199, v200
	v_mul_f32_e32 v199, 0x3d8293ee, v20
	v_mul_f32_e32 v200, 0x3d8293ee, v21
	v_max3_f32 v198, v198, v199, v200
	v_mul_f32_e32 v199, 0x3d8293ee, v22
	v_mul_f32_e32 v200, 0x3d8293ee, v23
	v_max3_f32 v198, v198, v199, v200
	v_mul_f32_e32 v199, 0x3d8293ee, v24
	v_mul_f32_e32 v200, 0x3d8293ee, v25
	v_max3_f32 v198, v198, v199, v200
	v_mul_f32_e32 v199, 0x3d8293ee, v26
	v_mul_f32_e32 v200, 0x3d8293ee, v27
	v_max3_f32 v198, v198, v199, v200
	v_mul_f32_e32 v199, 0x3d8293ee, v28
	v_mul_f32_e32 v200, 0x3d8293ee, v29
	v_max3_f32 v198, v198, v199, v200
	v_mul_f32_e32 v199, 0x3d8293ee, v30
	v_mul_f32_e32 v200, 0x3d8293ee, v31
	v_max3_f32 v198, v198, v199, v200
	v_mul_f32_e32 v199, 0x3d8293ee, v32
	v_mul_f32_e32 v200, 0x3d8293ee, v33
	v_max3_f32 v198, v198, v199, v200
	v_mul_f32_e32 v199, 0x3d8293ee, v34
	v_mul_f32_e32 v200, 0x3d8293ee, v35
	v_max3_f32 v198, v198, v199, v200
	v_mul_f32_e32 v199, 0x3d8293ee, v36
	v_mul_f32_e32 v200, 0x3d8293ee, v37
	v_max3_f32 v198, v198, v199, v200
	v_mul_f32_e32 v199, 0x3d8293ee, v38
	v_mul_f32_e32 v200, 0x3d8293ee, v39
	v_max3_f32 v198, v198, v199, v200
	v_mul_f32_e32 v199, 0x3d8293ee, v40
	v_mul_f32_e32 v200, 0x3d8293ee, v41
	v_max3_f32 v198, v198, v199, v200
	v_mul_f32_e32 v199, 0x3d8293ee, v42
	v_mul_f32_e32 v200, 0x3d8293ee, v43
	v_max3_f32 v198, v198, v199, v200
	v_mul_f32_e32 v199, 0x3d8293ee, v44
	v_mul_f32_e32 v200, 0x3d8293ee, v45
	v_max3_f32 v198, v198, v199, v200
	v_mul_f32_e32 v199, 0x3d8293ee, v46
	v_mul_f32_e32 v200, 0x3d8293ee, v47
	v_max3_f32 v198, v198, v199, v200
	v_mul_f32_e32 v199, 0x3d8293ee, v48
	v_mul_f32_e32 v200, 0x3d8293ee, v49
	v_max3_f32 v198, v198, v199, v200
	v_mul_f32_e32 v199, 0x3d8293ee, v50
	v_mul_f32_e32 v200, 0x3d8293ee, v51
	v_max3_f32 v198, v198, v199, v200
	v_mul_f32_e32 v199, 0x3d8293ee, v52
	v_mul_f32_e32 v200, 0x3d8293ee, v53
	v_max3_f32 v198, v198, v199, v200
	v_mul_f32_e32 v199, 0x3d8293ee, v54
	v_mul_f32_e32 v200, 0x3d8293ee, v55
	v_max3_f32 v198, v198, v199, v200
	v_mul_f32_e32 v199, 0x3d8293ee, v56
	v_mul_f32_e32 v200, 0x3d8293ee, v57
	v_max3_f32 v198, v198, v199, v200
	v_mul_f32_e32 v199, 0x3d8293ee, v58
	v_mul_f32_e32 v200, 0x3d8293ee, v59
	v_max3_f32 v198, v198, v199, v200
	v_mul_f32_e32 v199, 0x3d8293ee, v60
	v_mul_f32_e32 v200, 0x3d8293ee, v61
	v_max3_f32 v198, v198, v199, v200
	v_mul_f32_e32 v199, 0x3d8293ee, v62
	v_mul_f32_e32 v200, 0x3d8293ee, v63
	v_max3_f32 v198, v198, v199, v200
	v_mul_f32_e32 v199, 0x3d8293ee, v64
	v_mul_f32_e32 v200, 0x3d8293ee, v65
	v_max3_f32 v198, v198, v199, v200
	v_mul_f32_e32 v199, 0x3d8293ee, v66
	v_mul_f32_e32 v200, 0x3d8293ee, v67
	v_max3_f32 v198, v198, v199, v200
	ds_bpermute_b32 v199, v196, v198
	s_waitcnt lgkmcnt(0)
	v_max_f32_e32 v198, v198, v199
	ds_bpermute_b32 v199, v197, v198
	s_waitcnt lgkmcnt(0)
	v_max_f32_e32 v198, v198, v199
	v_fma_f32 v4, v4, s5, -v198
	v_fma_f32 v5, v5, s5, -v198
	v_fma_f32 v6, v6, s5, -v198
	v_fma_f32 v7, v7, s5, -v198
	v_fma_f32 v8, v8, s5, -v198
	v_fma_f32 v9, v9, s5, -v198
	v_fma_f32 v10, v10, s5, -v198
	v_fma_f32 v11, v11, s5, -v198
	v_fma_f32 v12, v12, s5, -v198
	v_fma_f32 v13, v13, s5, -v198
	v_fma_f32 v14, v14, s5, -v198
	v_fma_f32 v15, v15, s5, -v198
	v_fma_f32 v16, v16, s5, -v198
	v_fma_f32 v17, v17, s5, -v198
	v_fma_f32 v18, v18, s5, -v198
	v_fma_f32 v19, v19, s5, -v198
	v_fma_f32 v20, v20, s5, -v198
	v_fma_f32 v21, v21, s5, -v198
	v_fma_f32 v22, v22, s5, -v198
	v_fma_f32 v23, v23, s5, -v198
	v_fma_f32 v24, v24, s5, -v198
	v_fma_f32 v25, v25, s5, -v198
	v_fma_f32 v26, v26, s5, -v198
	v_fma_f32 v27, v27, s5, -v198
	v_fma_f32 v28, v28, s5, -v198
	v_fma_f32 v29, v29, s5, -v198
	v_fma_f32 v30, v30, s5, -v198
	v_fma_f32 v31, v31, s5, -v198
	v_fma_f32 v32, v32, s5, -v198
	v_fma_f32 v33, v33, s5, -v198
	v_fma_f32 v34, v34, s5, -v198
	v_fma_f32 v35, v35, s5, -v198
	v_fma_f32 v36, v36, s5, -v198
	v_fma_f32 v37, v37, s5, -v198
	v_fma_f32 v38, v38, s5, -v198
	v_fma_f32 v39, v39, s5, -v198
	v_fma_f32 v40, v40, s5, -v198
	v_fma_f32 v41, v41, s5, -v198
	v_fma_f32 v42, v42, s5, -v198
	v_fma_f32 v43, v43, s5, -v198
	v_fma_f32 v44, v44, s5, -v198
	v_fma_f32 v45, v45, s5, -v198
	v_fma_f32 v46, v46, s5, -v198
	v_fma_f32 v47, v47, s5, -v198
	v_fma_f32 v48, v48, s5, -v198
	v_fma_f32 v49, v49, s5, -v198
	v_fma_f32 v50, v50, s5, -v198
	v_fma_f32 v51, v51, s5, -v198
	v_fma_f32 v52, v52, s5, -v198
	v_fma_f32 v53, v53, s5, -v198
	v_fma_f32 v54, v54, s5, -v198
	v_fma_f32 v55, v55, s5, -v198
; __device__ __forceinline__ unsigned cvt_pk_bf16(float lo, float hi) { const f32x2v v = {lo, hi}; const b16x2v r = __builtin_convertvector(v, b16x2v); return __builtin_bit_cast(unsigned, r); }
; __device__ __forceinline__ float fexp2(float x) { return __builtin_amdgcn_exp2f(x); }
; __device__ void cross_items(const Params& p, LAS unsigned char* lds) {
;     ...
;         float sum = 0.f;
; #pragma unroll
;         for (int kt = 0; kt < 16; ++kt)
; #pragma unroll
;             for (int rr = 0; rr < 4; ++rr) { const float e = fexp2(sc[kt][rr] - mx); sc[kt][rr] = e; sum += e; }
;         sum += __shfl_xor(sum, 16); sum += __shfl_xor(sum, 32);
;         const float inv = 1.0f / sum;
;         bf16x8 pf[8];
; #pragma unroll
;         for (int sx = 0; sx < 8; ++sx) { u32x4 pw; pw.x = cvt_pk_bf16(sc[2 * sx][0], sc[2 * sx][1]); pw.y = cvt_pk_bf16(sc[2 * sx][2], sc[2 * sx][3]); pw.z = cvt_pk_bf16(sc[2 * sx + 1][0], sc[2 * sx + 1][1]); pw.w = cvt_pk_bf16(sc[2 * sx + 1][2], sc[2 * sx + 1][3]);
;             pf[sx] = __builtin_bit_cast(bf16x8, pw); }
	v_fma_f32 v56, v56, s5, -v198
	v_fma_f32 v57, v57, s5, -v198
	v_fma_f32 v58, v58, s5, -v198
	v_fma_f32 v59, v59, s5, -v198
	v_fma_f32 v60, v60, s5, -v198
	v_fma_f32 v61, v61, s5, -v198
	v_fma_f32 v62, v62, s5, -v198
	v_fma_f32 v63, v63, s5, -v198
	v_fma_f32 v64, v64, s5, -v198
	v_fma_f32 v65, v65, s5, -v198
	v_fma_f32 v66, v66, s5, -v198
	v_fma_f32 v67, v67, s5, -v198
	v_exp_f32_e32 v4, v4
	v_exp_f32_e32 v5, v5
	v_exp_f32_e32 v6, v6
	v_exp_f32_e32 v7, v7
	v_exp_f32_e32 v8, v8
	v_exp_f32_e32 v9, v9
	v_exp_f32_e32 v10, v10
	v_exp_f32_e32 v11, v11
	v_exp_f32_e32 v12, v12
	v_exp_f32_e32 v13, v13
	v_exp_f32_e32 v14, v14
	v_exp_f32_e32 v15, v15
	v_exp_f32_e32 v16, v16
	v_exp_f32_e32 v17, v17
	v_exp_f32_e32 v18, v18
	v_exp_f32_e32 v19, v19
	v_exp_f32_e32 v20, v20
	v_exp_f32_e32 v21, v21
	v_exp_f32_e32 v22, v22
	v_exp_f32_e32 v23, v23
	v_exp_f32_e32 v24, v24
	v_exp_f32_e32 v25, v25
	v_exp_f32_e32 v26, v26
	v_exp_f32_e32 v27, v27
	v_exp_f32_e32 v28, v28
	v_exp_f32_e32 v29, v29
	v_exp_f32_e32 v30, v30
	v_exp_f32_e32 v31, v31
	v_exp_f32_e32 v32, v32
	v_exp_f32_e32 v33, v33
	v_exp_f32_e32 v34, v34
	v_exp_f32_e32 v35, v35
	v_exp_f32_e32 v36, v36
	v_exp_f32_e32 v37, v37
	v_exp_f32_e32 v38, v38
	v_exp_f32_e32 v39, v39
	v_exp_f32_e32 v40, v40
	v_exp_f32_e32 v41, v41
	v_exp_f32_e32 v42, v42
	v_exp_f32_e32 v43, v43
	v_exp_f32_e32 v44, v44
	v_exp_f32_e32 v45, v45
	v_exp_f32_e32 v46, v46
	v_exp_f32_e32 v47, v47
	v_exp_f32_e32 v48, v48
	v_exp_f32_e32 v49, v49
	v_exp_f32_e32 v50, v50
	v_exp_f32_e32 v51, v51
	v_exp_f32_e32 v52, v52
	v_exp_f32_e32 v53, v53
	v_exp_f32_e32 v54, v54
	v_exp_f32_e32 v55, v55
	v_exp_f32_e32 v56, v56
	v_exp_f32_e32 v57, v57
	v_exp_f32_e32 v58, v58
	v_exp_f32_e32 v59, v59
	v_exp_f32_e32 v60, v60
	v_exp_f32_e32 v61, v61
	v_exp_f32_e32 v62, v62
	v_exp_f32_e32 v63, v63
	v_exp_f32_e32 v64, v64
	v_exp_f32_e32 v65, v65
	v_exp_f32_e32 v66, v66
	v_exp_f32_e32 v67, v67
	s_nop 0
	v_add_f32_e32 v201, 0, v4
	v_add_f32_e32 v201, v5, v201
	v_add_f32_e32 v201, v6, v201
	v_add_f32_e32 v201, v7, v201
	v_add_f32_e32 v201, v8, v201
	v_add_f32_e32 v201, v9, v201
	v_add_f32_e32 v201, v10, v201
	v_add_f32_e32 v201, v11, v201
	v_add_f32_e32 v201, v12, v201
	v_add_f32_e32 v201, v13, v201
	v_add_f32_e32 v201, v14, v201
	v_add_f32_e32 v201, v15, v201
	v_add_f32_e32 v201, v16, v201
	v_add_f32_e32 v201, v17, v201
	v_add_f32_e32 v201, v18, v201
	v_add_f32_e32 v201, v19, v201
	v_add_f32_e32 v201, v20, v201
	v_add_f32_e32 v201, v21, v201
	v_add_f32_e32 v201, v22, v201
	v_add_f32_e32 v201, v23, v201
	v_add_f32_e32 v201, v24, v201
	v_add_f32_e32 v201, v25, v201
	v_add_f32_e32 v201, v26, v201
	v_add_f32_e32 v201, v27, v201
	v_add_f32_e32 v201, v28, v201
	v_add_f32_e32 v201, v29, v201
	v_add_f32_e32 v201, v30, v201
	v_add_f32_e32 v201, v31, v201
	v_add_f32_e32 v201, v32, v201
	v_add_f32_e32 v201, v33, v201
	v_add_f32_e32 v201, v34, v201
	v_add_f32_e32 v201, v35, v201
	v_add_f32_e32 v201, v36, v201
	v_add_f32_e32 v201, v37, v201
	v_add_f32_e32 v201, v38, v201
	v_add_f32_e32 v201, v39, v201
	v_add_f32_e32 v201, v40, v201
	v_add_f32_e32 v201, v41, v201
	v_add_f32_e32 v201, v42, v201
	v_add_f32_e32 v201, v43, v201
	v_add_f32_e32 v201, v44, v201
	v_add_f32_e32 v201, v45, v201
	v_add_f32_e32 v201, v46, v201
	v_add_f32_e32 v201, v47, v201
	v_add_f32_e32 v201, v48, v201
	v_add_f32_e32 v201, v49, v201
	v_add_f32_e32 v201, v50, v201
	v_add_f32_e32 v201, v51, v201
	v_add_f32_e32 v201, v52, v201
	v_add_f32_e32 v201, v53, v201
	v_add_f32_e32 v201, v54, v201
	v_add_f32_e32 v201, v55, v201
	v_add_f32_e32 v201, v56, v201
	v_add_f32_e32 v201, v57, v201
	v_add_f32_e32 v201, v58, v201
	v_add_f32_e32 v201, v59, v201
	v_add_f32_e32 v201, v60, v201
	v_add_f32_e32 v201, v61, v201
	v_add_f32_e32 v201, v62, v201
	v_add_f32_e32 v201, v63, v201
	v_add_f32_e32 v201, v64, v201
	v_add_f32_e32 v201, v65, v201
	v_add_f32_e32 v201, v66, v201
	v_add_f32_e32 v201, v67, v201
	ds_bpermute_b32 v199, v196, v201
	s_waitcnt lgkmcnt(0)
	v_add_f32_e32 v201, v201, v199
	ds_bpermute_b32 v199, v197, v201
	s_waitcnt lgkmcnt(0)
	v_add_f32_e32 v201, v201, v199
	v_div_scale_f32 v199, s[8:9], v201, v201, 1.0
	v_rcp_f32_e32 v200, v199
	s_nop 0
	v_fma_f32 v244, -v199, v200, 1.0
	v_fmac_f32_e32 v200, v244, v200
	v_div_scale_f32 v244, vcc, 1.0, v201, 1.0
	v_mul_f32_e32 v202, v244, v200
	v_fma_f32 v203, -v199, v202, v244
	v_fmac_f32_e32 v202, v203, v200
	v_fma_f32 v199, -v199, v202, v244
	s_nop 1
	v_div_fmas_f32 v199, v199, v200, v202
	v_div_fixup_f32 v244, v199, v201, 1.0
	v_cvt_pk_bf16_f32 v4, v4, v5
	v_cvt_pk_bf16_f32 v5, v6, v7
	v_cvt_pk_bf16_f32 v6, v8, v9
	v_cvt_pk_bf16_f32 v7, v10, v11
	v_cvt_pk_bf16_f32 v12, v12, v13
	v_cvt_pk_bf16_f32 v13, v14, v15
	v_cvt_pk_bf16_f32 v14, v16, v17
	v_cvt_pk_bf16_f32 v15, v18, v19
	v_cvt_pk_bf16_f32 v20, v20, v21
	v_cvt_pk_bf16_f32 v21, v22, v23
	v_cvt_pk_bf16_f32 v22, v24, v25
	v_cvt_pk_bf16_f32 v23, v26, v27
	v_cvt_pk_bf16_f32 v28, v28, v29
	v_cvt_pk_bf16_f32 v29, v30, v31
	v_cvt_pk_bf16_f32 v30, v32, v33
	v_cvt_pk_bf16_f32 v31, v34, v35
	v_cvt_pk_bf16_f32 v36, v36, v37
	v_cvt_pk_bf16_f32 v37, v38, v39
	v_cvt_pk_bf16_f32 v38, v40, v41
	v_cvt_pk_bf16_f32 v39, v42, v43
	v_cvt_pk_bf16_f32 v44, v44, v45
	v_cvt_pk_bf16_f32 v45, v46, v47
	v_cvt_pk_bf16_f32 v46, v48, v49
	v_cvt_pk_bf16_f32 v47, v50, v51
	v_cvt_pk_bf16_f32 v52, v52, v53
	v_cvt_pk_bf16_f32 v53, v54, v55
	v_cvt_pk_bf16_f32 v54, v56, v57
	v_cvt_pk_bf16_f32 v55, v58, v59
	v_cvt_pk_bf16_f32 v60, v60, v61
	v_cvt_pk_bf16_f32 v61, v62, v63
	v_cvt_pk_bf16_f32 v62, v64, v65
	v_cvt_pk_bf16_f32 v63, v66, v67
	v_mov_b32_e32 v198, 0xf149f2ca
	v_mul_f32_e32 v199, 0x3d8293ee, v68
	v_mul_f32_e32 v200, 0x3d8293ee, v69
	v_max3_f32 v198, v198, v199, v200
; __device__ void cross_items(const Params& p, LAS unsigned char* lds) {
;     ...
;         const float scl = 0.04419417382415922f * LOG2E;
;         float mx = -1e30f;
; #pragma unroll
;         for (int kt = 0; kt < 16; ++kt)
; #pragma unroll
;             for (int rr = 0; rr < 4; ++rr) { const float sv = sc[kt][rr] * scl; sc[kt][rr] = sv; mx = fmaxf(mx, sv); }
;         mx = fmaxf(mx, __shfl_xor(mx, 16)); mx = fmaxf(mx, __shfl_xor(mx, 32));
	v_mul_f32_e32 v199, 0x3d8293ee, v70
	v_mul_f32_e32 v200, 0x3d8293ee, v71
	v_max3_f32 v198, v198, v199, v200
	v_mul_f32_e32 v199, 0x3d8293ee, v72
	v_mul_f32_e32 v200, 0x3d8293ee, v73
	v_max3_f32 v198, v198, v199, v200
	v_mul_f32_e32 v199, 0x3d8293ee, v74
	v_mul_f32_e32 v200, 0x3d8293ee, v75
	v_max3_f32 v198, v198, v199, v200
	v_mul_f32_e32 v199, 0x3d8293ee, v76
	v_mul_f32_e32 v200, 0x3d8293ee, v77
	v_max3_f32 v198, v198, v199, v200
	v_mul_f32_e32 v199, 0x3d8293ee, v78
	v_mul_f32_e32 v200, 0x3d8293ee, v79
	v_max3_f32 v198, v198, v199, v200
	v_mul_f32_e32 v199, 0x3d8293ee, v80
	v_mul_f32_e32 v200, 0x3d8293ee, v81
	v_max3_f32 v198, v198, v199, v200
	v_mul_f32_e32 v199, 0x3d8293ee, v82
	v_mul_f32_e32 v200, 0x3d8293ee, v83
	v_max3_f32 v198, v198, v199, v200
	v_mul_f32_e32 v199, 0x3d8293ee, v84
	v_mul_f32_e32 v200, 0x3d8293ee, v85
	v_max3_f32 v198, v198, v199, v200
	v_mul_f32_e32 v199, 0x3d8293ee, v86
	v_mul_f32_e32 v200, 0x3d8293ee, v87
	v_max3_f32 v198, v198, v199, v200
	v_mul_f32_e32 v199, 0x3d8293ee, v88
	v_mul_f32_e32 v200, 0x3d8293ee, v89
	v_max3_f32 v198, v198, v199, v200
	v_mul_f32_e32 v199, 0x3d8293ee, v90
	v_mul_f32_e32 v200, 0x3d8293ee, v91
	v_max3_f32 v198, v198, v199, v200
	v_mul_f32_e32 v199, 0x3d8293ee, v92
	v_mul_f32_e32 v200, 0x3d8293ee, v93
	v_max3_f32 v198, v198, v199, v200
	v_mul_f32_e32 v199, 0x3d8293ee, v94
	v_mul_f32_e32 v200, 0x3d8293ee, v95
	v_max3_f32 v198, v198, v199, v200
	v_mul_f32_e32 v199, 0x3d8293ee, v96
	v_mul_f32_e32 v200, 0x3d8293ee, v97
	v_max3_f32 v198, v198, v199, v200
	v_mul_f32_e32 v199, 0x3d8293ee, v98
	v_mul_f32_e32 v200, 0x3d8293ee, v99
	v_max3_f32 v198, v198, v199, v200
	v_mul_f32_e32 v199, 0x3d8293ee, v100
	v_mul_f32_e32 v200, 0x3d8293ee, v101
	v_max3_f32 v198, v198, v199, v200
	v_mul_f32_e32 v199, 0x3d8293ee, v102
	v_mul_f32_e32 v200, 0x3d8293ee, v103
	v_max3_f32 v198, v198, v199, v200
	v_mul_f32_e32 v199, 0x3d8293ee, v104
	v_mul_f32_e32 v200, 0x3d8293ee, v105
	v_max3_f32 v198, v198, v199, v200
	v_mul_f32_e32 v199, 0x3d8293ee, v106
	v_mul_f32_e32 v200, 0x3d8293ee, v107
	v_max3_f32 v198, v198, v199, v200
	v_mul_f32_e32 v199, 0x3d8293ee, v108
	v_mul_f32_e32 v200, 0x3d8293ee, v109
	v_max3_f32 v198, v198, v199, v200
	v_mul_f32_e32 v199, 0x3d8293ee, v110
	v_mul_f32_e32 v200, 0x3d8293ee, v111
	v_max3_f32 v198, v198, v199, v200
	v_mul_f32_e32 v199, 0x3d8293ee, v112
	v_mul_f32_e32 v200, 0x3d8293ee, v113
	v_max3_f32 v198, v198, v199, v200
	v_mul_f32_e32 v199, 0x3d8293ee, v114
	v_mul_f32_e32 v200, 0x3d8293ee, v115
	v_max3_f32 v198, v198, v199, v200
	v_mul_f32_e32 v199, 0x3d8293ee, v116
	v_mul_f32_e32 v200, 0x3d8293ee, v117
	v_max3_f32 v198, v198, v199, v200
	v_mul_f32_e32 v199, 0x3d8293ee, v118
	v_mul_f32_e32 v200, 0x3d8293ee, v119
	v_max3_f32 v198, v198, v199, v200
	v_mul_f32_e32 v199, 0x3d8293ee, v120
	v_mul_f32_e32 v200, 0x3d8293ee, v121
	v_max3_f32 v198, v198, v199, v200
	v_mul_f32_e32 v199, 0x3d8293ee, v122
	v_mul_f32_e32 v200, 0x3d8293ee, v123
	v_max3_f32 v198, v198, v199, v200
	v_mul_f32_e32 v199, 0x3d8293ee, v124
	v_mul_f32_e32 v200, 0x3d8293ee, v125
	v_max3_f32 v198, v198, v199, v200
	v_mul_f32_e32 v199, 0x3d8293ee, v126
	v_mul_f32_e32 v200, 0x3d8293ee, v127
	v_max3_f32 v198, v198, v199, v200
	v_mul_f32_e32 v199, 0x3d8293ee, v128
	v_mul_f32_e32 v200, 0x3d8293ee, v129
	v_max3_f32 v198, v198, v199, v200
	v_mul_f32_e32 v199, 0x3d8293ee, v130
	v_mul_f32_e32 v200, 0x3d8293ee, v131
	v_max3_f32 v198, v198, v199, v200
	ds_bpermute_b32 v199, v196, v198
	s_waitcnt lgkmcnt(0)
	v_max_f32_e32 v198, v198, v199
	ds_bpermute_b32 v199, v197, v198
	s_waitcnt lgkmcnt(0)
	v_max_f32_e32 v198, v198, v199
	v_fma_f32 v68, v68, s5, -v198
	v_fma_f32 v69, v69, s5, -v198
	v_fma_f32 v70, v70, s5, -v198
	v_fma_f32 v71, v71, s5, -v198
	v_fma_f32 v72, v72, s5, -v198
	v_fma_f32 v73, v73, s5, -v198
	v_fma_f32 v74, v74, s5, -v198
	v_fma_f32 v75, v75, s5, -v198
	v_fma_f32 v76, v76, s5, -v198
	v_fma_f32 v77, v77, s5, -v198
	v_fma_f32 v78, v78, s5, -v198
	v_fma_f32 v79, v79, s5, -v198
	v_fma_f32 v80, v80, s5, -v198
	v_fma_f32 v81, v81, s5, -v198
	v_fma_f32 v82, v82, s5, -v198
	v_fma_f32 v83, v83, s5, -v198
	v_fma_f32 v84, v84, s5, -v198
	v_fma_f32 v85, v85, s5, -v198
	v_fma_f32 v86, v86, s5, -v198
	v_fma_f32 v87, v87, s5, -v198
	v_fma_f32 v88, v88, s5, -v198
	v_fma_f32 v89, v89, s5, -v198
	v_fma_f32 v90, v90, s5, -v198
	v_fma_f32 v91, v91, s5, -v198
	v_fma_f32 v92, v92, s5, -v198
	v_fma_f32 v93, v93, s5, -v198
	v_fma_f32 v94, v94, s5, -v198
	v_fma_f32 v95, v95, s5, -v198
	v_fma_f32 v96, v96, s5, -v198
	v_fma_f32 v97, v97, s5, -v198
	v_fma_f32 v98, v98, s5, -v198
	v_fma_f32 v99, v99, s5, -v198
	v_fma_f32 v100, v100, s5, -v198
	v_fma_f32 v101, v101, s5, -v198
	v_fma_f32 v102, v102, s5, -v198
	v_fma_f32 v103, v103, s5, -v198
	v_fma_f32 v104, v104, s5, -v198
	v_fma_f32 v105, v105, s5, -v198
	v_fma_f32 v106, v106, s5, -v198
	v_fma_f32 v107, v107, s5, -v198
	v_fma_f32 v108, v108, s5, -v198
	v_fma_f32 v109, v109, s5, -v198
	v_fma_f32 v110, v110, s5, -v198
	v_fma_f32 v111, v111, s5, -v198
	v_fma_f32 v112, v112, s5, -v198
	v_fma_f32 v113, v113, s5, -v198
	v_fma_f32 v114, v114, s5, -v198
	v_fma_f32 v115, v115, s5, -v198
	v_fma_f32 v116, v116, s5, -v198
	v_fma_f32 v117, v117, s5, -v198
	v_fma_f32 v118, v118, s5, -v198
	v_fma_f32 v119, v119, s5, -v198
	v_fma_f32 v120, v120, s5, -v198
	v_fma_f32 v121, v121, s5, -v198
	v_fma_f32 v122, v122, s5, -v198
	v_fma_f32 v123, v123, s5, -v198
	v_fma_f32 v124, v124, s5, -v198
	v_fma_f32 v125, v125, s5, -v198
	v_fma_f32 v126, v126, s5, -v198
	v_fma_f32 v127, v127, s5, -v198
	v_fma_f32 v128, v128, s5, -v198
	v_fma_f32 v129, v129, s5, -v198
	v_fma_f32 v130, v130, s5, -v198
	v_fma_f32 v131, v131, s5, -v198
; #define LAS __attribute__((address_space(3)))
; __device__ __forceinline__ unsigned cvt_pk_bf16(float lo, float hi) { const f32x2v v = {lo, hi}; const b16x2v r = __builtin_convertvector(v, b16x2v); return __builtin_bit_cast(unsigned, r); }
; __device__ __forceinline__ float fexp2(float x) { return __builtin_amdgcn_exp2f(x); }
; #define LDS_BARRIER() do { asm volatile("s_waitcnt lgkmcnt(0)" ::: "memory"); __builtin_amdgcn_s_barrier(); asm volatile("" ::: "memory"); } while (0)
; #define XLOAD(kvbase, c8) do { const bf16_t* _src = (kvbase) + (((c8) >= 4) ? 2048 : 0) + ((c8) & 3) * 128 + piece * 8; \
;         _Pragma("unroll") for (int _it = 0; _it < 8; ++_it) pre[_it] = *(const u32x4*)(_src + (size_t)(srow + 32 * _it) * 4096); } while (0)
; #define XSTORE(buf) do { _Pragma("unroll") for (int _it = 0; _it < 8; ++_it) *(LAS u32x4*)((buf) + (srow + 32 * _it) * KV_STRIDE + piece * 16) = pre[_it]; } while (0)
; __device__ void cross_items(const Params& p, LAS unsigned char* lds) {
;     ...
;         float sum = 0.f;
; #pragma unroll
;         for (int kt = 0; kt < 16; ++kt)
; #pragma unroll
;             for (int rr = 0; rr < 4; ++rr) { const float e = fexp2(sc[kt][rr] - mx); sc[kt][rr] = e; sum += e; }
;         sum += __shfl_xor(sum, 16); sum += __shfl_xor(sum, 32);
;         const float inv = 1.0f / sum;
;         bf16x8 pf[8];
; #pragma unroll
;         for (int sx = 0; sx < 8; ++sx) { u32x4 pw; pw.x = cvt_pk_bf16(sc[2 * sx][0], sc[2 * sx][1]); pw.y = cvt_pk_bf16(sc[2 * sx][2], sc[2 * sx][3]); pw.z = cvt_pk_bf16(sc[2 * sx + 1][0], sc[2 * sx + 1][1]); pw.w = cvt_pk_bf16(sc[2 * sx + 1][2], sc[2 * sx + 1][3]);
;             pf[sx] = __builtin_bit_cast(bf16x8, pw); }
;     ...
;         for (int c = 0; c < 4; ++c) {
;             LAS unsigned char* buf = lds + (c & 1) * KV_BUF;
;             XSTORE(buf);
;             if (c < 3) XLOAD(kvb, 5 + c); else XLOAD(nkvb, 0);
;             LDS_BARRIER();
	v_exp_f32_e32 v68, v68
	v_exp_f32_e32 v69, v69
	v_exp_f32_e32 v70, v70
	v_exp_f32_e32 v71, v71
	v_exp_f32_e32 v72, v72
	v_exp_f32_e32 v73, v73
	v_exp_f32_e32 v74, v74
	v_exp_f32_e32 v75, v75
	v_exp_f32_e32 v76, v76
	v_exp_f32_e32 v77, v77
	v_exp_f32_e32 v78, v78
	v_exp_f32_e32 v79, v79
	v_exp_f32_e32 v80, v80
	v_exp_f32_e32 v81, v81
	v_exp_f32_e32 v82, v82
	v_exp_f32_e32 v83, v83
	v_exp_f32_e32 v84, v84
	v_exp_f32_e32 v85, v85
	v_exp_f32_e32 v86, v86
	v_exp_f32_e32 v87, v87
	v_exp_f32_e32 v88, v88
	v_exp_f32_e32 v89, v89
	v_exp_f32_e32 v90, v90
	v_exp_f32_e32 v91, v91
	v_exp_f32_e32 v92, v92
	v_exp_f32_e32 v93, v93
	v_exp_f32_e32 v94, v94
	v_exp_f32_e32 v95, v95
	v_exp_f32_e32 v96, v96
	v_exp_f32_e32 v97, v97
	v_exp_f32_e32 v98, v98
	v_exp_f32_e32 v99, v99
	v_exp_f32_e32 v100, v100
	v_exp_f32_e32 v101, v101
	v_exp_f32_e32 v102, v102
	v_exp_f32_e32 v103, v103
	v_exp_f32_e32 v104, v104
	v_exp_f32_e32 v105, v105
	v_exp_f32_e32 v106, v106
	v_exp_f32_e32 v107, v107
	v_exp_f32_e32 v108, v108
	v_exp_f32_e32 v109, v109
	v_exp_f32_e32 v110, v110
	v_exp_f32_e32 v111, v111
	v_exp_f32_e32 v112, v112
	v_exp_f32_e32 v113, v113
	v_exp_f32_e32 v114, v114
	v_exp_f32_e32 v115, v115
	v_exp_f32_e32 v116, v116
	v_exp_f32_e32 v117, v117
	v_exp_f32_e32 v118, v118
	v_exp_f32_e32 v119, v119
	v_exp_f32_e32 v120, v120
	v_exp_f32_e32 v121, v121
	v_exp_f32_e32 v122, v122
	v_exp_f32_e32 v123, v123
	v_exp_f32_e32 v124, v124
	v_exp_f32_e32 v125, v125
	v_exp_f32_e32 v126, v126
	v_exp_f32_e32 v127, v127
	v_exp_f32_e32 v128, v128
	v_exp_f32_e32 v129, v129
	v_exp_f32_e32 v130, v130
	v_exp_f32_e32 v131, v131
	s_nop 0
	v_add_f32_e32 v201, 0, v68
	v_add_f32_e32 v201, v69, v201
	v_add_f32_e32 v201, v70, v201
	v_add_f32_e32 v201, v71, v201
	v_add_f32_e32 v201, v72, v201
	v_add_f32_e32 v201, v73, v201
	v_add_f32_e32 v201, v74, v201
	v_add_f32_e32 v201, v75, v201
	v_add_f32_e32 v201, v76, v201
	v_add_f32_e32 v201, v77, v201
	v_add_f32_e32 v201, v78, v201
	v_add_f32_e32 v201, v79, v201
	v_add_f32_e32 v201, v80, v201
	v_add_f32_e32 v201, v81, v201
	v_add_f32_e32 v201, v82, v201
	v_add_f32_e32 v201, v83, v201
	v_add_f32_e32 v201, v84, v201
	v_add_f32_e32 v201, v85, v201
	v_add_f32_e32 v201, v86, v201
	v_add_f32_e32 v201, v87, v201
	v_add_f32_e32 v201, v88, v201
	v_add_f32_e32 v201, v89, v201
	v_add_f32_e32 v201, v90, v201
	v_add_f32_e32 v201, v91, v201
	v_add_f32_e32 v201, v92, v201
	v_add_f32_e32 v201, v93, v201
	v_add_f32_e32 v201, v94, v201
	v_add_f32_e32 v201, v95, v201
	v_add_f32_e32 v201, v96, v201
	v_add_f32_e32 v201, v97, v201
	v_add_f32_e32 v201, v98, v201
	v_add_f32_e32 v201, v99, v201
	v_add_f32_e32 v201, v100, v201
	v_add_f32_e32 v201, v101, v201
	v_add_f32_e32 v201, v102, v201
	v_add_f32_e32 v201, v103, v201
	v_add_f32_e32 v201, v104, v201
	v_add_f32_e32 v201, v105, v201
	v_add_f32_e32 v201, v106, v201
	v_add_f32_e32 v201, v107, v201
	v_add_f32_e32 v201, v108, v201
	v_add_f32_e32 v201, v109, v201
	v_add_f32_e32 v201, v110, v201
	v_add_f32_e32 v201, v111, v201
	v_add_f32_e32 v201, v112, v201
	v_add_f32_e32 v201, v113, v201
	v_add_f32_e32 v201, v114, v201
	v_add_f32_e32 v201, v115, v201
	v_add_f32_e32 v201, v116, v201
	v_add_f32_e32 v201, v117, v201
	v_add_f32_e32 v201, v118, v201
	v_add_f32_e32 v201, v119, v201
	v_add_f32_e32 v201, v120, v201
	v_add_f32_e32 v201, v121, v201
	v_add_f32_e32 v201, v122, v201
	v_add_f32_e32 v201, v123, v201
	v_add_f32_e32 v201, v124, v201
	v_add_f32_e32 v201, v125, v201
	v_add_f32_e32 v201, v126, v201
	v_add_f32_e32 v201, v127, v201
	v_add_f32_e32 v201, v128, v201
	v_add_f32_e32 v201, v129, v201
	v_add_f32_e32 v201, v130, v201
	v_add_f32_e32 v201, v131, v201
	ds_bpermute_b32 v199, v196, v201
	s_waitcnt lgkmcnt(0)
	v_add_f32_e32 v201, v201, v199
	ds_bpermute_b32 v199, v197, v201
	s_waitcnt lgkmcnt(0)
	v_add_f32_e32 v201, v201, v199
	v_div_scale_f32 v199, s[8:9], v201, v201, 1.0
	v_rcp_f32_e32 v200, v199
	s_nop 0
	v_fma_f32 v245, -v199, v200, 1.0
	v_fmac_f32_e32 v200, v245, v200
	v_div_scale_f32 v245, vcc, 1.0, v201, 1.0
	v_mul_f32_e32 v202, v245, v200
	v_fma_f32 v203, -v199, v202, v245
	v_fmac_f32_e32 v202, v203, v200
	v_fma_f32 v199, -v199, v202, v245
	s_nop 1
	v_div_fmas_f32 v199, v199, v200, v202
	v_div_fixup_f32 v245, v199, v201, 1.0
	v_cvt_pk_bf16_f32 v68, v68, v69
	v_cvt_pk_bf16_f32 v69, v70, v71
	v_cvt_pk_bf16_f32 v70, v72, v73
	v_cvt_pk_bf16_f32 v71, v74, v75
	v_cvt_pk_bf16_f32 v76, v76, v77
	v_cvt_pk_bf16_f32 v77, v78, v79
	v_cvt_pk_bf16_f32 v78, v80, v81
	v_cvt_pk_bf16_f32 v79, v82, v83
	v_cvt_pk_bf16_f32 v84, v84, v85
	v_cvt_pk_bf16_f32 v85, v86, v87
	v_cvt_pk_bf16_f32 v86, v88, v89
	v_cvt_pk_bf16_f32 v87, v90, v91
	v_cvt_pk_bf16_f32 v92, v92, v93
	v_cvt_pk_bf16_f32 v93, v94, v95
	v_cvt_pk_bf16_f32 v94, v96, v97
	v_cvt_pk_bf16_f32 v95, v98, v99
	v_cvt_pk_bf16_f32 v100, v100, v101
	v_cvt_pk_bf16_f32 v101, v102, v103
	v_cvt_pk_bf16_f32 v102, v104, v105
	v_cvt_pk_bf16_f32 v103, v106, v107
	v_cvt_pk_bf16_f32 v108, v108, v109
	v_cvt_pk_bf16_f32 v109, v110, v111
	v_cvt_pk_bf16_f32 v110, v112, v113
	v_cvt_pk_bf16_f32 v111, v114, v115
	v_cvt_pk_bf16_f32 v116, v116, v117
	v_cvt_pk_bf16_f32 v117, v118, v119
	v_cvt_pk_bf16_f32 v118, v120, v121
	v_cvt_pk_bf16_f32 v119, v122, v123
	v_cvt_pk_bf16_f32 v124, v124, v125
	v_cvt_pk_bf16_f32 v125, v126, v127
	v_cvt_pk_bf16_f32 v126, v128, v129
	v_cvt_pk_bf16_f32 v127, v130, v131
	s_waitcnt vmcnt(7)
	ds_write_b128 v0, v[164:167]
	s_waitcnt vmcnt(6)
	ds_write_b128 v0, v[168:171] offset:8704
	s_waitcnt vmcnt(5)
	ds_write_b128 v0, v[172:175] offset:17408
	s_waitcnt vmcnt(4)
	ds_write_b128 v0, v[176:179] offset:26112
	s_waitcnt vmcnt(3)
	ds_write_b128 v0, v[180:183] offset:34816
	s_waitcnt vmcnt(2)
	ds_write_b128 v0, v[184:187] offset:43520
	s_waitcnt vmcnt(1)
	ds_write_b128 v0, v[188:191] offset:52224
	s_waitcnt vmcnt(0)
	ds_write_b128 v0, v[192:195] offset:60928
	global_load_dwordx4 v[164:167], v242, s[6:7] offset:256
	v_add_u32_e32 v243, 0x40000, v242
	global_load_dwordx4 v[168:171], v243, s[6:7] offset:256
	v_add_u32_e32 v243, 0x80000, v242
	global_load_dwordx4 v[172:175], v243, s[6:7] offset:256
	v_add_u32_e32 v243, 0xc0000, v242
	global_load_dwordx4 v[176:179], v243, s[6:7] offset:256
	v_add_u32_e32 v243, 0x100000, v242
	global_load_dwordx4 v[180:183], v243, s[6:7] offset:256
	v_add_u32_e32 v243, 0x140000, v242
	global_load_dwordx4 v[184:187], v243, s[6:7] offset:256
	v_add_u32_e32 v243, 0x180000, v242
	global_load_dwordx4 v[188:191], v243, s[6:7] offset:256
	v_add_u32_e32 v243, 0x1c0000, v242
	global_load_dwordx4 v[192:195], v243, s[6:7] offset:256
	s_waitcnt lgkmcnt(0)
	s_barrier
; #define LAS __attribute__((address_space(3)))
; __device__ __forceinline__ f32x4 mfma16(bf16x8 a, bf16x8 b, f32x4 c) { return __builtin_amdgcn_mfma_f32_16x16x32_bf16(a, b, c, 0, 0, 0); }
; #define LDS_BARRIER() do { asm volatile("s_waitcnt lgkmcnt(0)" ::: "memory"); __builtin_amdgcn_s_barrier(); asm volatile("" ::: "memory"); } while (0)
; #define XLOAD(kvbase, c8) do { const bf16_t* _src = (kvbase) + (((c8) >= 4) ? 2048 : 0) + ((c8) & 3) * 128 + piece * 8; \
;         _Pragma("unroll") for (int _it = 0; _it < 8; ++_it) pre[_it] = *(const u32x4*)(_src + (size_t)(srow + 32 * _it) * 4096); } while (0)
; #define XSTORE(buf) do { _Pragma("unroll") for (int _it = 0; _it < 8; ++_it) *(LAS u32x4*)((buf) + (srow + 32 * _it) * KV_STRIDE + piece * 16) = pre[_it]; } while (0)
; __device__ void cross_items(const Params& p, LAS unsigned char* lds) {
;     ...
;         for (int c = 0; c < 4; ++c) {
;             LAS unsigned char* buf = lds + (c & 1) * KV_BUF;
;             XSTORE(buf);
;             if (c < 3) XLOAD(kvb, 5 + c); else XLOAD(nkvb, 0);
;             LDS_BARRIER();
;             f32x4 ot[8];
; #pragma unroll
;             for (int c8 = 0; c8 < 8; ++c8) ot[c8] = (f32x4){0.f, 0.f, 0.f, 0.f};
;             const unsigned bb = lbase + (unsigned)((c & 1) * KV_BUF);
; #pragma unroll
;             for (int sx = 0; sx < 8; ++sx) {
;                 const unsigned aA = bb + (unsigned)((32 * sx + 4 * g + (idx >> 2)) * KV_STRIDE + 8 * (idx & 3));
;                 const unsigned aB = aA + 16u * KV_STRIDE;
;                 bf16x8 vf[4];
;                 tr_frag4(aA, aB, vf);
; #pragma unroll
;                 for (int c8 = 0; c8 < 4; ++c8) ot[c8] = mfma16(vf[c8], pf[sx], ot[c8]);
;                 tr_frag4(aA + 128, aB + 128, vf);
; #pragma unroll
;                 for (int c8 = 0; c8 < 4; ++c8) ot[4 + c8] = mfma16(vf[c8], pf[sx], ot[4 + c8]);
	ds_read_b64_tr_b16 v[72:73], v209
	ds_read_b64_tr_b16 v[80:81], v209 offset:32
	ds_read_b64_tr_b16 v[74:75], v209 offset:4352
	ds_read_b64_tr_b16 v[82:83], v209 offset:4384
	ds_read_b64_tr_b16 v[88:89], v209 offset:64
	ds_read_b64_tr_b16 v[96:97], v209 offset:96
	ds_read_b64_tr_b16 v[90:91], v209 offset:4416
	ds_read_b64_tr_b16 v[98:99], v209 offset:4448
	ds_read_b64_tr_b16 v[104:105], v209 offset:128
	ds_read_b64_tr_b16 v[112:113], v209 offset:160
	ds_read_b64_tr_b16 v[106:107], v209 offset:4480
	ds_read_b64_tr_b16 v[114:115], v209 offset:4512
	s_waitcnt lgkmcnt(8)
	ds_read_b64_tr_b16 v[120:121], v209 offset:192
	ds_read_b64_tr_b16 v[128:129], v209 offset:224
	ds_read_b64_tr_b16 v[122:123], v209 offset:4544
	ds_read_b64_tr_b16 v[130:131], v209 offset:4576
	v_mfma_f32_16x16x32_bf16 v[132:135], v[72:75], v[4:7], 0
	v_mfma_f32_16x16x32_bf16 v[8:11], v[72:75], v[68:71], 0
	v_mfma_f32_16x16x32_bf16 v[136:139], v[80:83], v[4:7], 0
	v_mfma_f32_16x16x32_bf16 v[16:19], v[80:83], v[68:71], 0
	s_waitcnt lgkmcnt(8)
	ds_read_b64_tr_b16 v[72:73], v209 offset:8704
	ds_read_b64_tr_b16 v[80:81], v209 offset:8736
	ds_read_b64_tr_b16 v[74:75], v209 offset:13056
	ds_read_b64_tr_b16 v[82:83], v209 offset:13088
	v_mfma_f32_16x16x32_bf16 v[140:143], v[88:91], v[4:7], 0
	v_mfma_f32_16x16x32_bf16 v[24:27], v[88:91], v[68:71], 0
	v_mfma_f32_16x16x32_bf16 v[144:147], v[96:99], v[4:7], 0
	v_mfma_f32_16x16x32_bf16 v[32:35], v[96:99], v[68:71], 0
	s_waitcnt lgkmcnt(8)
	ds_read_b64_tr_b16 v[88:89], v209 offset:8768
	ds_read_b64_tr_b16 v[96:97], v209 offset:8800
	ds_read_b64_tr_b16 v[90:91], v209 offset:13120
	ds_read_b64_tr_b16 v[98:99], v209 offset:13152
	v_mfma_f32_16x16x32_bf16 v[148:151], v[104:107], v[4:7], 0
	v_mfma_f32_16x16x32_bf16 v[40:43], v[104:107], v[68:71], 0
	v_mfma_f32_16x16x32_bf16 v[152:155], v[112:115], v[4:7], 0
	v_mfma_f32_16x16x32_bf16 v[48:51], v[112:115], v[68:71], 0
	s_waitcnt lgkmcnt(8)
	ds_read_b64_tr_b16 v[104:105], v209 offset:8832
	ds_read_b64_tr_b16 v[112:113], v209 offset:8864
	ds_read_b64_tr_b16 v[106:107], v209 offset:13184
	ds_read_b64_tr_b16 v[114:115], v209 offset:13216
	v_mfma_f32_16x16x32_bf16 v[156:159], v[120:123], v[4:7], 0
	v_mfma_f32_16x16x32_bf16 v[56:59], v[120:123], v[68:71], 0
	v_mfma_f32_16x16x32_bf16 v[160:163], v[128:131], v[4:7], 0
	v_mfma_f32_16x16x32_bf16 v[64:67], v[128:131], v[68:71], 0
	s_waitcnt lgkmcnt(8)
	ds_read_b64_tr_b16 v[120:121], v209 offset:8896
	ds_read_b64_tr_b16 v[128:129], v209 offset:8928
	ds_read_b64_tr_b16 v[122:123], v209 offset:13248
	ds_read_b64_tr_b16 v[130:131], v209 offset:13280
	v_mfma_f32_16x16x32_bf16 v[132:135], v[72:75], v[12:15], v[132:135]
	v_mfma_f32_16x16x32_bf16 v[8:11], v[72:75], v[76:79], v[8:11]
	v_mfma_f32_16x16x32_bf16 v[136:139], v[80:83], v[12:15], v[136:139]
	v_mfma_f32_16x16x32_bf16 v[16:19], v[80:83], v[76:79], v[16:19]
	s_waitcnt lgkmcnt(8)
	ds_read_b64_tr_b16 v[72:73], v209 offset:17408
	ds_read_b64_tr_b16 v[80:81], v209 offset:17440
	ds_read_b64_tr_b16 v[74:75], v209 offset:21760
	ds_read_b64_tr_b16 v[82:83], v209 offset:21792
	v_mfma_f32_16x16x32_bf16 v[140:143], v[88:91], v[12:15], v[140:143]
	v_mfma_f32_16x16x32_bf16 v[24:27], v[88:91], v[76:79], v[24:27]
	v_mfma_f32_16x16x32_bf16 v[144:147], v[96:99], v[12:15], v[144:147]
	v_mfma_f32_16x16x32_bf16 v[32:35], v[96:99], v[76:79], v[32:35]
	s_waitcnt lgkmcnt(8)
	ds_read_b64_tr_b16 v[88:89], v209 offset:17472
	ds_read_b64_tr_b16 v[96:97], v209 offset:17504
	ds_read_b64_tr_b16 v[90:91], v209 offset:21824
	ds_read_b64_tr_b16 v[98:99], v209 offset:21856
	v_mfma_f32_16x16x32_bf16 v[148:151], v[104:107], v[12:15], v[148:151]
	v_mfma_f32_16x16x32_bf16 v[40:43], v[104:107], v[76:79], v[40:43]
	v_mfma_f32_16x16x32_bf16 v[152:155], v[112:115], v[12:15], v[152:155]
	v_mfma_f32_16x16x32_bf16 v[48:51], v[112:115], v[76:79], v[48:51]
	s_waitcnt lgkmcnt(8)
	ds_read_b64_tr_b16 v[104:105], v209 offset:17536
	ds_read_b64_tr_b16 v[112:113], v209 offset:17568
	ds_read_b64_tr_b16 v[106:107], v209 offset:21888
	ds_read_b64_tr_b16 v[114:115], v209 offset:21920
	v_mfma_f32_16x16x32_bf16 v[156:159], v[120:123], v[12:15], v[156:159]
	v_mfma_f32_16x16x32_bf16 v[56:59], v[120:123], v[76:79], v[56:59]
	v_mfma_f32_16x16x32_bf16 v[160:163], v[128:131], v[12:15], v[160:163]
	v_mfma_f32_16x16x32_bf16 v[64:67], v[128:131], v[76:79], v[64:67]
	s_waitcnt lgkmcnt(8)
	ds_read_b64_tr_b16 v[120:121], v209 offset:17600
	ds_read_b64_tr_b16 v[128:129], v209 offset:17632
	ds_read_b64_tr_b16 v[122:123], v209 offset:21952
	ds_read_b64_tr_b16 v[130:131], v209 offset:21984
	v_mfma_f32_16x16x32_bf16 v[132:135], v[72:75], v[20:23], v[132:135]
	v_mfma_f32_16x16x32_bf16 v[8:11], v[72:75], v[84:87], v[8:11]
	v_mfma_f32_16x16x32_bf16 v[136:139], v[80:83], v[20:23], v[136:139]
	v_mfma_f32_16x16x32_bf16 v[16:19], v[80:83], v[84:87], v[16:19]
	s_waitcnt lgkmcnt(8)
	ds_read_b64_tr_b16 v[72:73], v209 offset:26112
	ds_read_b64_tr_b16 v[80:81], v209 offset:26144
	ds_read_b64_tr_b16 v[74:75], v209 offset:30464
	ds_read_b64_tr_b16 v[82:83], v209 offset:30496
	v_mfma_f32_16x16x32_bf16 v[140:143], v[88:91], v[20:23], v[140:143]
	v_mfma_f32_16x16x32_bf16 v[24:27], v[88:91], v[84:87], v[24:27]
	v_mfma_f32_16x16x32_bf16 v[144:147], v[96:99], v[20:23], v[144:147]
	v_mfma_f32_16x16x32_bf16 v[32:35], v[96:99], v[84:87], v[32:35]
	s_waitcnt lgkmcnt(8)
	ds_read_b64_tr_b16 v[88:89], v209 offset:26176
	ds_read_b64_tr_b16 v[96:97], v209 offset:26208
	ds_read_b64_tr_b16 v[90:91], v209 offset:30528
	ds_read_b64_tr_b16 v[98:99], v209 offset:30560
	v_mfma_f32_16x16x32_bf16 v[148:151], v[104:107], v[20:23], v[148:151]
	v_mfma_f32_16x16x32_bf16 v[40:43], v[104:107], v[84:87], v[40:43]
	v_mfma_f32_16x16x32_bf16 v[152:155], v[112:115], v[20:23], v[152:155]
	v_mfma_f32_16x16x32_bf16 v[48:51], v[112:115], v[84:87], v[48:51]
	s_waitcnt lgkmcnt(8)
; __device__ __forceinline__ f32x4 mfma16(bf16x8 a, bf16x8 b, f32x4 c) { return __builtin_amdgcn_mfma_f32_16x16x32_bf16(a, b, c, 0, 0, 0); }
; __device__ void cross_items(const Params& p, LAS unsigned char* lds) {
;     ...
; #pragma unroll
;             for (int sx = 0; sx < 8; ++sx) {
;                 const unsigned aA = bb + (unsigned)((32 * sx + 4 * g + (idx >> 2)) * KV_STRIDE + 8 * (idx & 3));
;                 const unsigned aB = aA + 16u * KV_STRIDE;
;                 bf16x8 vf[4];
;                 tr_frag4(aA, aB, vf);
; #pragma unroll
;                 for (int c8 = 0; c8 < 4; ++c8) ot[c8] = mfma16(vf[c8], pf[sx], ot[c8]);
;                 tr_frag4(aA + 128, aB + 128, vf);
; #pragma unroll
;                 for (int c8 = 0; c8 < 4; ++c8) ot[4 + c8] = mfma16(vf[c8], pf[sx], ot[4 + c8]);
	ds_read_b64_tr_b16 v[104:105], v209 offset:26240
	ds_read_b64_tr_b16 v[112:113], v209 offset:26272
	ds_read_b64_tr_b16 v[106:107], v209 offset:30592
	ds_read_b64_tr_b16 v[114:115], v209 offset:30624
	v_mfma_f32_16x16x32_bf16 v[156:159], v[120:123], v[20:23], v[156:159]
	v_mfma_f32_16x16x32_bf16 v[56:59], v[120:123], v[84:87], v[56:59]
	v_mfma_f32_16x16x32_bf16 v[160:163], v[128:131], v[20:23], v[160:163]
	v_mfma_f32_16x16x32_bf16 v[64:67], v[128:131], v[84:87], v[64:67]
	s_waitcnt lgkmcnt(8)
	ds_read_b64_tr_b16 v[120:121], v209 offset:26304
	ds_read_b64_tr_b16 v[128:129], v209 offset:26336
	ds_read_b64_tr_b16 v[122:123], v209 offset:30656
	ds_read_b64_tr_b16 v[130:131], v209 offset:30688
	v_mfma_f32_16x16x32_bf16 v[132:135], v[72:75], v[28:31], v[132:135]
	v_mfma_f32_16x16x32_bf16 v[8:11], v[72:75], v[92:95], v[8:11]
	v_mfma_f32_16x16x32_bf16 v[136:139], v[80:83], v[28:31], v[136:139]
	v_mfma_f32_16x16x32_bf16 v[16:19], v[80:83], v[92:95], v[16:19]
	s_waitcnt lgkmcnt(8)
	ds_read_b64_tr_b16 v[72:73], v209 offset:34816
	ds_read_b64_tr_b16 v[80:81], v209 offset:34848
	ds_read_b64_tr_b16 v[74:75], v209 offset:39168
	ds_read_b64_tr_b16 v[82:83], v209 offset:39200
	v_mfma_f32_16x16x32_bf16 v[140:143], v[88:91], v[28:31], v[140:143]
	v_mfma_f32_16x16x32_bf16 v[24:27], v[88:91], v[92:95], v[24:27]
	v_mfma_f32_16x16x32_bf16 v[144:147], v[96:99], v[28:31], v[144:147]
	v_mfma_f32_16x16x32_bf16 v[32:35], v[96:99], v[92:95], v[32:35]
	s_waitcnt lgkmcnt(8)
	ds_read_b64_tr_b16 v[88:89], v209 offset:34880
	ds_read_b64_tr_b16 v[96:97], v209 offset:34912
	ds_read_b64_tr_b16 v[90:91], v209 offset:39232
	ds_read_b64_tr_b16 v[98:99], v209 offset:39264
	v_mfma_f32_16x16x32_bf16 v[148:151], v[104:107], v[28:31], v[148:151]
	v_mfma_f32_16x16x32_bf16 v[40:43], v[104:107], v[92:95], v[40:43]
	v_mfma_f32_16x16x32_bf16 v[152:155], v[112:115], v[28:31], v[152:155]
	v_mfma_f32_16x16x32_bf16 v[48:51], v[112:115], v[92:95], v[48:51]
	s_waitcnt lgkmcnt(8)
	ds_read_b64_tr_b16 v[104:105], v209 offset:34944
	ds_read_b64_tr_b16 v[112:113], v209 offset:34976
	ds_read_b64_tr_b16 v[106:107], v209 offset:39296
	ds_read_b64_tr_b16 v[114:115], v209 offset:39328
	v_mfma_f32_16x16x32_bf16 v[156:159], v[120:123], v[28:31], v[156:159]
	v_mfma_f32_16x16x32_bf16 v[56:59], v[120:123], v[92:95], v[56:59]
	v_mfma_f32_16x16x32_bf16 v[160:163], v[128:131], v[28:31], v[160:163]
	v_mfma_f32_16x16x32_bf16 v[64:67], v[128:131], v[92:95], v[64:67]
	s_waitcnt lgkmcnt(8)
	ds_read_b64_tr_b16 v[120:121], v209 offset:35008
	ds_read_b64_tr_b16 v[128:129], v209 offset:35040
	ds_read_b64_tr_b16 v[122:123], v209 offset:39360
	ds_read_b64_tr_b16 v[130:131], v209 offset:39392
	v_mfma_f32_16x16x32_bf16 v[132:135], v[72:75], v[36:39], v[132:135]
	v_mfma_f32_16x16x32_bf16 v[8:11], v[72:75], v[100:103], v[8:11]
	v_mfma_f32_16x16x32_bf16 v[136:139], v[80:83], v[36:39], v[136:139]
	v_mfma_f32_16x16x32_bf16 v[16:19], v[80:83], v[100:103], v[16:19]
	s_waitcnt lgkmcnt(8)
	ds_read_b64_tr_b16 v[72:73], v209 offset:43520
	ds_read_b64_tr_b16 v[80:81], v209 offset:43552
	ds_read_b64_tr_b16 v[74:75], v209 offset:47872
	ds_read_b64_tr_b16 v[82:83], v209 offset:47904
	v_mfma_f32_16x16x32_bf16 v[140:143], v[88:91], v[36:39], v[140:143]
	v_mfma_f32_16x16x32_bf16 v[24:27], v[88:91], v[100:103], v[24:27]
	v_mfma_f32_16x16x32_bf16 v[144:147], v[96:99], v[36:39], v[144:147]
	v_mfma_f32_16x16x32_bf16 v[32:35], v[96:99], v[100:103], v[32:35]
	s_waitcnt lgkmcnt(8)
	ds_read_b64_tr_b16 v[88:89], v209 offset:43584
	ds_read_b64_tr_b16 v[96:97], v209 offset:43616
	ds_read_b64_tr_b16 v[90:91], v209 offset:47936
	ds_read_b64_tr_b16 v[98:99], v209 offset:47968
	v_mfma_f32_16x16x32_bf16 v[148:151], v[104:107], v[36:39], v[148:151]
	v_mfma_f32_16x16x32_bf16 v[40:43], v[104:107], v[100:103], v[40:43]
	v_mfma_f32_16x16x32_bf16 v[152:155], v[112:115], v[36:39], v[152:155]
	v_mfma_f32_16x16x32_bf16 v[48:51], v[112:115], v[100:103], v[48:51]
	s_waitcnt lgkmcnt(8)
	ds_read_b64_tr_b16 v[104:105], v209 offset:43648
	ds_read_b64_tr_b16 v[112:113], v209 offset:43680
	ds_read_b64_tr_b16 v[106:107], v209 offset:48000
	ds_read_b64_tr_b16 v[114:115], v209 offset:48032
	v_mfma_f32_16x16x32_bf16 v[156:159], v[120:123], v[36:39], v[156:159]
	v_mfma_f32_16x16x32_bf16 v[56:59], v[120:123], v[100:103], v[56:59]
	v_mfma_f32_16x16x32_bf16 v[160:163], v[128:131], v[36:39], v[160:163]
	v_mfma_f32_16x16x32_bf16 v[64:67], v[128:131], v[100:103], v[64:67]
	s_waitcnt lgkmcnt(8)
	ds_read_b64_tr_b16 v[120:121], v209 offset:43712
	ds_read_b64_tr_b16 v[128:129], v209 offset:43744
	ds_read_b64_tr_b16 v[122:123], v209 offset:48064
	ds_read_b64_tr_b16 v[130:131], v209 offset:48096
	v_mfma_f32_16x16x32_bf16 v[132:135], v[72:75], v[44:47], v[132:135]
	v_mfma_f32_16x16x32_bf16 v[8:11], v[72:75], v[108:111], v[8:11]
	v_mfma_f32_16x16x32_bf16 v[136:139], v[80:83], v[44:47], v[136:139]
	v_mfma_f32_16x16x32_bf16 v[16:19], v[80:83], v[108:111], v[16:19]
	s_waitcnt lgkmcnt(8)
	ds_read_b64_tr_b16 v[72:73], v209 offset:52224
	ds_read_b64_tr_b16 v[80:81], v209 offset:52256
	ds_read_b64_tr_b16 v[74:75], v209 offset:56576
	ds_read_b64_tr_b16 v[82:83], v209 offset:56608
	v_mfma_f32_16x16x32_bf16 v[140:143], v[88:91], v[44:47], v[140:143]
	v_mfma_f32_16x16x32_bf16 v[24:27], v[88:91], v[108:111], v[24:27]
	v_mfma_f32_16x16x32_bf16 v[144:147], v[96:99], v[44:47], v[144:147]
	v_mfma_f32_16x16x32_bf16 v[32:35], v[96:99], v[108:111], v[32:35]
	s_waitcnt lgkmcnt(8)
; __device__ __forceinline__ unsigned cvt_pk_bf16(float lo, float hi) { const f32x2v v = {lo, hi}; const b16x2v r = __builtin_convertvector(v, b16x2v); return __builtin_bit_cast(unsigned, r); }
; __device__ __forceinline__ f32x4 mfma16(bf16x8 a, bf16x8 b, f32x4 c) { return __builtin_amdgcn_mfma_f32_16x16x32_bf16(a, b, c, 0, 0, 0); }
; __device__ void cross_items(const Params& p, LAS unsigned char* lds) {
;     ...
; #pragma unroll
;             for (int sx = 0; sx < 8; ++sx) {
;                 const unsigned aA = bb + (unsigned)((32 * sx + 4 * g + (idx >> 2)) * KV_STRIDE + 8 * (idx & 3));
;                 const unsigned aB = aA + 16u * KV_STRIDE;
;                 bf16x8 vf[4];
;                 tr_frag4(aA, aB, vf);
; #pragma unroll
;                 for (int c8 = 0; c8 < 4; ++c8) ot[c8] = mfma16(vf[c8], pf[sx], ot[c8]);
;                 tr_frag4(aA + 128, aB + 128, vf);
; #pragma unroll
;                 for (int c8 = 0; c8 < 4; ++c8) ot[4 + c8] = mfma16(vf[c8], pf[sx], ot[4 + c8]);
;             }
; #pragma unroll
;             for (int c8 = 0; c8 < 8; ++c8) { u32x2 wv; wv.x = cvt_pk_bf16(ot[c8][0] * inv, ot[c8][1] * inv); wv.y = cvt_pk_bf16(ot[c8][2] * inv, ot[c8][3] * inv);
;                 *(u32x2*)(oc + tok * DM + head * 512 + c * 128 + 16 * c8 + 4 * g) = wv; }
	ds_read_b64_tr_b16 v[88:89], v209 offset:52288
	ds_read_b64_tr_b16 v[96:97], v209 offset:52320
	ds_read_b64_tr_b16 v[90:91], v209 offset:56640
	ds_read_b64_tr_b16 v[98:99], v209 offset:56672
	v_mfma_f32_16x16x32_bf16 v[148:151], v[104:107], v[44:47], v[148:151]
	v_mfma_f32_16x16x32_bf16 v[40:43], v[104:107], v[108:111], v[40:43]
	v_mfma_f32_16x16x32_bf16 v[152:155], v[112:115], v[44:47], v[152:155]
	v_mfma_f32_16x16x32_bf16 v[48:51], v[112:115], v[108:111], v[48:51]
	s_waitcnt lgkmcnt(8)
	ds_read_b64_tr_b16 v[104:105], v209 offset:52352
	ds_read_b64_tr_b16 v[112:113], v209 offset:52384
	ds_read_b64_tr_b16 v[106:107], v209 offset:56704
	ds_read_b64_tr_b16 v[114:115], v209 offset:56736
	v_mfma_f32_16x16x32_bf16 v[156:159], v[120:123], v[44:47], v[156:159]
	v_mfma_f32_16x16x32_bf16 v[56:59], v[120:123], v[108:111], v[56:59]
	v_mfma_f32_16x16x32_bf16 v[160:163], v[128:131], v[44:47], v[160:163]
	v_mfma_f32_16x16x32_bf16 v[64:67], v[128:131], v[108:111], v[64:67]
	s_waitcnt lgkmcnt(8)
	ds_read_b64_tr_b16 v[120:121], v209 offset:52416
	ds_read_b64_tr_b16 v[128:129], v209 offset:52448
	ds_read_b64_tr_b16 v[122:123], v209 offset:56768
	ds_read_b64_tr_b16 v[130:131], v209 offset:56800
	v_mfma_f32_16x16x32_bf16 v[132:135], v[72:75], v[52:55], v[132:135]
	v_mfma_f32_16x16x32_bf16 v[8:11], v[72:75], v[116:119], v[8:11]
	v_mfma_f32_16x16x32_bf16 v[136:139], v[80:83], v[52:55], v[136:139]
	v_mfma_f32_16x16x32_bf16 v[16:19], v[80:83], v[116:119], v[16:19]
	s_waitcnt lgkmcnt(8)
	ds_read_b64_tr_b16 v[72:73], v209 offset:60928
	ds_read_b64_tr_b16 v[80:81], v209 offset:60960
	ds_read_b64_tr_b16 v[74:75], v209 offset:65280
	ds_read_b64_tr_b16 v[82:83], v209 offset:65312
	v_mfma_f32_16x16x32_bf16 v[140:143], v[88:91], v[52:55], v[140:143]
	v_mfma_f32_16x16x32_bf16 v[24:27], v[88:91], v[116:119], v[24:27]
	v_mfma_f32_16x16x32_bf16 v[144:147], v[96:99], v[52:55], v[144:147]
	v_mfma_f32_16x16x32_bf16 v[32:35], v[96:99], v[116:119], v[32:35]
	s_waitcnt lgkmcnt(8)
	ds_read_b64_tr_b16 v[88:89], v209 offset:60992
	ds_read_b64_tr_b16 v[96:97], v209 offset:61024
	ds_read_b64_tr_b16 v[90:91], v209 offset:65344
	ds_read_b64_tr_b16 v[98:99], v209 offset:65376
	v_mfma_f32_16x16x32_bf16 v[148:151], v[104:107], v[52:55], v[148:151]
	v_mfma_f32_16x16x32_bf16 v[40:43], v[104:107], v[116:119], v[40:43]
	v_mfma_f32_16x16x32_bf16 v[152:155], v[112:115], v[52:55], v[152:155]
	v_mfma_f32_16x16x32_bf16 v[48:51], v[112:115], v[116:119], v[48:51]
	s_waitcnt lgkmcnt(8)
	ds_read_b64_tr_b16 v[104:105], v209 offset:61056
	ds_read_b64_tr_b16 v[112:113], v209 offset:61088
	ds_read_b64_tr_b16 v[106:107], v209 offset:65408
	ds_read_b64_tr_b16 v[114:115], v209 offset:65440
	v_mfma_f32_16x16x32_bf16 v[156:159], v[120:123], v[52:55], v[156:159]
	v_mfma_f32_16x16x32_bf16 v[56:59], v[120:123], v[116:119], v[56:59]
	v_mfma_f32_16x16x32_bf16 v[160:163], v[128:131], v[52:55], v[160:163]
	v_mfma_f32_16x16x32_bf16 v[64:67], v[128:131], v[116:119], v[64:67]
	s_waitcnt lgkmcnt(8)
	ds_read_b64_tr_b16 v[120:121], v209 offset:61120
	ds_read_b64_tr_b16 v[128:129], v209 offset:61152
	ds_read_b64_tr_b16 v[122:123], v209 offset:65472
	ds_read_b64_tr_b16 v[130:131], v209 offset:65504
	v_mfma_f32_16x16x32_bf16 v[132:135], v[72:75], v[60:63], v[132:135]
	v_mfma_f32_16x16x32_bf16 v[8:11], v[72:75], v[124:127], v[8:11]
	v_mfma_f32_16x16x32_bf16 v[136:139], v[80:83], v[60:63], v[136:139]
	v_mfma_f32_16x16x32_bf16 v[16:19], v[80:83], v[124:127], v[16:19]
	s_waitcnt lgkmcnt(8)
	v_mfma_f32_16x16x32_bf16 v[140:143], v[88:91], v[60:63], v[140:143]
	v_mfma_f32_16x16x32_bf16 v[24:27], v[88:91], v[124:127], v[24:27]
	v_mfma_f32_16x16x32_bf16 v[144:147], v[96:99], v[60:63], v[144:147]
	v_mfma_f32_16x16x32_bf16 v[32:35], v[96:99], v[124:127], v[32:35]
	s_waitcnt lgkmcnt(4)
	v_mfma_f32_16x16x32_bf16 v[148:151], v[104:107], v[60:63], v[148:151]
	v_mfma_f32_16x16x32_bf16 v[40:43], v[104:107], v[124:127], v[40:43]
	v_mfma_f32_16x16x32_bf16 v[152:155], v[112:115], v[60:63], v[152:155]
	v_mfma_f32_16x16x32_bf16 v[48:51], v[112:115], v[124:127], v[48:51]
	s_waitcnt lgkmcnt(0)
	v_mfma_f32_16x16x32_bf16 v[156:159], v[120:123], v[60:63], v[156:159]
	v_mfma_f32_16x16x32_bf16 v[56:59], v[120:123], v[124:127], v[56:59]
	v_mfma_f32_16x16x32_bf16 v[160:163], v[128:131], v[60:63], v[160:163]
	v_mfma_f32_16x16x32_bf16 v[64:67], v[128:131], v[124:127], v[64:67]
	s_nop 7
	s_nop 7
	v_mul_f32_e32 v230, v244, v132
	v_mul_f32_e32 v231, v244, v133
	v_mul_f32_e32 v232, v244, v134
	v_mul_f32_e32 v233, v244, v135
	v_cvt_pk_bf16_f32 v230, v230, v231
	v_cvt_pk_bf16_f32 v231, v232, v233
	global_store_dwordx2 v248, v[230:231], s[92:93] offset:0
	v_mul_f32_e32 v234, v244, v136
	v_mul_f32_e32 v235, v244, v137
	v_mul_f32_e32 v236, v244, v138
	v_mul_f32_e32 v237, v244, v139
	v_cvt_pk_bf16_f32 v234, v234, v235
	v_cvt_pk_bf16_f32 v235, v236, v237
	global_store_dwordx2 v248, v[234:235], s[92:93] offset:32
	v_mul_f32_e32 v230, v244, v140
	v_mul_f32_e32 v231, v244, v141
	v_mul_f32_e32 v232, v244, v142
	v_mul_f32_e32 v233, v244, v143
	v_cvt_pk_bf16_f32 v230, v230, v231
	v_cvt_pk_bf16_f32 v231, v232, v233
	global_store_dwordx2 v248, v[230:231], s[92:93] offset:64
	v_mul_f32_e32 v234, v244, v144
	v_mul_f32_e32 v235, v244, v145
	v_mul_f32_e32 v236, v244, v146
	v_mul_f32_e32 v237, v244, v147
	v_cvt_pk_bf16_f32 v234, v234, v235
	v_cvt_pk_bf16_f32 v235, v236, v237
	global_store_dwordx2 v248, v[234:235], s[92:93] offset:96
	v_mul_f32_e32 v230, v244, v148
	v_mul_f32_e32 v231, v244, v149
	v_mul_f32_e32 v232, v244, v150
	v_mul_f32_e32 v233, v244, v151
	v_cvt_pk_bf16_f32 v230, v230, v231
	v_cvt_pk_bf16_f32 v231, v232, v233
	global_store_dwordx2 v248, v[230:231], s[92:93] offset:128
; #define LAS __attribute__((address_space(3)))
; __device__ __forceinline__ unsigned cvt_pk_bf16(float lo, float hi) { const f32x2v v = {lo, hi}; const b16x2v r = __builtin_convertvector(v, b16x2v); return __builtin_bit_cast(unsigned, r); }
; __device__ __forceinline__ f32x4 mfma16(bf16x8 a, bf16x8 b, f32x4 c) { return __builtin_amdgcn_mfma_f32_16x16x32_bf16(a, b, c, 0, 0, 0); }
; #define LDS_BARRIER() do { asm volatile("s_waitcnt lgkmcnt(0)" ::: "memory"); __builtin_amdgcn_s_barrier(); asm volatile("" ::: "memory"); } while (0)
; #define XLOAD(kvbase, c8) do { const bf16_t* _src = (kvbase) + (((c8) >= 4) ? 2048 : 0) + ((c8) & 3) * 128 + piece * 8; \
;         _Pragma("unroll") for (int _it = 0; _it < 8; ++_it) pre[_it] = *(const u32x4*)(_src + (size_t)(srow + 32 * _it) * 4096); } while (0)
; #define XSTORE(buf) do { _Pragma("unroll") for (int _it = 0; _it < 8; ++_it) *(LAS u32x4*)((buf) + (srow + 32 * _it) * KV_STRIDE + piece * 16) = pre[_it]; } while (0)
; __device__ void cross_items(const Params& p, LAS unsigned char* lds) {
;     ...
;             LAS unsigned char* buf = lds + (c & 1) * KV_BUF;
;             XSTORE(buf);
;             if (c < 3) XLOAD(kvb, 5 + c); else XLOAD(nkvb, 0);
;             LDS_BARRIER();
;             f32x4 ot[8];
; #pragma unroll
;             for (int c8 = 0; c8 < 8; ++c8) ot[c8] = (f32x4){0.f, 0.f, 0.f, 0.f};
;             const unsigned bb = lbase + (unsigned)((c & 1) * KV_BUF);
; #pragma unroll
;             for (int sx = 0; sx < 8; ++sx) {
;                 const unsigned aA = bb + (unsigned)((32 * sx + 4 * g + (idx >> 2)) * KV_STRIDE + 8 * (idx & 3));
;                 const unsigned aB = aA + 16u * KV_STRIDE;
;                 bf16x8 vf[4];
;                 tr_frag4(aA, aB, vf);
; #pragma unroll
;                 for (int c8 = 0; c8 < 4; ++c8) ot[c8] = mfma16(vf[c8], pf[sx], ot[c8]);
;                 tr_frag4(aA + 128, aB + 128, vf);
; #pragma unroll
;                 for (int c8 = 0; c8 < 4; ++c8) ot[4 + c8] = mfma16(vf[c8], pf[sx], ot[4 + c8]);
;             }
; #pragma unroll
;             for (int c8 = 0; c8 < 8; ++c8) { u32x2 wv; wv.x = cvt_pk_bf16(ot[c8][0] * inv, ot[c8][1] * inv); wv.y = cvt_pk_bf16(ot[c8][2] * inv, ot[c8][3] * inv);
;                 *(u32x2*)(oc + tok * DM + head * 512 + c * 128 + 16 * c8 + 4 * g) = wv; }
	v_mul_f32_e32 v234, v244, v152
	v_mul_f32_e32 v235, v244, v153
	v_mul_f32_e32 v236, v244, v154
	v_mul_f32_e32 v237, v244, v155
	v_cvt_pk_bf16_f32 v234, v234, v235
	v_cvt_pk_bf16_f32 v235, v236, v237
	global_store_dwordx2 v248, v[234:235], s[92:93] offset:160
	v_mul_f32_e32 v230, v244, v156
	v_mul_f32_e32 v231, v244, v157
	v_mul_f32_e32 v232, v244, v158
	v_mul_f32_e32 v233, v244, v159
	v_cvt_pk_bf16_f32 v230, v230, v231
	v_cvt_pk_bf16_f32 v231, v232, v233
	global_store_dwordx2 v248, v[230:231], s[92:93] offset:192
	v_mul_f32_e32 v234, v244, v160
	v_mul_f32_e32 v235, v244, v161
	v_mul_f32_e32 v236, v244, v162
	v_mul_f32_e32 v237, v244, v163
	v_cvt_pk_bf16_f32 v234, v234, v235
	v_cvt_pk_bf16_f32 v235, v236, v237
	global_store_dwordx2 v248, v[234:235], s[92:93] offset:224
	v_mul_f32_e32 v230, v245, v8
	v_mul_f32_e32 v231, v245, v9
	v_mul_f32_e32 v232, v245, v10
	v_mul_f32_e32 v233, v245, v11
	v_cvt_pk_bf16_f32 v230, v230, v231
	v_cvt_pk_bf16_f32 v231, v232, v233
	global_store_dwordx2 v249, v[230:231], s[92:93] offset:0
	v_mul_f32_e32 v234, v245, v16
	v_mul_f32_e32 v235, v245, v17
	v_mul_f32_e32 v236, v245, v18
	v_mul_f32_e32 v237, v245, v19
	v_cvt_pk_bf16_f32 v234, v234, v235
	v_cvt_pk_bf16_f32 v235, v236, v237
	global_store_dwordx2 v249, v[234:235], s[92:93] offset:32
	v_mul_f32_e32 v230, v245, v24
	v_mul_f32_e32 v231, v245, v25
	v_mul_f32_e32 v232, v245, v26
	v_mul_f32_e32 v233, v245, v27
	v_cvt_pk_bf16_f32 v230, v230, v231
	v_cvt_pk_bf16_f32 v231, v232, v233
	global_store_dwordx2 v249, v[230:231], s[92:93] offset:64
	v_mul_f32_e32 v234, v245, v32
	v_mul_f32_e32 v235, v245, v33
	v_mul_f32_e32 v236, v245, v34
	v_mul_f32_e32 v237, v245, v35
	v_cvt_pk_bf16_f32 v234, v234, v235
	v_cvt_pk_bf16_f32 v235, v236, v237
	global_store_dwordx2 v249, v[234:235], s[92:93] offset:96
	v_mul_f32_e32 v230, v245, v40
	v_mul_f32_e32 v231, v245, v41
	v_mul_f32_e32 v232, v245, v42
	v_mul_f32_e32 v233, v245, v43
	v_cvt_pk_bf16_f32 v230, v230, v231
	v_cvt_pk_bf16_f32 v231, v232, v233
	global_store_dwordx2 v249, v[230:231], s[92:93] offset:128
	v_mul_f32_e32 v234, v245, v48
	v_mul_f32_e32 v235, v245, v49
	v_mul_f32_e32 v236, v245, v50
	v_mul_f32_e32 v237, v245, v51
	v_cvt_pk_bf16_f32 v234, v234, v235
	v_cvt_pk_bf16_f32 v235, v236, v237
	global_store_dwordx2 v249, v[234:235], s[92:93] offset:160
	v_mul_f32_e32 v230, v245, v56
	v_mul_f32_e32 v231, v245, v57
	v_mul_f32_e32 v232, v245, v58
	v_mul_f32_e32 v233, v245, v59
	v_cvt_pk_bf16_f32 v230, v230, v231
	v_cvt_pk_bf16_f32 v231, v232, v233
	global_store_dwordx2 v249, v[230:231], s[92:93] offset:192
	v_mul_f32_e32 v234, v245, v64
	v_mul_f32_e32 v235, v245, v65
	v_mul_f32_e32 v236, v245, v66
	v_mul_f32_e32 v237, v245, v67
	v_cvt_pk_bf16_f32 v234, v234, v235
	v_cvt_pk_bf16_f32 v235, v236, v237
	global_store_dwordx2 v249, v[234:235], s[92:93] offset:224
	s_waitcnt vmcnt(23)
	ds_write_b128 v1, v[164:167]
	s_waitcnt vmcnt(22)
	ds_write_b128 v1, v[168:171] offset:8704
	s_waitcnt vmcnt(21)
	ds_write_b128 v1, v[172:175] offset:17408
	s_waitcnt vmcnt(20)
	ds_write_b128 v1, v[176:179] offset:26112
	s_waitcnt vmcnt(19)
	ds_write_b128 v1, v[180:183] offset:34816
	s_waitcnt vmcnt(18)
	ds_write_b128 v1, v[184:187] offset:43520
	s_waitcnt vmcnt(17)
	ds_write_b128 v1, v[188:191] offset:52224
	s_waitcnt vmcnt(16)
	ds_write_b128 v1, v[192:195] offset:60928
	global_load_dwordx4 v[164:167], v242, s[6:7] offset:512
	v_add_u32_e32 v243, 0x40000, v242
	global_load_dwordx4 v[168:171], v243, s[6:7] offset:512
	v_add_u32_e32 v243, 0x80000, v242
	global_load_dwordx4 v[172:175], v243, s[6:7] offset:512
	v_add_u32_e32 v243, 0xc0000, v242
	global_load_dwordx4 v[176:179], v243, s[6:7] offset:512
	v_add_u32_e32 v243, 0x100000, v242
	global_load_dwordx4 v[180:183], v243, s[6:7] offset:512
	v_add_u32_e32 v243, 0x140000, v242
	global_load_dwordx4 v[184:187], v243, s[6:7] offset:512
	v_add_u32_e32 v243, 0x180000, v242
	global_load_dwordx4 v[188:191], v243, s[6:7] offset:512
	v_add_u32_e32 v243, 0x1c0000, v242
	global_load_dwordx4 v[192:195], v243, s[6:7] offset:512
	s_waitcnt lgkmcnt(0)
	s_barrier
	ds_read_b64_tr_b16 v[72:73], v210
	ds_read_b64_tr_b16 v[80:81], v210 offset:32
	ds_read_b64_tr_b16 v[74:75], v210 offset:4352
	ds_read_b64_tr_b16 v[82:83], v210 offset:4384
	ds_read_b64_tr_b16 v[88:89], v210 offset:64
	ds_read_b64_tr_b16 v[96:97], v210 offset:96
	ds_read_b64_tr_b16 v[90:91], v210 offset:4416
	ds_read_b64_tr_b16 v[98:99], v210 offset:4448
	ds_read_b64_tr_b16 v[104:105], v210 offset:128
	ds_read_b64_tr_b16 v[112:113], v210 offset:160
	ds_read_b64_tr_b16 v[106:107], v210 offset:4480
	ds_read_b64_tr_b16 v[114:115], v210 offset:4512
	s_waitcnt lgkmcnt(8)
	ds_read_b64_tr_b16 v[120:121], v210 offset:192
	ds_read_b64_tr_b16 v[128:129], v210 offset:224
	ds_read_b64_tr_b16 v[122:123], v210 offset:4544
	ds_read_b64_tr_b16 v[130:131], v210 offset:4576
	v_mfma_f32_16x16x32_bf16 v[132:135], v[72:75], v[4:7], 0
	v_mfma_f32_16x16x32_bf16 v[8:11], v[72:75], v[68:71], 0
	v_mfma_f32_16x16x32_bf16 v[136:139], v[80:83], v[4:7], 0
	v_mfma_f32_16x16x32_bf16 v[16:19], v[80:83], v[68:71], 0
	s_waitcnt lgkmcnt(8)
	ds_read_b64_tr_b16 v[72:73], v210 offset:8704
	ds_read_b64_tr_b16 v[80:81], v210 offset:8736
	ds_read_b64_tr_b16 v[74:75], v210 offset:13056
	ds_read_b64_tr_b16 v[82:83], v210 offset:13088
	v_mfma_f32_16x16x32_bf16 v[140:143], v[88:91], v[4:7], 0
	v_mfma_f32_16x16x32_bf16 v[24:27], v[88:91], v[68:71], 0
	v_mfma_f32_16x16x32_bf16 v[144:147], v[96:99], v[4:7], 0
	v_mfma_f32_16x16x32_bf16 v[32:35], v[96:99], v[68:71], 0
	s_waitcnt lgkmcnt(8)
; __device__ __forceinline__ f32x4 mfma16(bf16x8 a, bf16x8 b, f32x4 c) { return __builtin_amdgcn_mfma_f32_16x16x32_bf16(a, b, c, 0, 0, 0); }
; __device__ void cross_items(const Params& p, LAS unsigned char* lds) {
;     ...
; #pragma unroll
;             for (int sx = 0; sx < 8; ++sx) {
;                 const unsigned aA = bb + (unsigned)((32 * sx + 4 * g + (idx >> 2)) * KV_STRIDE + 8 * (idx & 3));
;                 const unsigned aB = aA + 16u * KV_STRIDE;
;                 bf16x8 vf[4];
;                 tr_frag4(aA, aB, vf);
; #pragma unroll
;                 for (int c8 = 0; c8 < 4; ++c8) ot[c8] = mfma16(vf[c8], pf[sx], ot[c8]);
;                 tr_frag4(aA + 128, aB + 128, vf);
; #pragma unroll
;                 for (int c8 = 0; c8 < 4; ++c8) ot[4 + c8] = mfma16(vf[c8], pf[sx], ot[4 + c8]);
	ds_read_b64_tr_b16 v[88:89], v210 offset:8768
	ds_read_b64_tr_b16 v[96:97], v210 offset:8800
	ds_read_b64_tr_b16 v[90:91], v210 offset:13120
	ds_read_b64_tr_b16 v[98:99], v210 offset:13152
	v_mfma_f32_16x16x32_bf16 v[148:151], v[104:107], v[4:7], 0
	v_mfma_f32_16x16x32_bf16 v[40:43], v[104:107], v[68:71], 0
	v_mfma_f32_16x16x32_bf16 v[152:155], v[112:115], v[4:7], 0
	v_mfma_f32_16x16x32_bf16 v[48:51], v[112:115], v[68:71], 0
	s_waitcnt lgkmcnt(8)
	ds_read_b64_tr_b16 v[104:105], v210 offset:8832
	ds_read_b64_tr_b16 v[112:113], v210 offset:8864
	ds_read_b64_tr_b16 v[106:107], v210 offset:13184
	ds_read_b64_tr_b16 v[114:115], v210 offset:13216
	v_mfma_f32_16x16x32_bf16 v[156:159], v[120:123], v[4:7], 0
	v_mfma_f32_16x16x32_bf16 v[56:59], v[120:123], v[68:71], 0
	v_mfma_f32_16x16x32_bf16 v[160:163], v[128:131], v[4:7], 0
	v_mfma_f32_16x16x32_bf16 v[64:67], v[128:131], v[68:71], 0
	s_waitcnt lgkmcnt(8)
	ds_read_b64_tr_b16 v[120:121], v210 offset:8896
	ds_read_b64_tr_b16 v[128:129], v210 offset:8928
	ds_read_b64_tr_b16 v[122:123], v210 offset:13248
	ds_read_b64_tr_b16 v[130:131], v210 offset:13280
	v_mfma_f32_16x16x32_bf16 v[132:135], v[72:75], v[12:15], v[132:135]
	v_mfma_f32_16x16x32_bf16 v[8:11], v[72:75], v[76:79], v[8:11]
	v_mfma_f32_16x16x32_bf16 v[136:139], v[80:83], v[12:15], v[136:139]
	v_mfma_f32_16x16x32_bf16 v[16:19], v[80:83], v[76:79], v[16:19]
	s_waitcnt lgkmcnt(8)
	ds_read_b64_tr_b16 v[72:73], v210 offset:17408
	ds_read_b64_tr_b16 v[80:81], v210 offset:17440
	ds_read_b64_tr_b16 v[74:75], v210 offset:21760
	ds_read_b64_tr_b16 v[82:83], v210 offset:21792
	v_mfma_f32_16x16x32_bf16 v[140:143], v[88:91], v[12:15], v[140:143]
	v_mfma_f32_16x16x32_bf16 v[24:27], v[88:91], v[76:79], v[24:27]
	v_mfma_f32_16x16x32_bf16 v[144:147], v[96:99], v[12:15], v[144:147]
	v_mfma_f32_16x16x32_bf16 v[32:35], v[96:99], v[76:79], v[32:35]
	s_waitcnt lgkmcnt(8)
	ds_read_b64_tr_b16 v[88:89], v210 offset:17472
	ds_read_b64_tr_b16 v[96:97], v210 offset:17504
	ds_read_b64_tr_b16 v[90:91], v210 offset:21824
	ds_read_b64_tr_b16 v[98:99], v210 offset:21856
	v_mfma_f32_16x16x32_bf16 v[148:151], v[104:107], v[12:15], v[148:151]
	v_mfma_f32_16x16x32_bf16 v[40:43], v[104:107], v[76:79], v[40:43]
	v_mfma_f32_16x16x32_bf16 v[152:155], v[112:115], v[12:15], v[152:155]
	v_mfma_f32_16x16x32_bf16 v[48:51], v[112:115], v[76:79], v[48:51]
	s_waitcnt lgkmcnt(8)
	ds_read_b64_tr_b16 v[104:105], v210 offset:17536
	ds_read_b64_tr_b16 v[112:113], v210 offset:17568
	ds_read_b64_tr_b16 v[106:107], v210 offset:21888
	ds_read_b64_tr_b16 v[114:115], v210 offset:21920
	v_mfma_f32_16x16x32_bf16 v[156:159], v[120:123], v[12:15], v[156:159]
	v_mfma_f32_16x16x32_bf16 v[56:59], v[120:123], v[76:79], v[56:59]
	v_mfma_f32_16x16x32_bf16 v[160:163], v[128:131], v[12:15], v[160:163]
	v_mfma_f32_16x16x32_bf16 v[64:67], v[128:131], v[76:79], v[64:67]
	s_waitcnt lgkmcnt(8)
	ds_read_b64_tr_b16 v[120:121], v210 offset:17600
	ds_read_b64_tr_b16 v[128:129], v210 offset:17632
	ds_read_b64_tr_b16 v[122:123], v210 offset:21952
	ds_read_b64_tr_b16 v[130:131], v210 offset:21984
	v_mfma_f32_16x16x32_bf16 v[132:135], v[72:75], v[20:23], v[132:135]
	v_mfma_f32_16x16x32_bf16 v[8:11], v[72:75], v[84:87], v[8:11]
	v_mfma_f32_16x16x32_bf16 v[136:139], v[80:83], v[20:23], v[136:139]
	v_mfma_f32_16x16x32_bf16 v[16:19], v[80:83], v[84:87], v[16:19]
	s_waitcnt lgkmcnt(8)
	ds_read_b64_tr_b16 v[72:73], v210 offset:26112
	ds_read_b64_tr_b16 v[80:81], v210 offset:26144
	ds_read_b64_tr_b16 v[74:75], v210 offset:30464
	ds_read_b64_tr_b16 v[82:83], v210 offset:30496
	v_mfma_f32_16x16x32_bf16 v[140:143], v[88:91], v[20:23], v[140:143]
	v_mfma_f32_16x16x32_bf16 v[24:27], v[88:91], v[84:87], v[24:27]
	v_mfma_f32_16x16x32_bf16 v[144:147], v[96:99], v[20:23], v[144:147]
	v_mfma_f32_16x16x32_bf16 v[32:35], v[96:99], v[84:87], v[32:35]
	s_waitcnt lgkmcnt(8)
	ds_read_b64_tr_b16 v[88:89], v210 offset:26176
	ds_read_b64_tr_b16 v[96:97], v210 offset:26208
	ds_read_b64_tr_b16 v[90:91], v210 offset:30528
	ds_read_b64_tr_b16 v[98:99], v210 offset:30560
	v_mfma_f32_16x16x32_bf16 v[148:151], v[104:107], v[20:23], v[148:151]
	v_mfma_f32_16x16x32_bf16 v[40:43], v[104:107], v[84:87], v[40:43]
	v_mfma_f32_16x16x32_bf16 v[152:155], v[112:115], v[20:23], v[152:155]
	v_mfma_f32_16x16x32_bf16 v[48:51], v[112:115], v[84:87], v[48:51]
	s_waitcnt lgkmcnt(8)
	ds_read_b64_tr_b16 v[104:105], v210 offset:26240
	ds_read_b64_tr_b16 v[112:113], v210 offset:26272
	ds_read_b64_tr_b16 v[106:107], v210 offset:30592
	ds_read_b64_tr_b16 v[114:115], v210 offset:30624
	v_mfma_f32_16x16x32_bf16 v[156:159], v[120:123], v[20:23], v[156:159]
	v_mfma_f32_16x16x32_bf16 v[56:59], v[120:123], v[84:87], v[56:59]
	v_mfma_f32_16x16x32_bf16 v[160:163], v[128:131], v[20:23], v[160:163]
	v_mfma_f32_16x16x32_bf16 v[64:67], v[128:131], v[84:87], v[64:67]
	s_waitcnt lgkmcnt(8)
	ds_read_b64_tr_b16 v[120:121], v210 offset:26304
	ds_read_b64_tr_b16 v[128:129], v210 offset:26336
	ds_read_b64_tr_b16 v[122:123], v210 offset:30656
	ds_read_b64_tr_b16 v[130:131], v210 offset:30688
	v_mfma_f32_16x16x32_bf16 v[132:135], v[72:75], v[28:31], v[132:135]
	v_mfma_f32_16x16x32_bf16 v[8:11], v[72:75], v[92:95], v[8:11]
	v_mfma_f32_16x16x32_bf16 v[136:139], v[80:83], v[28:31], v[136:139]
	v_mfma_f32_16x16x32_bf16 v[16:19], v[80:83], v[92:95], v[16:19]
	s_waitcnt lgkmcnt(8)
	ds_read_b64_tr_b16 v[72:73], v210 offset:34816
	ds_read_b64_tr_b16 v[80:81], v210 offset:34848
	ds_read_b64_tr_b16 v[74:75], v210 offset:39168
	ds_read_b64_tr_b16 v[82:83], v210 offset:39200
	v_mfma_f32_16x16x32_bf16 v[140:143], v[88:91], v[28:31], v[140:143]
	v_mfma_f32_16x16x32_bf16 v[24:27], v[88:91], v[92:95], v[24:27]
	v_mfma_f32_16x16x32_bf16 v[144:147], v[96:99], v[28:31], v[144:147]
	v_mfma_f32_16x16x32_bf16 v[32:35], v[96:99], v[92:95], v[32:35]
	s_waitcnt lgkmcnt(8)
; __device__ __forceinline__ f32x4 mfma16(bf16x8 a, bf16x8 b, f32x4 c) { return __builtin_amdgcn_mfma_f32_16x16x32_bf16(a, b, c, 0, 0, 0); }
; __device__ void cross_items(const Params& p, LAS unsigned char* lds) {
;     ...
; #pragma unroll
;             for (int sx = 0; sx < 8; ++sx) {
;                 const unsigned aA = bb + (unsigned)((32 * sx + 4 * g + (idx >> 2)) * KV_STRIDE + 8 * (idx & 3));
;                 const unsigned aB = aA + 16u * KV_STRIDE;
;                 bf16x8 vf[4];
;                 tr_frag4(aA, aB, vf);
; #pragma unroll
;                 for (int c8 = 0; c8 < 4; ++c8) ot[c8] = mfma16(vf[c8], pf[sx], ot[c8]);
;                 tr_frag4(aA + 128, aB + 128, vf);
; #pragma unroll
;                 for (int c8 = 0; c8 < 4; ++c8) ot[4 + c8] = mfma16(vf[c8], pf[sx], ot[4 + c8]);
	ds_read_b64_tr_b16 v[88:89], v210 offset:34880
	ds_read_b64_tr_b16 v[96:97], v210 offset:34912
	ds_read_b64_tr_b16 v[90:91], v210 offset:39232
	ds_read_b64_tr_b16 v[98:99], v210 offset:39264
	v_mfma_f32_16x16x32_bf16 v[148:151], v[104:107], v[28:31], v[148:151]
	v_mfma_f32_16x16x32_bf16 v[40:43], v[104:107], v[92:95], v[40:43]
	v_mfma_f32_16x16x32_bf16 v[152:155], v[112:115], v[28:31], v[152:155]
	v_mfma_f32_16x16x32_bf16 v[48:51], v[112:115], v[92:95], v[48:51]
	s_waitcnt lgkmcnt(8)
	ds_read_b64_tr_b16 v[104:105], v210 offset:34944
	ds_read_b64_tr_b16 v[112:113], v210 offset:34976
	ds_read_b64_tr_b16 v[106:107], v210 offset:39296
	ds_read_b64_tr_b16 v[114:115], v210 offset:39328
	v_mfma_f32_16x16x32_bf16 v[156:159], v[120:123], v[28:31], v[156:159]
	v_mfma_f32_16x16x32_bf16 v[56:59], v[120:123], v[92:95], v[56:59]
	v_mfma_f32_16x16x32_bf16 v[160:163], v[128:131], v[28:31], v[160:163]
	v_mfma_f32_16x16x32_bf16 v[64:67], v[128:131], v[92:95], v[64:67]
	s_waitcnt lgkmcnt(8)
	ds_read_b64_tr_b16 v[120:121], v210 offset:35008
	ds_read_b64_tr_b16 v[128:129], v210 offset:35040
	ds_read_b64_tr_b16 v[122:123], v210 offset:39360
	ds_read_b64_tr_b16 v[130:131], v210 offset:39392
	v_mfma_f32_16x16x32_bf16 v[132:135], v[72:75], v[36:39], v[132:135]
	v_mfma_f32_16x16x32_bf16 v[8:11], v[72:75], v[100:103], v[8:11]
	v_mfma_f32_16x16x32_bf16 v[136:139], v[80:83], v[36:39], v[136:139]
	v_mfma_f32_16x16x32_bf16 v[16:19], v[80:83], v[100:103], v[16:19]
	s_waitcnt lgkmcnt(8)
	ds_read_b64_tr_b16 v[72:73], v210 offset:43520
	ds_read_b64_tr_b16 v[80:81], v210 offset:43552
	ds_read_b64_tr_b16 v[74:75], v210 offset:47872
	ds_read_b64_tr_b16 v[82:83], v210 offset:47904
	v_mfma_f32_16x16x32_bf16 v[140:143], v[88:91], v[36:39], v[140:143]
	v_mfma_f32_16x16x32_bf16 v[24:27], v[88:91], v[100:103], v[24:27]
	v_mfma_f32_16x16x32_bf16 v[144:147], v[96:99], v[36:39], v[144:147]
	v_mfma_f32_16x16x32_bf16 v[32:35], v[96:99], v[100:103], v[32:35]
	s_waitcnt lgkmcnt(8)
	ds_read_b64_tr_b16 v[88:89], v210 offset:43584
	ds_read_b64_tr_b16 v[96:97], v210 offset:43616
	ds_read_b64_tr_b16 v[90:91], v210 offset:47936
	ds_read_b64_tr_b16 v[98:99], v210 offset:47968
	v_mfma_f32_16x16x32_bf16 v[148:151], v[104:107], v[36:39], v[148:151]
	v_mfma_f32_16x16x32_bf16 v[40:43], v[104:107], v[100:103], v[40:43]
	v_mfma_f32_16x16x32_bf16 v[152:155], v[112:115], v[36:39], v[152:155]
	v_mfma_f32_16x16x32_bf16 v[48:51], v[112:115], v[100:103], v[48:51]
	s_waitcnt lgkmcnt(8)
	ds_read_b64_tr_b16 v[104:105], v210 offset:43648
	ds_read_b64_tr_b16 v[112:113], v210 offset:43680
	ds_read_b64_tr_b16 v[106:107], v210 offset:48000
	ds_read_b64_tr_b16 v[114:115], v210 offset:48032
	v_mfma_f32_16x16x32_bf16 v[156:159], v[120:123], v[36:39], v[156:159]
	v_mfma_f32_16x16x32_bf16 v[56:59], v[120:123], v[100:103], v[56:59]
	v_mfma_f32_16x16x32_bf16 v[160:163], v[128:131], v[36:39], v[160:163]
	v_mfma_f32_16x16x32_bf16 v[64:67], v[128:131], v[100:103], v[64:67]
	s_waitcnt lgkmcnt(8)
	ds_read_b64_tr_b16 v[120:121], v210 offset:43712
	ds_read_b64_tr_b16 v[128:129], v210 offset:43744
	ds_read_b64_tr_b16 v[122:123], v210 offset:48064
	ds_read_b64_tr_b16 v[130:131], v210 offset:48096
	v_mfma_f32_16x16x32_bf16 v[132:135], v[72:75], v[44:47], v[132:135]
	v_mfma_f32_16x16x32_bf16 v[8:11], v[72:75], v[108:111], v[8:11]
	v_mfma_f32_16x16x32_bf16 v[136:139], v[80:83], v[44:47], v[136:139]
	v_mfma_f32_16x16x32_bf16 v[16:19], v[80:83], v[108:111], v[16:19]
	s_waitcnt lgkmcnt(8)
	ds_read_b64_tr_b16 v[72:73], v210 offset:52224
	ds_read_b64_tr_b16 v[80:81], v210 offset:52256
	ds_read_b64_tr_b16 v[74:75], v210 offset:56576
	ds_read_b64_tr_b16 v[82:83], v210 offset:56608
	v_mfma_f32_16x16x32_bf16 v[140:143], v[88:91], v[44:47], v[140:143]
	v_mfma_f32_16x16x32_bf16 v[24:27], v[88:91], v[108:111], v[24:27]
	v_mfma_f32_16x16x32_bf16 v[144:147], v[96:99], v[44:47], v[144:147]
	v_mfma_f32_16x16x32_bf16 v[32:35], v[96:99], v[108:111], v[32:35]
	s_waitcnt lgkmcnt(8)
	ds_read_b64_tr_b16 v[88:89], v210 offset:52288
	ds_read_b64_tr_b16 v[96:97], v210 offset:52320
	ds_read_b64_tr_b16 v[90:91], v210 offset:56640
	ds_read_b64_tr_b16 v[98:99], v210 offset:56672
	v_mfma_f32_16x16x32_bf16 v[148:151], v[104:107], v[44:47], v[148:151]
	v_mfma_f32_16x16x32_bf16 v[40:43], v[104:107], v[108:111], v[40:43]
	v_mfma_f32_16x16x32_bf16 v[152:155], v[112:115], v[44:47], v[152:155]
	v_mfma_f32_16x16x32_bf16 v[48:51], v[112:115], v[108:111], v[48:51]
	s_waitcnt lgkmcnt(8)
	ds_read_b64_tr_b16 v[104:105], v210 offset:52352
	ds_read_b64_tr_b16 v[112:113], v210 offset:52384
	ds_read_b64_tr_b16 v[106:107], v210 offset:56704
	ds_read_b64_tr_b16 v[114:115], v210 offset:56736
	v_mfma_f32_16x16x32_bf16 v[156:159], v[120:123], v[44:47], v[156:159]
	v_mfma_f32_16x16x32_bf16 v[56:59], v[120:123], v[108:111], v[56:59]
	v_mfma_f32_16x16x32_bf16 v[160:163], v[128:131], v[44:47], v[160:163]
	v_mfma_f32_16x16x32_bf16 v[64:67], v[128:131], v[108:111], v[64:67]
	s_waitcnt lgkmcnt(8)
	ds_read_b64_tr_b16 v[120:121], v210 offset:52416
	ds_read_b64_tr_b16 v[128:129], v210 offset:52448
	ds_read_b64_tr_b16 v[122:123], v210 offset:56768
	ds_read_b64_tr_b16 v[130:131], v210 offset:56800
	v_mfma_f32_16x16x32_bf16 v[132:135], v[72:75], v[52:55], v[132:135]
	v_mfma_f32_16x16x32_bf16 v[8:11], v[72:75], v[116:119], v[8:11]
	v_mfma_f32_16x16x32_bf16 v[136:139], v[80:83], v[52:55], v[136:139]
	v_mfma_f32_16x16x32_bf16 v[16:19], v[80:83], v[116:119], v[16:19]
	s_waitcnt lgkmcnt(8)
; __device__ __forceinline__ unsigned cvt_pk_bf16(float lo, float hi) { const f32x2v v = {lo, hi}; const b16x2v r = __builtin_convertvector(v, b16x2v); return __builtin_bit_cast(unsigned, r); }
; __device__ __forceinline__ f32x4 mfma16(bf16x8 a, bf16x8 b, f32x4 c) { return __builtin_amdgcn_mfma_f32_16x16x32_bf16(a, b, c, 0, 0, 0); }
; __device__ void cross_items(const Params& p, LAS unsigned char* lds) {
;     ...
; #pragma unroll
;             for (int sx = 0; sx < 8; ++sx) {
;                 const unsigned aA = bb + (unsigned)((32 * sx + 4 * g + (idx >> 2)) * KV_STRIDE + 8 * (idx & 3));
;                 const unsigned aB = aA + 16u * KV_STRIDE;
;                 bf16x8 vf[4];
;                 tr_frag4(aA, aB, vf);
; #pragma unroll
;                 for (int c8 = 0; c8 < 4; ++c8) ot[c8] = mfma16(vf[c8], pf[sx], ot[c8]);
;                 tr_frag4(aA + 128, aB + 128, vf);
; #pragma unroll
;                 for (int c8 = 0; c8 < 4; ++c8) ot[4 + c8] = mfma16(vf[c8], pf[sx], ot[4 + c8]);
;             }
; #pragma unroll
;             for (int c8 = 0; c8 < 8; ++c8) { u32x2 wv; wv.x = cvt_pk_bf16(ot[c8][0] * inv, ot[c8][1] * inv); wv.y = cvt_pk_bf16(ot[c8][2] * inv, ot[c8][3] * inv);
;                 *(u32x2*)(oc + tok * DM + head * 512 + c * 128 + 16 * c8 + 4 * g) = wv; }
	ds_read_b64_tr_b16 v[72:73], v210 offset:60928
	ds_read_b64_tr_b16 v[80:81], v210 offset:60960
	ds_read_b64_tr_b16 v[74:75], v210 offset:65280
	ds_read_b64_tr_b16 v[82:83], v210 offset:65312
	v_mfma_f32_16x16x32_bf16 v[140:143], v[88:91], v[52:55], v[140:143]
	v_mfma_f32_16x16x32_bf16 v[24:27], v[88:91], v[116:119], v[24:27]
	v_mfma_f32_16x16x32_bf16 v[144:147], v[96:99], v[52:55], v[144:147]
	v_mfma_f32_16x16x32_bf16 v[32:35], v[96:99], v[116:119], v[32:35]
	s_waitcnt lgkmcnt(8)
	ds_read_b64_tr_b16 v[88:89], v210 offset:60992
	ds_read_b64_tr_b16 v[96:97], v210 offset:61024
	ds_read_b64_tr_b16 v[90:91], v210 offset:65344
	ds_read_b64_tr_b16 v[98:99], v210 offset:65376
	v_mfma_f32_16x16x32_bf16 v[148:151], v[104:107], v[52:55], v[148:151]
	v_mfma_f32_16x16x32_bf16 v[40:43], v[104:107], v[116:119], v[40:43]
	v_mfma_f32_16x16x32_bf16 v[152:155], v[112:115], v[52:55], v[152:155]
	v_mfma_f32_16x16x32_bf16 v[48:51], v[112:115], v[116:119], v[48:51]
	s_waitcnt lgkmcnt(8)
	ds_read_b64_tr_b16 v[104:105], v210 offset:61056
	ds_read_b64_tr_b16 v[112:113], v210 offset:61088
	ds_read_b64_tr_b16 v[106:107], v210 offset:65408
	ds_read_b64_tr_b16 v[114:115], v210 offset:65440
	v_mfma_f32_16x16x32_bf16 v[156:159], v[120:123], v[52:55], v[156:159]
	v_mfma_f32_16x16x32_bf16 v[56:59], v[120:123], v[116:119], v[56:59]
	v_mfma_f32_16x16x32_bf16 v[160:163], v[128:131], v[52:55], v[160:163]
	v_mfma_f32_16x16x32_bf16 v[64:67], v[128:131], v[116:119], v[64:67]
	s_waitcnt lgkmcnt(8)
	ds_read_b64_tr_b16 v[120:121], v210 offset:61120
	ds_read_b64_tr_b16 v[128:129], v210 offset:61152
	ds_read_b64_tr_b16 v[122:123], v210 offset:65472
	ds_read_b64_tr_b16 v[130:131], v210 offset:65504
	v_mfma_f32_16x16x32_bf16 v[132:135], v[72:75], v[60:63], v[132:135]
	v_mfma_f32_16x16x32_bf16 v[8:11], v[72:75], v[124:127], v[8:11]
	v_mfma_f32_16x16x32_bf16 v[136:139], v[80:83], v[60:63], v[136:139]
	v_mfma_f32_16x16x32_bf16 v[16:19], v[80:83], v[124:127], v[16:19]
	s_waitcnt lgkmcnt(8)
	v_mfma_f32_16x16x32_bf16 v[140:143], v[88:91], v[60:63], v[140:143]
	v_mfma_f32_16x16x32_bf16 v[24:27], v[88:91], v[124:127], v[24:27]
	v_mfma_f32_16x16x32_bf16 v[144:147], v[96:99], v[60:63], v[144:147]
	v_mfma_f32_16x16x32_bf16 v[32:35], v[96:99], v[124:127], v[32:35]
	s_waitcnt lgkmcnt(4)
	v_mfma_f32_16x16x32_bf16 v[148:151], v[104:107], v[60:63], v[148:151]
	v_mfma_f32_16x16x32_bf16 v[40:43], v[104:107], v[124:127], v[40:43]
	v_mfma_f32_16x16x32_bf16 v[152:155], v[112:115], v[60:63], v[152:155]
	v_mfma_f32_16x16x32_bf16 v[48:51], v[112:115], v[124:127], v[48:51]
	s_waitcnt lgkmcnt(0)
	v_mfma_f32_16x16x32_bf16 v[156:159], v[120:123], v[60:63], v[156:159]
	v_mfma_f32_16x16x32_bf16 v[56:59], v[120:123], v[124:127], v[56:59]
	v_mfma_f32_16x16x32_bf16 v[160:163], v[128:131], v[60:63], v[160:163]
	v_mfma_f32_16x16x32_bf16 v[64:67], v[128:131], v[124:127], v[64:67]
	s_nop 7
	s_nop 7
	v_mul_f32_e32 v230, v244, v132
	v_mul_f32_e32 v231, v244, v133
	v_mul_f32_e32 v232, v244, v134
	v_mul_f32_e32 v233, v244, v135
	v_cvt_pk_bf16_f32 v230, v230, v231
	v_cvt_pk_bf16_f32 v231, v232, v233
	global_store_dwordx2 v248, v[230:231], s[92:93] offset:256
	v_mul_f32_e32 v234, v244, v136
	v_mul_f32_e32 v235, v244, v137
	v_mul_f32_e32 v236, v244, v138
	v_mul_f32_e32 v237, v244, v139
	v_cvt_pk_bf16_f32 v234, v234, v235
	v_cvt_pk_bf16_f32 v235, v236, v237
	global_store_dwordx2 v248, v[234:235], s[92:93] offset:288
	v_mul_f32_e32 v230, v244, v140
	v_mul_f32_e32 v231, v244, v141
	v_mul_f32_e32 v232, v244, v142
	v_mul_f32_e32 v233, v244, v143
	v_cvt_pk_bf16_f32 v230, v230, v231
	v_cvt_pk_bf16_f32 v231, v232, v233
	global_store_dwordx2 v248, v[230:231], s[92:93] offset:320
	v_mul_f32_e32 v234, v244, v144
	v_mul_f32_e32 v235, v244, v145
	v_mul_f32_e32 v236, v244, v146
	v_mul_f32_e32 v237, v244, v147
	v_cvt_pk_bf16_f32 v234, v234, v235
	v_cvt_pk_bf16_f32 v235, v236, v237
	global_store_dwordx2 v248, v[234:235], s[92:93] offset:352
	v_mul_f32_e32 v230, v244, v148
	v_mul_f32_e32 v231, v244, v149
	v_mul_f32_e32 v232, v244, v150
	v_mul_f32_e32 v233, v244, v151
	v_cvt_pk_bf16_f32 v230, v230, v231
	v_cvt_pk_bf16_f32 v231, v232, v233
	global_store_dwordx2 v248, v[230:231], s[92:93] offset:384
	v_mul_f32_e32 v234, v244, v152
	v_mul_f32_e32 v235, v244, v153
	v_mul_f32_e32 v236, v244, v154
	v_mul_f32_e32 v237, v244, v155
	v_cvt_pk_bf16_f32 v234, v234, v235
	v_cvt_pk_bf16_f32 v235, v236, v237
	global_store_dwordx2 v248, v[234:235], s[92:93] offset:416
	v_mul_f32_e32 v230, v244, v156
	v_mul_f32_e32 v231, v244, v157
	v_mul_f32_e32 v232, v244, v158
	v_mul_f32_e32 v233, v244, v159
	v_cvt_pk_bf16_f32 v230, v230, v231
	v_cvt_pk_bf16_f32 v231, v232, v233
	global_store_dwordx2 v248, v[230:231], s[92:93] offset:448
	v_mul_f32_e32 v234, v244, v160
	v_mul_f32_e32 v235, v244, v161
	v_mul_f32_e32 v236, v244, v162
	v_mul_f32_e32 v237, v244, v163
	v_cvt_pk_bf16_f32 v234, v234, v235
	v_cvt_pk_bf16_f32 v235, v236, v237
	global_store_dwordx2 v248, v[234:235], s[92:93] offset:480
	v_mul_f32_e32 v230, v245, v8
	v_mul_f32_e32 v231, v245, v9
	v_mul_f32_e32 v232, v245, v10
	v_mul_f32_e32 v233, v245, v11
	v_cvt_pk_bf16_f32 v230, v230, v231
	v_cvt_pk_bf16_f32 v231, v232, v233
	global_store_dwordx2 v249, v[230:231], s[92:93] offset:256
	v_mul_f32_e32 v234, v245, v16
	v_mul_f32_e32 v235, v245, v17
	v_mul_f32_e32 v236, v245, v18
	v_mul_f32_e32 v237, v245, v19
	v_cvt_pk_bf16_f32 v234, v234, v235
	v_cvt_pk_bf16_f32 v235, v236, v237
	global_store_dwordx2 v249, v[234:235], s[92:93] offset:288
	v_mul_f32_e32 v230, v245, v24
	v_mul_f32_e32 v231, v245, v25
	v_mul_f32_e32 v232, v245, v26
	v_mul_f32_e32 v233, v245, v27
	v_cvt_pk_bf16_f32 v230, v230, v231
	v_cvt_pk_bf16_f32 v231, v232, v233
	global_store_dwordx2 v249, v[230:231], s[92:93] offset:320
	v_mul_f32_e32 v234, v245, v32
	v_mul_f32_e32 v235, v245, v33
	v_mul_f32_e32 v236, v245, v34
	v_mul_f32_e32 v237, v245, v35
	v_cvt_pk_bf16_f32 v234, v234, v235
	v_cvt_pk_bf16_f32 v235, v236, v237
	global_store_dwordx2 v249, v[234:235], s[92:93] offset:352
	v_mul_f32_e32 v230, v245, v40
	v_mul_f32_e32 v231, v245, v41
	v_mul_f32_e32 v232, v245, v42
	v_mul_f32_e32 v233, v245, v43
	v_cvt_pk_bf16_f32 v230, v230, v231
	v_cvt_pk_bf16_f32 v231, v232, v233
	global_store_dwordx2 v249, v[230:231], s[92:93] offset:384
	v_mul_f32_e32 v234, v245, v48
	v_mul_f32_e32 v235, v245, v49
	v_mul_f32_e32 v236, v245, v50
	v_mul_f32_e32 v237, v245, v51
	v_cvt_pk_bf16_f32 v234, v234, v235
	v_cvt_pk_bf16_f32 v235, v236, v237
	global_store_dwordx2 v249, v[234:235], s[92:93] offset:416
	v_mul_f32_e32 v230, v245, v56
	v_mul_f32_e32 v231, v245, v57
	v_mul_f32_e32 v232, v245, v58
	v_mul_f32_e32 v233, v245, v59
	v_cvt_pk_bf16_f32 v230, v230, v231
	v_cvt_pk_bf16_f32 v231, v232, v233
	global_store_dwordx2 v249, v[230:231], s[92:93] offset:448
	v_mul_f32_e32 v234, v245, v64
	v_mul_f32_e32 v235, v245, v65
	v_mul_f32_e32 v236, v245, v66
	v_mul_f32_e32 v237, v245, v67
	v_cvt_pk_bf16_f32 v234, v234, v235
	v_cvt_pk_bf16_f32 v235, v236, v237
	global_store_dwordx2 v249, v[234:235], s[92:93] offset:480
	s_waitcnt vmcnt(23)
; #define LAS __attribute__((address_space(3)))
; __device__ __forceinline__ f32x4 mfma16(bf16x8 a, bf16x8 b, f32x4 c) { return __builtin_amdgcn_mfma_f32_16x16x32_bf16(a, b, c, 0, 0, 0); }
; #define LDS_BARRIER() do { asm volatile("s_waitcnt lgkmcnt(0)" ::: "memory"); __builtin_amdgcn_s_barrier(); asm volatile("" ::: "memory"); } while (0)
; #define XLOAD(kvbase, c8) do { const bf16_t* _src = (kvbase) + (((c8) >= 4) ? 2048 : 0) + ((c8) & 3) * 128 + piece * 8; \
;         _Pragma("unroll") for (int _it = 0; _it < 8; ++_it) pre[_it] = *(const u32x4*)(_src + (size_t)(srow + 32 * _it) * 4096); } while (0)
; #define XSTORE(buf) do { _Pragma("unroll") for (int _it = 0; _it < 8; ++_it) *(LAS u32x4*)((buf) + (srow + 32 * _it) * KV_STRIDE + piece * 16) = pre[_it]; } while (0)
; __device__ void cross_items(const Params& p, LAS unsigned char* lds) {
;     ...
;             LAS unsigned char* buf = lds + (c & 1) * KV_BUF;
;             XSTORE(buf);
;             if (c < 3) XLOAD(kvb, 5 + c); else XLOAD(nkvb, 0);
;             LDS_BARRIER();
;             f32x4 ot[8];
; #pragma unroll
;             for (int c8 = 0; c8 < 8; ++c8) ot[c8] = (f32x4){0.f, 0.f, 0.f, 0.f};
;             const unsigned bb = lbase + (unsigned)((c & 1) * KV_BUF);
; #pragma unroll
;             for (int sx = 0; sx < 8; ++sx) {
;                 const unsigned aA = bb + (unsigned)((32 * sx + 4 * g + (idx >> 2)) * KV_STRIDE + 8 * (idx & 3));
;                 const unsigned aB = aA + 16u * KV_STRIDE;
;                 bf16x8 vf[4];
;                 tr_frag4(aA, aB, vf);
; #pragma unroll
;                 for (int c8 = 0; c8 < 4; ++c8) ot[c8] = mfma16(vf[c8], pf[sx], ot[c8]);
;                 tr_frag4(aA + 128, aB + 128, vf);
; #pragma unroll
;                 for (int c8 = 0; c8 < 4; ++c8) ot[4 + c8] = mfma16(vf[c8], pf[sx], ot[4 + c8]);
	ds_write_b128 v0, v[164:167]
	s_waitcnt vmcnt(22)
	ds_write_b128 v0, v[168:171] offset:8704
	s_waitcnt vmcnt(21)
	ds_write_b128 v0, v[172:175] offset:17408
	s_waitcnt vmcnt(20)
	ds_write_b128 v0, v[176:179] offset:26112
	s_waitcnt vmcnt(19)
	ds_write_b128 v0, v[180:183] offset:34816
	s_waitcnt vmcnt(18)
	ds_write_b128 v0, v[184:187] offset:43520
	s_waitcnt vmcnt(17)
	ds_write_b128 v0, v[188:191] offset:52224
	s_waitcnt vmcnt(16)
	ds_write_b128 v0, v[192:195] offset:60928
	global_load_dwordx4 v[164:167], v242, s[6:7] offset:768
	v_add_u32_e32 v243, 0x40000, v242
	global_load_dwordx4 v[168:171], v243, s[6:7] offset:768
	v_add_u32_e32 v243, 0x80000, v242
	global_load_dwordx4 v[172:175], v243, s[6:7] offset:768
	v_add_u32_e32 v243, 0xc0000, v242
	global_load_dwordx4 v[176:179], v243, s[6:7] offset:768
	v_add_u32_e32 v243, 0x100000, v242
	global_load_dwordx4 v[180:183], v243, s[6:7] offset:768
	v_add_u32_e32 v243, 0x140000, v242
	global_load_dwordx4 v[184:187], v243, s[6:7] offset:768
	v_add_u32_e32 v243, 0x180000, v242
	global_load_dwordx4 v[188:191], v243, s[6:7] offset:768
	v_add_u32_e32 v243, 0x1c0000, v242
	global_load_dwordx4 v[192:195], v243, s[6:7] offset:768
	s_waitcnt lgkmcnt(0)
	s_barrier
	ds_read_b64_tr_b16 v[72:73], v209
	ds_read_b64_tr_b16 v[80:81], v209 offset:32
	ds_read_b64_tr_b16 v[74:75], v209 offset:4352
	ds_read_b64_tr_b16 v[82:83], v209 offset:4384
	ds_read_b64_tr_b16 v[88:89], v209 offset:64
	ds_read_b64_tr_b16 v[96:97], v209 offset:96
	ds_read_b64_tr_b16 v[90:91], v209 offset:4416
	ds_read_b64_tr_b16 v[98:99], v209 offset:4448
	ds_read_b64_tr_b16 v[104:105], v209 offset:128
	ds_read_b64_tr_b16 v[112:113], v209 offset:160
	ds_read_b64_tr_b16 v[106:107], v209 offset:4480
	ds_read_b64_tr_b16 v[114:115], v209 offset:4512
	s_waitcnt lgkmcnt(8)
	ds_read_b64_tr_b16 v[120:121], v209 offset:192
	ds_read_b64_tr_b16 v[128:129], v209 offset:224
	ds_read_b64_tr_b16 v[122:123], v209 offset:4544
	ds_read_b64_tr_b16 v[130:131], v209 offset:4576
	v_mfma_f32_16x16x32_bf16 v[132:135], v[72:75], v[4:7], 0
	v_mfma_f32_16x16x32_bf16 v[8:11], v[72:75], v[68:71], 0
	v_mfma_f32_16x16x32_bf16 v[136:139], v[80:83], v[4:7], 0
	v_mfma_f32_16x16x32_bf16 v[16:19], v[80:83], v[68:71], 0
	s_waitcnt lgkmcnt(8)
	ds_read_b64_tr_b16 v[72:73], v209 offset:8704
	ds_read_b64_tr_b16 v[80:81], v209 offset:8736
	ds_read_b64_tr_b16 v[74:75], v209 offset:13056
	ds_read_b64_tr_b16 v[82:83], v209 offset:13088
	v_mfma_f32_16x16x32_bf16 v[140:143], v[88:91], v[4:7], 0
	v_mfma_f32_16x16x32_bf16 v[24:27], v[88:91], v[68:71], 0
	v_mfma_f32_16x16x32_bf16 v[144:147], v[96:99], v[4:7], 0
	v_mfma_f32_16x16x32_bf16 v[32:35], v[96:99], v[68:71], 0
	s_waitcnt lgkmcnt(8)
	ds_read_b64_tr_b16 v[88:89], v209 offset:8768
	ds_read_b64_tr_b16 v[96:97], v209 offset:8800
	ds_read_b64_tr_b16 v[90:91], v209 offset:13120
	ds_read_b64_tr_b16 v[98:99], v209 offset:13152
	v_mfma_f32_16x16x32_bf16 v[148:151], v[104:107], v[4:7], 0
	v_mfma_f32_16x16x32_bf16 v[40:43], v[104:107], v[68:71], 0
	v_mfma_f32_16x16x32_bf16 v[152:155], v[112:115], v[4:7], 0
	v_mfma_f32_16x16x32_bf16 v[48:51], v[112:115], v[68:71], 0
	s_waitcnt lgkmcnt(8)
	ds_read_b64_tr_b16 v[104:105], v209 offset:8832
	ds_read_b64_tr_b16 v[112:113], v209 offset:8864
	ds_read_b64_tr_b16 v[106:107], v209 offset:13184
	ds_read_b64_tr_b16 v[114:115], v209 offset:13216
	v_mfma_f32_16x16x32_bf16 v[156:159], v[120:123], v[4:7], 0
	v_mfma_f32_16x16x32_bf16 v[56:59], v[120:123], v[68:71], 0
	v_mfma_f32_16x16x32_bf16 v[160:163], v[128:131], v[4:7], 0
	v_mfma_f32_16x16x32_bf16 v[64:67], v[128:131], v[68:71], 0
	s_waitcnt lgkmcnt(8)
	ds_read_b64_tr_b16 v[120:121], v209 offset:8896
	ds_read_b64_tr_b16 v[128:129], v209 offset:8928
	ds_read_b64_tr_b16 v[122:123], v209 offset:13248
	ds_read_b64_tr_b16 v[130:131], v209 offset:13280
	v_mfma_f32_16x16x32_bf16 v[132:135], v[72:75], v[12:15], v[132:135]
	v_mfma_f32_16x16x32_bf16 v[8:11], v[72:75], v[76:79], v[8:11]
	v_mfma_f32_16x16x32_bf16 v[136:139], v[80:83], v[12:15], v[136:139]
	v_mfma_f32_16x16x32_bf16 v[16:19], v[80:83], v[76:79], v[16:19]
	s_waitcnt lgkmcnt(8)
	ds_read_b64_tr_b16 v[72:73], v209 offset:17408
	ds_read_b64_tr_b16 v[80:81], v209 offset:17440
	ds_read_b64_tr_b16 v[74:75], v209 offset:21760
	ds_read_b64_tr_b16 v[82:83], v209 offset:21792
	v_mfma_f32_16x16x32_bf16 v[140:143], v[88:91], v[12:15], v[140:143]
	v_mfma_f32_16x16x32_bf16 v[24:27], v[88:91], v[76:79], v[24:27]
	v_mfma_f32_16x16x32_bf16 v[144:147], v[96:99], v[12:15], v[144:147]
	v_mfma_f32_16x16x32_bf16 v[32:35], v[96:99], v[76:79], v[32:35]
	s_waitcnt lgkmcnt(8)
	ds_read_b64_tr_b16 v[88:89], v209 offset:17472
	ds_read_b64_tr_b16 v[96:97], v209 offset:17504
	ds_read_b64_tr_b16 v[90:91], v209 offset:21824
	ds_read_b64_tr_b16 v[98:99], v209 offset:21856
	v_mfma_f32_16x16x32_bf16 v[148:151], v[104:107], v[12:15], v[148:151]
	v_mfma_f32_16x16x32_bf16 v[40:43], v[104:107], v[76:79], v[40:43]
	v_mfma_f32_16x16x32_bf16 v[152:155], v[112:115], v[12:15], v[152:155]
	v_mfma_f32_16x16x32_bf16 v[48:51], v[112:115], v[76:79], v[48:51]
	s_waitcnt lgkmcnt(8)
	ds_read_b64_tr_b16 v[104:105], v209 offset:17536
	ds_read_b64_tr_b16 v[112:113], v209 offset:17568
	ds_read_b64_tr_b16 v[106:107], v209 offset:21888
	ds_read_b64_tr_b16 v[114:115], v209 offset:21920
	v_mfma_f32_16x16x32_bf16 v[156:159], v[120:123], v[12:15], v[156:159]
	v_mfma_f32_16x16x32_bf16 v[56:59], v[120:123], v[76:79], v[56:59]
	v_mfma_f32_16x16x32_bf16 v[160:163], v[128:131], v[12:15], v[160:163]
	v_mfma_f32_16x16x32_bf16 v[64:67], v[128:131], v[76:79], v[64:67]
	s_waitcnt lgkmcnt(8)
; __device__ __forceinline__ f32x4 mfma16(bf16x8 a, bf16x8 b, f32x4 c) { return __builtin_amdgcn_mfma_f32_16x16x32_bf16(a, b, c, 0, 0, 0); }
; __device__ void cross_items(const Params& p, LAS unsigned char* lds) {
;     ...
; #pragma unroll
;             for (int sx = 0; sx < 8; ++sx) {
;                 const unsigned aA = bb + (unsigned)((32 * sx + 4 * g + (idx >> 2)) * KV_STRIDE + 8 * (idx & 3));
;                 const unsigned aB = aA + 16u * KV_STRIDE;
;                 bf16x8 vf[4];
;                 tr_frag4(aA, aB, vf);
; #pragma unroll
;                 for (int c8 = 0; c8 < 4; ++c8) ot[c8] = mfma16(vf[c8], pf[sx], ot[c8]);
;                 tr_frag4(aA + 128, aB + 128, vf);
; #pragma unroll
;                 for (int c8 = 0; c8 < 4; ++c8) ot[4 + c8] = mfma16(vf[c8], pf[sx], ot[4 + c8]);
	ds_read_b64_tr_b16 v[120:121], v209 offset:17600
	ds_read_b64_tr_b16 v[128:129], v209 offset:17632
	ds_read_b64_tr_b16 v[122:123], v209 offset:21952
	ds_read_b64_tr_b16 v[130:131], v209 offset:21984
	v_mfma_f32_16x16x32_bf16 v[132:135], v[72:75], v[20:23], v[132:135]
	v_mfma_f32_16x16x32_bf16 v[8:11], v[72:75], v[84:87], v[8:11]
	v_mfma_f32_16x16x32_bf16 v[136:139], v[80:83], v[20:23], v[136:139]
	v_mfma_f32_16x16x32_bf16 v[16:19], v[80:83], v[84:87], v[16:19]
	s_waitcnt lgkmcnt(8)
	ds_read_b64_tr_b16 v[72:73], v209 offset:26112
	ds_read_b64_tr_b16 v[80:81], v209 offset:26144
	ds_read_b64_tr_b16 v[74:75], v209 offset:30464
	ds_read_b64_tr_b16 v[82:83], v209 offset:30496
	v_mfma_f32_16x16x32_bf16 v[140:143], v[88:91], v[20:23], v[140:143]
	v_mfma_f32_16x16x32_bf16 v[24:27], v[88:91], v[84:87], v[24:27]
	v_mfma_f32_16x16x32_bf16 v[144:147], v[96:99], v[20:23], v[144:147]
	v_mfma_f32_16x16x32_bf16 v[32:35], v[96:99], v[84:87], v[32:35]
	s_waitcnt lgkmcnt(8)
	ds_read_b64_tr_b16 v[88:89], v209 offset:26176
	ds_read_b64_tr_b16 v[96:97], v209 offset:26208
	ds_read_b64_tr_b16 v[90:91], v209 offset:30528
	ds_read_b64_tr_b16 v[98:99], v209 offset:30560
	v_mfma_f32_16x16x32_bf16 v[148:151], v[104:107], v[20:23], v[148:151]
	v_mfma_f32_16x16x32_bf16 v[40:43], v[104:107], v[84:87], v[40:43]
	v_mfma_f32_16x16x32_bf16 v[152:155], v[112:115], v[20:23], v[152:155]
	v_mfma_f32_16x16x32_bf16 v[48:51], v[112:115], v[84:87], v[48:51]
	s_waitcnt lgkmcnt(8)
	ds_read_b64_tr_b16 v[104:105], v209 offset:26240
	ds_read_b64_tr_b16 v[112:113], v209 offset:26272
	ds_read_b64_tr_b16 v[106:107], v209 offset:30592
	ds_read_b64_tr_b16 v[114:115], v209 offset:30624
	v_mfma_f32_16x16x32_bf16 v[156:159], v[120:123], v[20:23], v[156:159]
	v_mfma_f32_16x16x32_bf16 v[56:59], v[120:123], v[84:87], v[56:59]
	v_mfma_f32_16x16x32_bf16 v[160:163], v[128:131], v[20:23], v[160:163]
	v_mfma_f32_16x16x32_bf16 v[64:67], v[128:131], v[84:87], v[64:67]
	s_waitcnt lgkmcnt(8)
	ds_read_b64_tr_b16 v[120:121], v209 offset:26304
	ds_read_b64_tr_b16 v[128:129], v209 offset:26336
	ds_read_b64_tr_b16 v[122:123], v209 offset:30656
	ds_read_b64_tr_b16 v[130:131], v209 offset:30688
	v_mfma_f32_16x16x32_bf16 v[132:135], v[72:75], v[28:31], v[132:135]
	v_mfma_f32_16x16x32_bf16 v[8:11], v[72:75], v[92:95], v[8:11]
	v_mfma_f32_16x16x32_bf16 v[136:139], v[80:83], v[28:31], v[136:139]
	v_mfma_f32_16x16x32_bf16 v[16:19], v[80:83], v[92:95], v[16:19]
	s_waitcnt lgkmcnt(8)
	ds_read_b64_tr_b16 v[72:73], v209 offset:34816
	ds_read_b64_tr_b16 v[80:81], v209 offset:34848
	ds_read_b64_tr_b16 v[74:75], v209 offset:39168
	ds_read_b64_tr_b16 v[82:83], v209 offset:39200
	v_mfma_f32_16x16x32_bf16 v[140:143], v[88:91], v[28:31], v[140:143]
	v_mfma_f32_16x16x32_bf16 v[24:27], v[88:91], v[92:95], v[24:27]
	v_mfma_f32_16x16x32_bf16 v[144:147], v[96:99], v[28:31], v[144:147]
	v_mfma_f32_16x16x32_bf16 v[32:35], v[96:99], v[92:95], v[32:35]
	s_waitcnt lgkmcnt(8)
	ds_read_b64_tr_b16 v[88:89], v209 offset:34880
	ds_read_b64_tr_b16 v[96:97], v209 offset:34912
	ds_read_b64_tr_b16 v[90:91], v209 offset:39232
	ds_read_b64_tr_b16 v[98:99], v209 offset:39264
	v_mfma_f32_16x16x32_bf16 v[148:151], v[104:107], v[28:31], v[148:151]
	v_mfma_f32_16x16x32_bf16 v[40:43], v[104:107], v[92:95], v[40:43]
	v_mfma_f32_16x16x32_bf16 v[152:155], v[112:115], v[28:31], v[152:155]
	v_mfma_f32_16x16x32_bf16 v[48:51], v[112:115], v[92:95], v[48:51]
	s_waitcnt lgkmcnt(8)
	ds_read_b64_tr_b16 v[104:105], v209 offset:34944
	ds_read_b64_tr_b16 v[112:113], v209 offset:34976
	ds_read_b64_tr_b16 v[106:107], v209 offset:39296
	ds_read_b64_tr_b16 v[114:115], v209 offset:39328
	v_mfma_f32_16x16x32_bf16 v[156:159], v[120:123], v[28:31], v[156:159]
	v_mfma_f32_16x16x32_bf16 v[56:59], v[120:123], v[92:95], v[56:59]
	v_mfma_f32_16x16x32_bf16 v[160:163], v[128:131], v[28:31], v[160:163]
	v_mfma_f32_16x16x32_bf16 v[64:67], v[128:131], v[92:95], v[64:67]
	s_waitcnt lgkmcnt(8)
	ds_read_b64_tr_b16 v[120:121], v209 offset:35008
	ds_read_b64_tr_b16 v[128:129], v209 offset:35040
	ds_read_b64_tr_b16 v[122:123], v209 offset:39360
	ds_read_b64_tr_b16 v[130:131], v209 offset:39392
	v_mfma_f32_16x16x32_bf16 v[132:135], v[72:75], v[36:39], v[132:135]
	v_mfma_f32_16x16x32_bf16 v[8:11], v[72:75], v[100:103], v[8:11]
	v_mfma_f32_16x16x32_bf16 v[136:139], v[80:83], v[36:39], v[136:139]
	v_mfma_f32_16x16x32_bf16 v[16:19], v[80:83], v[100:103], v[16:19]
	s_waitcnt lgkmcnt(8)
	ds_read_b64_tr_b16 v[72:73], v209 offset:43520
	ds_read_b64_tr_b16 v[80:81], v209 offset:43552
	ds_read_b64_tr_b16 v[74:75], v209 offset:47872
	ds_read_b64_tr_b16 v[82:83], v209 offset:47904
	v_mfma_f32_16x16x32_bf16 v[140:143], v[88:91], v[36:39], v[140:143]
	v_mfma_f32_16x16x32_bf16 v[24:27], v[88:91], v[100:103], v[24:27]
	v_mfma_f32_16x16x32_bf16 v[144:147], v[96:99], v[36:39], v[144:147]
	v_mfma_f32_16x16x32_bf16 v[32:35], v[96:99], v[100:103], v[32:35]
	s_waitcnt lgkmcnt(8)
	ds_read_b64_tr_b16 v[88:89], v209 offset:43584
	ds_read_b64_tr_b16 v[96:97], v209 offset:43616
	ds_read_b64_tr_b16 v[90:91], v209 offset:47936
	ds_read_b64_tr_b16 v[98:99], v209 offset:47968
	v_mfma_f32_16x16x32_bf16 v[148:151], v[104:107], v[36:39], v[148:151]
	v_mfma_f32_16x16x32_bf16 v[40:43], v[104:107], v[100:103], v[40:43]
	v_mfma_f32_16x16x32_bf16 v[152:155], v[112:115], v[36:39], v[152:155]
	v_mfma_f32_16x16x32_bf16 v[48:51], v[112:115], v[100:103], v[48:51]
	s_waitcnt lgkmcnt(8)
	ds_read_b64_tr_b16 v[104:105], v209 offset:43648
	ds_read_b64_tr_b16 v[112:113], v209 offset:43680
	ds_read_b64_tr_b16 v[106:107], v209 offset:48000
	ds_read_b64_tr_b16 v[114:115], v209 offset:48032
	v_mfma_f32_16x16x32_bf16 v[156:159], v[120:123], v[36:39], v[156:159]
	v_mfma_f32_16x16x32_bf16 v[56:59], v[120:123], v[100:103], v[56:59]
	v_mfma_f32_16x16x32_bf16 v[160:163], v[128:131], v[36:39], v[160:163]
	v_mfma_f32_16x16x32_bf16 v[64:67], v[128:131], v[100:103], v[64:67]
	s_waitcnt lgkmcnt(8)
; __device__ __forceinline__ f32x4 mfma16(bf16x8 a, bf16x8 b, f32x4 c) { return __builtin_amdgcn_mfma_f32_16x16x32_bf16(a, b, c, 0, 0, 0); }
; __device__ void cross_items(const Params& p, LAS unsigned char* lds) {
;     ...
; #pragma unroll
;             for (int sx = 0; sx < 8; ++sx) {
;                 const unsigned aA = bb + (unsigned)((32 * sx + 4 * g + (idx >> 2)) * KV_STRIDE + 8 * (idx & 3));
;                 const unsigned aB = aA + 16u * KV_STRIDE;
;                 bf16x8 vf[4];
;                 tr_frag4(aA, aB, vf);
; #pragma unroll
;                 for (int c8 = 0; c8 < 4; ++c8) ot[c8] = mfma16(vf[c8], pf[sx], ot[c8]);
;                 tr_frag4(aA + 128, aB + 128, vf);
; #pragma unroll
;                 for (int c8 = 0; c8 < 4; ++c8) ot[4 + c8] = mfma16(vf[c8], pf[sx], ot[4 + c8]);
	ds_read_b64_tr_b16 v[120:121], v209 offset:43712
	ds_read_b64_tr_b16 v[128:129], v209 offset:43744
	ds_read_b64_tr_b16 v[122:123], v209 offset:48064
	ds_read_b64_tr_b16 v[130:131], v209 offset:48096
	v_mfma_f32_16x16x32_bf16 v[132:135], v[72:75], v[44:47], v[132:135]
	v_mfma_f32_16x16x32_bf16 v[8:11], v[72:75], v[108:111], v[8:11]
	v_mfma_f32_16x16x32_bf16 v[136:139], v[80:83], v[44:47], v[136:139]
	v_mfma_f32_16x16x32_bf16 v[16:19], v[80:83], v[108:111], v[16:19]
	s_waitcnt lgkmcnt(8)
	ds_read_b64_tr_b16 v[72:73], v209 offset:52224
	ds_read_b64_tr_b16 v[80:81], v209 offset:52256
	ds_read_b64_tr_b16 v[74:75], v209 offset:56576
	ds_read_b64_tr_b16 v[82:83], v209 offset:56608
	v_mfma_f32_16x16x32_bf16 v[140:143], v[88:91], v[44:47], v[140:143]
	v_mfma_f32_16x16x32_bf16 v[24:27], v[88:91], v[108:111], v[24:27]
	v_mfma_f32_16x16x32_bf16 v[144:147], v[96:99], v[44:47], v[144:147]
	v_mfma_f32_16x16x32_bf16 v[32:35], v[96:99], v[108:111], v[32:35]
	s_waitcnt lgkmcnt(8)
	ds_read_b64_tr_b16 v[88:89], v209 offset:52288
	ds_read_b64_tr_b16 v[96:97], v209 offset:52320
	ds_read_b64_tr_b16 v[90:91], v209 offset:56640
	ds_read_b64_tr_b16 v[98:99], v209 offset:56672
	v_mfma_f32_16x16x32_bf16 v[148:151], v[104:107], v[44:47], v[148:151]
	v_mfma_f32_16x16x32_bf16 v[40:43], v[104:107], v[108:111], v[40:43]
	v_mfma_f32_16x16x32_bf16 v[152:155], v[112:115], v[44:47], v[152:155]
	v_mfma_f32_16x16x32_bf16 v[48:51], v[112:115], v[108:111], v[48:51]
	s_waitcnt lgkmcnt(8)
	ds_read_b64_tr_b16 v[104:105], v209 offset:52352
	ds_read_b64_tr_b16 v[112:113], v209 offset:52384
	ds_read_b64_tr_b16 v[106:107], v209 offset:56704
	ds_read_b64_tr_b16 v[114:115], v209 offset:56736
	v_mfma_f32_16x16x32_bf16 v[156:159], v[120:123], v[44:47], v[156:159]
	v_mfma_f32_16x16x32_bf16 v[56:59], v[120:123], v[108:111], v[56:59]
	v_mfma_f32_16x16x32_bf16 v[160:163], v[128:131], v[44:47], v[160:163]
	v_mfma_f32_16x16x32_bf16 v[64:67], v[128:131], v[108:111], v[64:67]
	s_waitcnt lgkmcnt(8)
	ds_read_b64_tr_b16 v[120:121], v209 offset:52416
	ds_read_b64_tr_b16 v[128:129], v209 offset:52448
	ds_read_b64_tr_b16 v[122:123], v209 offset:56768
	ds_read_b64_tr_b16 v[130:131], v209 offset:56800
	v_mfma_f32_16x16x32_bf16 v[132:135], v[72:75], v[52:55], v[132:135]
	v_mfma_f32_16x16x32_bf16 v[8:11], v[72:75], v[116:119], v[8:11]
	v_mfma_f32_16x16x32_bf16 v[136:139], v[80:83], v[52:55], v[136:139]
	v_mfma_f32_16x16x32_bf16 v[16:19], v[80:83], v[116:119], v[16:19]
	s_waitcnt lgkmcnt(8)
	ds_read_b64_tr_b16 v[72:73], v209 offset:60928
	ds_read_b64_tr_b16 v[80:81], v209 offset:60960
	ds_read_b64_tr_b16 v[74:75], v209 offset:65280
	ds_read_b64_tr_b16 v[82:83], v209 offset:65312
	v_mfma_f32_16x16x32_bf16 v[140:143], v[88:91], v[52:55], v[140:143]
	v_mfma_f32_16x16x32_bf16 v[24:27], v[88:91], v[116:119], v[24:27]
	v_mfma_f32_16x16x32_bf16 v[144:147], v[96:99], v[52:55], v[144:147]
	v_mfma_f32_16x16x32_bf16 v[32:35], v[96:99], v[116:119], v[32:35]
	s_waitcnt lgkmcnt(8)
	ds_read_b64_tr_b16 v[88:89], v209 offset:60992
	ds_read_b64_tr_b16 v[96:97], v209 offset:61024
	ds_read_b64_tr_b16 v[90:91], v209 offset:65344
	ds_read_b64_tr_b16 v[98:99], v209 offset:65376
	v_mfma_f32_16x16x32_bf16 v[148:151], v[104:107], v[52:55], v[148:151]
	v_mfma_f32_16x16x32_bf16 v[40:43], v[104:107], v[116:119], v[40:43]
	v_mfma_f32_16x16x32_bf16 v[152:155], v[112:115], v[52:55], v[152:155]
	v_mfma_f32_16x16x32_bf16 v[48:51], v[112:115], v[116:119], v[48:51]
	s_waitcnt lgkmcnt(8)
	ds_read_b64_tr_b16 v[104:105], v209 offset:61056
	ds_read_b64_tr_b16 v[112:113], v209 offset:61088
	ds_read_b64_tr_b16 v[106:107], v209 offset:65408
	ds_read_b64_tr_b16 v[114:115], v209 offset:65440
	v_mfma_f32_16x16x32_bf16 v[156:159], v[120:123], v[52:55], v[156:159]
	v_mfma_f32_16x16x32_bf16 v[56:59], v[120:123], v[116:119], v[56:59]
	v_mfma_f32_16x16x32_bf16 v[160:163], v[128:131], v[52:55], v[160:163]
	v_mfma_f32_16x16x32_bf16 v[64:67], v[128:131], v[116:119], v[64:67]
	s_waitcnt lgkmcnt(8)
	ds_read_b64_tr_b16 v[120:121], v209 offset:61120
	ds_read_b64_tr_b16 v[128:129], v209 offset:61152
	ds_read_b64_tr_b16 v[122:123], v209 offset:65472
	ds_read_b64_tr_b16 v[130:131], v209 offset:65504
	v_mfma_f32_16x16x32_bf16 v[132:135], v[72:75], v[60:63], v[132:135]
	v_mfma_f32_16x16x32_bf16 v[8:11], v[72:75], v[124:127], v[8:11]
	v_mfma_f32_16x16x32_bf16 v[136:139], v[80:83], v[60:63], v[136:139]
	v_mfma_f32_16x16x32_bf16 v[16:19], v[80:83], v[124:127], v[16:19]
	s_waitcnt lgkmcnt(8)
	v_mfma_f32_16x16x32_bf16 v[140:143], v[88:91], v[60:63], v[140:143]
	v_mfma_f32_16x16x32_bf16 v[24:27], v[88:91], v[124:127], v[24:27]
	v_mfma_f32_16x16x32_bf16 v[144:147], v[96:99], v[60:63], v[144:147]
	v_mfma_f32_16x16x32_bf16 v[32:35], v[96:99], v[124:127], v[32:35]
	s_waitcnt lgkmcnt(4)
	v_mfma_f32_16x16x32_bf16 v[148:151], v[104:107], v[60:63], v[148:151]
	v_mfma_f32_16x16x32_bf16 v[40:43], v[104:107], v[124:127], v[40:43]
	v_mfma_f32_16x16x32_bf16 v[152:155], v[112:115], v[60:63], v[152:155]
	v_mfma_f32_16x16x32_bf16 v[48:51], v[112:115], v[124:127], v[48:51]
	s_waitcnt lgkmcnt(0)
; __device__ __forceinline__ unsigned cvt_pk_bf16(float lo, float hi) { const f32x2v v = {lo, hi}; const b16x2v r = __builtin_convertvector(v, b16x2v); return __builtin_bit_cast(unsigned, r); }
; __device__ __forceinline__ f32x4 mfma16(bf16x8 a, bf16x8 b, f32x4 c) { return __builtin_amdgcn_mfma_f32_16x16x32_bf16(a, b, c, 0, 0, 0); }
; __device__ void cross_items(const Params& p, LAS unsigned char* lds) {
;     ...
; #pragma unroll
;             for (int sx = 0; sx < 8; ++sx) {
;                 const unsigned aA = bb + (unsigned)((32 * sx + 4 * g + (idx >> 2)) * KV_STRIDE + 8 * (idx & 3));
;                 const unsigned aB = aA + 16u * KV_STRIDE;
;                 bf16x8 vf[4];
;                 tr_frag4(aA, aB, vf);
; #pragma unroll
;                 for (int c8 = 0; c8 < 4; ++c8) ot[c8] = mfma16(vf[c8], pf[sx], ot[c8]);
;                 tr_frag4(aA + 128, aB + 128, vf);
; #pragma unroll
;                 for (int c8 = 0; c8 < 4; ++c8) ot[4 + c8] = mfma16(vf[c8], pf[sx], ot[4 + c8]);
;             }
; #pragma unroll
;             for (int c8 = 0; c8 < 8; ++c8) { u32x2 wv; wv.x = cvt_pk_bf16(ot[c8][0] * inv, ot[c8][1] * inv); wv.y = cvt_pk_bf16(ot[c8][2] * inv, ot[c8][3] * inv);
;                 *(u32x2*)(oc + tok * DM + head * 512 + c * 128 + 16 * c8 + 4 * g) = wv; }
;         }
	v_mfma_f32_16x16x32_bf16 v[156:159], v[120:123], v[60:63], v[156:159]
	v_mfma_f32_16x16x32_bf16 v[56:59], v[120:123], v[124:127], v[56:59]
	v_mfma_f32_16x16x32_bf16 v[160:163], v[128:131], v[60:63], v[160:163]
	v_mfma_f32_16x16x32_bf16 v[64:67], v[128:131], v[124:127], v[64:67]
	s_nop 7
	s_nop 7
	v_mul_f32_e32 v230, v244, v132
	v_mul_f32_e32 v231, v244, v133
	v_mul_f32_e32 v232, v244, v134
	v_mul_f32_e32 v233, v244, v135
	v_cvt_pk_bf16_f32 v230, v230, v231
	v_cvt_pk_bf16_f32 v231, v232, v233
	global_store_dwordx2 v248, v[230:231], s[92:93] offset:512
	v_mul_f32_e32 v234, v244, v136
	v_mul_f32_e32 v235, v244, v137
	v_mul_f32_e32 v236, v244, v138
	v_mul_f32_e32 v237, v244, v139
	v_cvt_pk_bf16_f32 v234, v234, v235
	v_cvt_pk_bf16_f32 v235, v236, v237
	global_store_dwordx2 v248, v[234:235], s[92:93] offset:544
	v_mul_f32_e32 v230, v244, v140
	v_mul_f32_e32 v231, v244, v141
	v_mul_f32_e32 v232, v244, v142
	v_mul_f32_e32 v233, v244, v143
	v_cvt_pk_bf16_f32 v230, v230, v231
	v_cvt_pk_bf16_f32 v231, v232, v233
	global_store_dwordx2 v248, v[230:231], s[92:93] offset:576
	v_mul_f32_e32 v234, v244, v144
	v_mul_f32_e32 v235, v244, v145
	v_mul_f32_e32 v236, v244, v146
	v_mul_f32_e32 v237, v244, v147
	v_cvt_pk_bf16_f32 v234, v234, v235
	v_cvt_pk_bf16_f32 v235, v236, v237
	global_store_dwordx2 v248, v[234:235], s[92:93] offset:608
	v_mul_f32_e32 v230, v244, v148
	v_mul_f32_e32 v231, v244, v149
	v_mul_f32_e32 v232, v244, v150
	v_mul_f32_e32 v233, v244, v151
	v_cvt_pk_bf16_f32 v230, v230, v231
	v_cvt_pk_bf16_f32 v231, v232, v233
	global_store_dwordx2 v248, v[230:231], s[92:93] offset:640
	v_mul_f32_e32 v234, v244, v152
	v_mul_f32_e32 v235, v244, v153
	v_mul_f32_e32 v236, v244, v154
	v_mul_f32_e32 v237, v244, v155
	v_cvt_pk_bf16_f32 v234, v234, v235
	v_cvt_pk_bf16_f32 v235, v236, v237
	global_store_dwordx2 v248, v[234:235], s[92:93] offset:672
	v_mul_f32_e32 v230, v244, v156
	v_mul_f32_e32 v231, v244, v157
	v_mul_f32_e32 v232, v244, v158
	v_mul_f32_e32 v233, v244, v159
	v_cvt_pk_bf16_f32 v230, v230, v231
	v_cvt_pk_bf16_f32 v231, v232, v233
	global_store_dwordx2 v248, v[230:231], s[92:93] offset:704
	v_mul_f32_e32 v234, v244, v160
	v_mul_f32_e32 v235, v244, v161
	v_mul_f32_e32 v236, v244, v162
	v_mul_f32_e32 v237, v244, v163
	v_cvt_pk_bf16_f32 v234, v234, v235
	v_cvt_pk_bf16_f32 v235, v236, v237
	global_store_dwordx2 v248, v[234:235], s[92:93] offset:736
	v_mul_f32_e32 v230, v245, v8
	v_mul_f32_e32 v231, v245, v9
	v_mul_f32_e32 v232, v245, v10
	v_mul_f32_e32 v233, v245, v11
	v_cvt_pk_bf16_f32 v230, v230, v231
	v_cvt_pk_bf16_f32 v231, v232, v233
	global_store_dwordx2 v249, v[230:231], s[92:93] offset:512
	v_mul_f32_e32 v234, v245, v16
	v_mul_f32_e32 v235, v245, v17
	v_mul_f32_e32 v236, v245, v18
	v_mul_f32_e32 v237, v245, v19
	v_cvt_pk_bf16_f32 v234, v234, v235
	v_cvt_pk_bf16_f32 v235, v236, v237
	global_store_dwordx2 v249, v[234:235], s[92:93] offset:544
	v_mul_f32_e32 v230, v245, v24
	v_mul_f32_e32 v231, v245, v25
	v_mul_f32_e32 v232, v245, v26
	v_mul_f32_e32 v233, v245, v27
	v_cvt_pk_bf16_f32 v230, v230, v231
	v_cvt_pk_bf16_f32 v231, v232, v233
	global_store_dwordx2 v249, v[230:231], s[92:93] offset:576
	v_mul_f32_e32 v234, v245, v32
	v_mul_f32_e32 v235, v245, v33
	v_mul_f32_e32 v236, v245, v34
	v_mul_f32_e32 v237, v245, v35
	v_cvt_pk_bf16_f32 v234, v234, v235
	v_cvt_pk_bf16_f32 v235, v236, v237
	global_store_dwordx2 v249, v[234:235], s[92:93] offset:608
	v_mul_f32_e32 v230, v245, v40
	v_mul_f32_e32 v231, v245, v41
	v_mul_f32_e32 v232, v245, v42
	v_mul_f32_e32 v233, v245, v43
	v_cvt_pk_bf16_f32 v230, v230, v231
	v_cvt_pk_bf16_f32 v231, v232, v233
	global_store_dwordx2 v249, v[230:231], s[92:93] offset:640
	v_mul_f32_e32 v234, v245, v48
	v_mul_f32_e32 v235, v245, v49
	v_mul_f32_e32 v236, v245, v50
	v_mul_f32_e32 v237, v245, v51
	v_cvt_pk_bf16_f32 v234, v234, v235
	v_cvt_pk_bf16_f32 v235, v236, v237
	global_store_dwordx2 v249, v[234:235], s[92:93] offset:672
	v_mul_f32_e32 v230, v245, v56
	v_mul_f32_e32 v231, v245, v57
	v_mul_f32_e32 v232, v245, v58
	v_mul_f32_e32 v233, v245, v59
	v_cvt_pk_bf16_f32 v230, v230, v231
	v_cvt_pk_bf16_f32 v231, v232, v233
	global_store_dwordx2 v249, v[230:231], s[92:93] offset:704
	v_mul_f32_e32 v234, v245, v64
	v_mul_f32_e32 v235, v245, v65
	v_mul_f32_e32 v236, v245, v66
	v_mul_f32_e32 v237, v245, v67
	v_cvt_pk_bf16_f32 v234, v234, v235
	v_cvt_pk_bf16_f32 v235, v236, v237
	global_store_dwordx2 v249, v[234:235], s[92:93] offset:736
	s_waitcnt vmcnt(23)
	ds_write_b128 v1, v[164:167]
	s_waitcnt vmcnt(22)
	ds_write_b128 v1, v[168:171] offset:8704
	s_waitcnt vmcnt(21)
	ds_write_b128 v1, v[172:175] offset:17408
	s_waitcnt vmcnt(20)
	ds_write_b128 v1, v[176:179] offset:26112
	s_waitcnt vmcnt(19)
	ds_write_b128 v1, v[180:183] offset:34816
	s_waitcnt vmcnt(18)
	ds_write_b128 v1, v[184:187] offset:43520
	s_waitcnt vmcnt(17)
	ds_write_b128 v1, v[188:191] offset:52224
	s_waitcnt vmcnt(16)
	ds_write_b128 v1, v[192:195] offset:60928
	s_waitcnt lgkmcnt(0)
	s_barrier
; __device__ __forceinline__ f32x4 mfma16(bf16x8 a, bf16x8 b, f32x4 c) { return __builtin_amdgcn_mfma_f32_16x16x32_bf16(a, b, c, 0, 0, 0); }
; __device__ void cross_items(const Params& p, LAS unsigned char* lds) {
;     ...
; #pragma unroll
;             for (int sx = 0; sx < 8; ++sx) {
;                 const unsigned aA = bb + (unsigned)((32 * sx + 4 * g + (idx >> 2)) * KV_STRIDE + 8 * (idx & 3));
;                 const unsigned aB = aA + 16u * KV_STRIDE;
;                 bf16x8 vf[4];
;                 tr_frag4(aA, aB, vf);
; #pragma unroll
;                 for (int c8 = 0; c8 < 4; ++c8) ot[c8] = mfma16(vf[c8], pf[sx], ot[c8]);
;                 tr_frag4(aA + 128, aB + 128, vf);
; #pragma unroll
;                 for (int c8 = 0; c8 < 4; ++c8) ot[4 + c8] = mfma16(vf[c8], pf[sx], ot[4 + c8]);
	ds_read_b64_tr_b16 v[72:73], v210
	ds_read_b64_tr_b16 v[80:81], v210 offset:32
	ds_read_b64_tr_b16 v[74:75], v210 offset:4352
	ds_read_b64_tr_b16 v[82:83], v210 offset:4384
	ds_read_b64_tr_b16 v[88:89], v210 offset:64
	ds_read_b64_tr_b16 v[96:97], v210 offset:96
	ds_read_b64_tr_b16 v[90:91], v210 offset:4416
	ds_read_b64_tr_b16 v[98:99], v210 offset:4448
	ds_read_b64_tr_b16 v[104:105], v210 offset:128
	ds_read_b64_tr_b16 v[112:113], v210 offset:160
	ds_read_b64_tr_b16 v[106:107], v210 offset:4480
	ds_read_b64_tr_b16 v[114:115], v210 offset:4512
	s_waitcnt lgkmcnt(8)
	ds_read_b64_tr_b16 v[120:121], v210 offset:192
	ds_read_b64_tr_b16 v[128:129], v210 offset:224
	ds_read_b64_tr_b16 v[122:123], v210 offset:4544
	ds_read_b64_tr_b16 v[130:131], v210 offset:4576
	v_mfma_f32_16x16x32_bf16 v[132:135], v[72:75], v[4:7], 0
	v_mfma_f32_16x16x32_bf16 v[8:11], v[72:75], v[68:71], 0
	v_mfma_f32_16x16x32_bf16 v[136:139], v[80:83], v[4:7], 0
	v_mfma_f32_16x16x32_bf16 v[16:19], v[80:83], v[68:71], 0
	s_waitcnt lgkmcnt(8)
	ds_read_b64_tr_b16 v[72:73], v210 offset:8704
	ds_read_b64_tr_b16 v[80:81], v210 offset:8736
	ds_read_b64_tr_b16 v[74:75], v210 offset:13056
	ds_read_b64_tr_b16 v[82:83], v210 offset:13088
	v_mfma_f32_16x16x32_bf16 v[140:143], v[88:91], v[4:7], 0
	v_mfma_f32_16x16x32_bf16 v[24:27], v[88:91], v[68:71], 0
	v_mfma_f32_16x16x32_bf16 v[144:147], v[96:99], v[4:7], 0
	v_mfma_f32_16x16x32_bf16 v[32:35], v[96:99], v[68:71], 0
	s_waitcnt lgkmcnt(8)
	ds_read_b64_tr_b16 v[88:89], v210 offset:8768
	ds_read_b64_tr_b16 v[96:97], v210 offset:8800
	ds_read_b64_tr_b16 v[90:91], v210 offset:13120
	ds_read_b64_tr_b16 v[98:99], v210 offset:13152
	v_mfma_f32_16x16x32_bf16 v[148:151], v[104:107], v[4:7], 0
	v_mfma_f32_16x16x32_bf16 v[40:43], v[104:107], v[68:71], 0
	v_mfma_f32_16x16x32_bf16 v[152:155], v[112:115], v[4:7], 0
	v_mfma_f32_16x16x32_bf16 v[48:51], v[112:115], v[68:71], 0
	s_waitcnt lgkmcnt(8)
	ds_read_b64_tr_b16 v[104:105], v210 offset:8832
	ds_read_b64_tr_b16 v[112:113], v210 offset:8864
	ds_read_b64_tr_b16 v[106:107], v210 offset:13184
	ds_read_b64_tr_b16 v[114:115], v210 offset:13216
	v_mfma_f32_16x16x32_bf16 v[156:159], v[120:123], v[4:7], 0
	v_mfma_f32_16x16x32_bf16 v[56:59], v[120:123], v[68:71], 0
	v_mfma_f32_16x16x32_bf16 v[160:163], v[128:131], v[4:7], 0
	v_mfma_f32_16x16x32_bf16 v[64:67], v[128:131], v[68:71], 0
	s_waitcnt lgkmcnt(8)
	ds_read_b64_tr_b16 v[120:121], v210 offset:8896
	ds_read_b64_tr_b16 v[128:129], v210 offset:8928
	ds_read_b64_tr_b16 v[122:123], v210 offset:13248
	ds_read_b64_tr_b16 v[130:131], v210 offset:13280
	v_mfma_f32_16x16x32_bf16 v[132:135], v[72:75], v[12:15], v[132:135]
	v_mfma_f32_16x16x32_bf16 v[8:11], v[72:75], v[76:79], v[8:11]
	v_mfma_f32_16x16x32_bf16 v[136:139], v[80:83], v[12:15], v[136:139]
	v_mfma_f32_16x16x32_bf16 v[16:19], v[80:83], v[76:79], v[16:19]
	s_waitcnt lgkmcnt(8)
	ds_read_b64_tr_b16 v[72:73], v210 offset:17408
	ds_read_b64_tr_b16 v[80:81], v210 offset:17440
	ds_read_b64_tr_b16 v[74:75], v210 offset:21760
	ds_read_b64_tr_b16 v[82:83], v210 offset:21792
	v_mfma_f32_16x16x32_bf16 v[140:143], v[88:91], v[12:15], v[140:143]
	v_mfma_f32_16x16x32_bf16 v[24:27], v[88:91], v[76:79], v[24:27]
	v_mfma_f32_16x16x32_bf16 v[144:147], v[96:99], v[12:15], v[144:147]
	v_mfma_f32_16x16x32_bf16 v[32:35], v[96:99], v[76:79], v[32:35]
	s_waitcnt lgkmcnt(8)
	ds_read_b64_tr_b16 v[88:89], v210 offset:17472
	ds_read_b64_tr_b16 v[96:97], v210 offset:17504
	ds_read_b64_tr_b16 v[90:91], v210 offset:21824
	ds_read_b64_tr_b16 v[98:99], v210 offset:21856
	v_mfma_f32_16x16x32_bf16 v[148:151], v[104:107], v[12:15], v[148:151]
	v_mfma_f32_16x16x32_bf16 v[40:43], v[104:107], v[76:79], v[40:43]
	v_mfma_f32_16x16x32_bf16 v[152:155], v[112:115], v[12:15], v[152:155]
	v_mfma_f32_16x16x32_bf16 v[48:51], v[112:115], v[76:79], v[48:51]
	s_waitcnt lgkmcnt(8)
	ds_read_b64_tr_b16 v[104:105], v210 offset:17536
	ds_read_b64_tr_b16 v[112:113], v210 offset:17568
	ds_read_b64_tr_b16 v[106:107], v210 offset:21888
	ds_read_b64_tr_b16 v[114:115], v210 offset:21920
	v_mfma_f32_16x16x32_bf16 v[156:159], v[120:123], v[12:15], v[156:159]
	v_mfma_f32_16x16x32_bf16 v[56:59], v[120:123], v[76:79], v[56:59]
	v_mfma_f32_16x16x32_bf16 v[160:163], v[128:131], v[12:15], v[160:163]
	v_mfma_f32_16x16x32_bf16 v[64:67], v[128:131], v[76:79], v[64:67]
	s_waitcnt lgkmcnt(8)
	ds_read_b64_tr_b16 v[120:121], v210 offset:17600
	ds_read_b64_tr_b16 v[128:129], v210 offset:17632
	ds_read_b64_tr_b16 v[122:123], v210 offset:21952
	ds_read_b64_tr_b16 v[130:131], v210 offset:21984
	v_mfma_f32_16x16x32_bf16 v[132:135], v[72:75], v[20:23], v[132:135]
	v_mfma_f32_16x16x32_bf16 v[8:11], v[72:75], v[84:87], v[8:11]
	v_mfma_f32_16x16x32_bf16 v[136:139], v[80:83], v[20:23], v[136:139]
	v_mfma_f32_16x16x32_bf16 v[16:19], v[80:83], v[84:87], v[16:19]
	s_waitcnt lgkmcnt(8)
	ds_read_b64_tr_b16 v[72:73], v210 offset:26112
	ds_read_b64_tr_b16 v[80:81], v210 offset:26144
	ds_read_b64_tr_b16 v[74:75], v210 offset:30464
	ds_read_b64_tr_b16 v[82:83], v210 offset:30496
	v_mfma_f32_16x16x32_bf16 v[140:143], v[88:91], v[20:23], v[140:143]
	v_mfma_f32_16x16x32_bf16 v[24:27], v[88:91], v[84:87], v[24:27]
	v_mfma_f32_16x16x32_bf16 v[144:147], v[96:99], v[20:23], v[144:147]
	v_mfma_f32_16x16x32_bf16 v[32:35], v[96:99], v[84:87], v[32:35]
	s_waitcnt lgkmcnt(8)
	ds_read_b64_tr_b16 v[88:89], v210 offset:26176
	ds_read_b64_tr_b16 v[96:97], v210 offset:26208
	ds_read_b64_tr_b16 v[90:91], v210 offset:30528
	ds_read_b64_tr_b16 v[98:99], v210 offset:30560
	v_mfma_f32_16x16x32_bf16 v[148:151], v[104:107], v[20:23], v[148:151]
	v_mfma_f32_16x16x32_bf16 v[40:43], v[104:107], v[84:87], v[40:43]
	v_mfma_f32_16x16x32_bf16 v[152:155], v[112:115], v[20:23], v[152:155]
	v_mfma_f32_16x16x32_bf16 v[48:51], v[112:115], v[84:87], v[48:51]
	s_waitcnt lgkmcnt(8)
; __device__ __forceinline__ f32x4 mfma16(bf16x8 a, bf16x8 b, f32x4 c) { return __builtin_amdgcn_mfma_f32_16x16x32_bf16(a, b, c, 0, 0, 0); }
; __device__ void cross_items(const Params& p, LAS unsigned char* lds) {
;     ...
; #pragma unroll
;             for (int sx = 0; sx < 8; ++sx) {
;                 const unsigned aA = bb + (unsigned)((32 * sx + 4 * g + (idx >> 2)) * KV_STRIDE + 8 * (idx & 3));
;                 const unsigned aB = aA + 16u * KV_STRIDE;
;                 bf16x8 vf[4];
;                 tr_frag4(aA, aB, vf);
; #pragma unroll
;                 for (int c8 = 0; c8 < 4; ++c8) ot[c8] = mfma16(vf[c8], pf[sx], ot[c8]);
;                 tr_frag4(aA + 128, aB + 128, vf);
; #pragma unroll
;                 for (int c8 = 0; c8 < 4; ++c8) ot[4 + c8] = mfma16(vf[c8], pf[sx], ot[4 + c8]);
	ds_read_b64_tr_b16 v[104:105], v210 offset:26240
	ds_read_b64_tr_b16 v[112:113], v210 offset:26272
	ds_read_b64_tr_b16 v[106:107], v210 offset:30592
	ds_read_b64_tr_b16 v[114:115], v210 offset:30624
	v_mfma_f32_16x16x32_bf16 v[156:159], v[120:123], v[20:23], v[156:159]
	v_mfma_f32_16x16x32_bf16 v[56:59], v[120:123], v[84:87], v[56:59]
	v_mfma_f32_16x16x32_bf16 v[160:163], v[128:131], v[20:23], v[160:163]
	v_mfma_f32_16x16x32_bf16 v[64:67], v[128:131], v[84:87], v[64:67]
	s_waitcnt lgkmcnt(8)
	ds_read_b64_tr_b16 v[120:121], v210 offset:26304
	ds_read_b64_tr_b16 v[128:129], v210 offset:26336
	ds_read_b64_tr_b16 v[122:123], v210 offset:30656
	ds_read_b64_tr_b16 v[130:131], v210 offset:30688
	v_mfma_f32_16x16x32_bf16 v[132:135], v[72:75], v[28:31], v[132:135]
	v_mfma_f32_16x16x32_bf16 v[8:11], v[72:75], v[92:95], v[8:11]
	v_mfma_f32_16x16x32_bf16 v[136:139], v[80:83], v[28:31], v[136:139]
	v_mfma_f32_16x16x32_bf16 v[16:19], v[80:83], v[92:95], v[16:19]
	s_waitcnt lgkmcnt(8)
	ds_read_b64_tr_b16 v[72:73], v210 offset:34816
	ds_read_b64_tr_b16 v[80:81], v210 offset:34848
	ds_read_b64_tr_b16 v[74:75], v210 offset:39168
	ds_read_b64_tr_b16 v[82:83], v210 offset:39200
	v_mfma_f32_16x16x32_bf16 v[140:143], v[88:91], v[28:31], v[140:143]
	v_mfma_f32_16x16x32_bf16 v[24:27], v[88:91], v[92:95], v[24:27]
	v_mfma_f32_16x16x32_bf16 v[144:147], v[96:99], v[28:31], v[144:147]
	v_mfma_f32_16x16x32_bf16 v[32:35], v[96:99], v[92:95], v[32:35]
	s_waitcnt lgkmcnt(8)
	ds_read_b64_tr_b16 v[88:89], v210 offset:34880
	ds_read_b64_tr_b16 v[96:97], v210 offset:34912
	ds_read_b64_tr_b16 v[90:91], v210 offset:39232
	ds_read_b64_tr_b16 v[98:99], v210 offset:39264
	v_mfma_f32_16x16x32_bf16 v[148:151], v[104:107], v[28:31], v[148:151]
	v_mfma_f32_16x16x32_bf16 v[40:43], v[104:107], v[92:95], v[40:43]
	v_mfma_f32_16x16x32_bf16 v[152:155], v[112:115], v[28:31], v[152:155]
	v_mfma_f32_16x16x32_bf16 v[48:51], v[112:115], v[92:95], v[48:51]
	s_waitcnt lgkmcnt(8)
	ds_read_b64_tr_b16 v[104:105], v210 offset:34944
	ds_read_b64_tr_b16 v[112:113], v210 offset:34976
	ds_read_b64_tr_b16 v[106:107], v210 offset:39296
	ds_read_b64_tr_b16 v[114:115], v210 offset:39328
	v_mfma_f32_16x16x32_bf16 v[156:159], v[120:123], v[28:31], v[156:159]
	v_mfma_f32_16x16x32_bf16 v[56:59], v[120:123], v[92:95], v[56:59]
	v_mfma_f32_16x16x32_bf16 v[160:163], v[128:131], v[28:31], v[160:163]
	v_mfma_f32_16x16x32_bf16 v[64:67], v[128:131], v[92:95], v[64:67]
	s_waitcnt lgkmcnt(8)
	ds_read_b64_tr_b16 v[120:121], v210 offset:35008
	ds_read_b64_tr_b16 v[128:129], v210 offset:35040
	ds_read_b64_tr_b16 v[122:123], v210 offset:39360
	ds_read_b64_tr_b16 v[130:131], v210 offset:39392
	v_mfma_f32_16x16x32_bf16 v[132:135], v[72:75], v[36:39], v[132:135]
	v_mfma_f32_16x16x32_bf16 v[8:11], v[72:75], v[100:103], v[8:11]
	v_mfma_f32_16x16x32_bf16 v[136:139], v[80:83], v[36:39], v[136:139]
	v_mfma_f32_16x16x32_bf16 v[16:19], v[80:83], v[100:103], v[16:19]
	s_waitcnt lgkmcnt(8)
	ds_read_b64_tr_b16 v[72:73], v210 offset:43520
	ds_read_b64_tr_b16 v[80:81], v210 offset:43552
	ds_read_b64_tr_b16 v[74:75], v210 offset:47872
	ds_read_b64_tr_b16 v[82:83], v210 offset:47904
	v_mfma_f32_16x16x32_bf16 v[140:143], v[88:91], v[36:39], v[140:143]
	v_mfma_f32_16x16x32_bf16 v[24:27], v[88:91], v[100:103], v[24:27]
	v_mfma_f32_16x16x32_bf16 v[144:147], v[96:99], v[36:39], v[144:147]
	v_mfma_f32_16x16x32_bf16 v[32:35], v[96:99], v[100:103], v[32:35]
	s_waitcnt lgkmcnt(8)
	ds_read_b64_tr_b16 v[88:89], v210 offset:43584
	ds_read_b64_tr_b16 v[96:97], v210 offset:43616
	ds_read_b64_tr_b16 v[90:91], v210 offset:47936
	ds_read_b64_tr_b16 v[98:99], v210 offset:47968
	v_mfma_f32_16x16x32_bf16 v[148:151], v[104:107], v[36:39], v[148:151]
	v_mfma_f32_16x16x32_bf16 v[40:43], v[104:107], v[100:103], v[40:43]
	v_mfma_f32_16x16x32_bf16 v[152:155], v[112:115], v[36:39], v[152:155]
	v_mfma_f32_16x16x32_bf16 v[48:51], v[112:115], v[100:103], v[48:51]
	s_waitcnt lgkmcnt(8)
	ds_read_b64_tr_b16 v[104:105], v210 offset:43648
	ds_read_b64_tr_b16 v[112:113], v210 offset:43680
	ds_read_b64_tr_b16 v[106:107], v210 offset:48000
	ds_read_b64_tr_b16 v[114:115], v210 offset:48032
	v_mfma_f32_16x16x32_bf16 v[156:159], v[120:123], v[36:39], v[156:159]
	v_mfma_f32_16x16x32_bf16 v[56:59], v[120:123], v[100:103], v[56:59]
	v_mfma_f32_16x16x32_bf16 v[160:163], v[128:131], v[36:39], v[160:163]
	v_mfma_f32_16x16x32_bf16 v[64:67], v[128:131], v[100:103], v[64:67]
	s_waitcnt lgkmcnt(8)
	ds_read_b64_tr_b16 v[120:121], v210 offset:43712
	ds_read_b64_tr_b16 v[128:129], v210 offset:43744
	ds_read_b64_tr_b16 v[122:123], v210 offset:48064
	ds_read_b64_tr_b16 v[130:131], v210 offset:48096
	v_mfma_f32_16x16x32_bf16 v[132:135], v[72:75], v[44:47], v[132:135]
	v_mfma_f32_16x16x32_bf16 v[8:11], v[72:75], v[108:111], v[8:11]
	v_mfma_f32_16x16x32_bf16 v[136:139], v[80:83], v[44:47], v[136:139]
	v_mfma_f32_16x16x32_bf16 v[16:19], v[80:83], v[108:111], v[16:19]
	s_waitcnt lgkmcnt(8)
	ds_read_b64_tr_b16 v[72:73], v210 offset:52224
	ds_read_b64_tr_b16 v[80:81], v210 offset:52256
	ds_read_b64_tr_b16 v[74:75], v210 offset:56576
	ds_read_b64_tr_b16 v[82:83], v210 offset:56608
	v_mfma_f32_16x16x32_bf16 v[140:143], v[88:91], v[44:47], v[140:143]
	v_mfma_f32_16x16x32_bf16 v[24:27], v[88:91], v[108:111], v[24:27]
	v_mfma_f32_16x16x32_bf16 v[144:147], v[96:99], v[44:47], v[144:147]
	v_mfma_f32_16x16x32_bf16 v[32:35], v[96:99], v[108:111], v[32:35]
	s_waitcnt lgkmcnt(8)
; __device__ __forceinline__ f32x4 mfma16(bf16x8 a, bf16x8 b, f32x4 c) { return __builtin_amdgcn_mfma_f32_16x16x32_bf16(a, b, c, 0, 0, 0); }
; __device__ void cross_items(const Params& p, LAS unsigned char* lds) {
;     ...
; #pragma unroll
;             for (int sx = 0; sx < 8; ++sx) {
;                 const unsigned aA = bb + (unsigned)((32 * sx + 4 * g + (idx >> 2)) * KV_STRIDE + 8 * (idx & 3));
;                 const unsigned aB = aA + 16u * KV_STRIDE;
;                 bf16x8 vf[4];
;                 tr_frag4(aA, aB, vf);
; #pragma unroll
;                 for (int c8 = 0; c8 < 4; ++c8) ot[c8] = mfma16(vf[c8], pf[sx], ot[c8]);
;                 tr_frag4(aA + 128, aB + 128, vf);
; #pragma unroll
;                 for (int c8 = 0; c8 < 4; ++c8) ot[4 + c8] = mfma16(vf[c8], pf[sx], ot[4 + c8]);
	ds_read_b64_tr_b16 v[88:89], v210 offset:52288
	ds_read_b64_tr_b16 v[96:97], v210 offset:52320
	ds_read_b64_tr_b16 v[90:91], v210 offset:56640
	ds_read_b64_tr_b16 v[98:99], v210 offset:56672
	v_mfma_f32_16x16x32_bf16 v[148:151], v[104:107], v[44:47], v[148:151]
	v_mfma_f32_16x16x32_bf16 v[40:43], v[104:107], v[108:111], v[40:43]
	v_mfma_f32_16x16x32_bf16 v[152:155], v[112:115], v[44:47], v[152:155]
	v_mfma_f32_16x16x32_bf16 v[48:51], v[112:115], v[108:111], v[48:51]
	s_waitcnt lgkmcnt(8)
	ds_read_b64_tr_b16 v[104:105], v210 offset:52352
	ds_read_b64_tr_b16 v[112:113], v210 offset:52384
	ds_read_b64_tr_b16 v[106:107], v210 offset:56704
	ds_read_b64_tr_b16 v[114:115], v210 offset:56736
	v_mfma_f32_16x16x32_bf16 v[156:159], v[120:123], v[44:47], v[156:159]
	v_mfma_f32_16x16x32_bf16 v[56:59], v[120:123], v[108:111], v[56:59]
	v_mfma_f32_16x16x32_bf16 v[160:163], v[128:131], v[44:47], v[160:163]
	v_mfma_f32_16x16x32_bf16 v[64:67], v[128:131], v[108:111], v[64:67]
	s_waitcnt lgkmcnt(8)
	ds_read_b64_tr_b16 v[120:121], v210 offset:52416
	ds_read_b64_tr_b16 v[128:129], v210 offset:52448
	ds_read_b64_tr_b16 v[122:123], v210 offset:56768
	ds_read_b64_tr_b16 v[130:131], v210 offset:56800
	v_mfma_f32_16x16x32_bf16 v[132:135], v[72:75], v[52:55], v[132:135]
	v_mfma_f32_16x16x32_bf16 v[8:11], v[72:75], v[116:119], v[8:11]
	v_mfma_f32_16x16x32_bf16 v[136:139], v[80:83], v[52:55], v[136:139]
	v_mfma_f32_16x16x32_bf16 v[16:19], v[80:83], v[116:119], v[16:19]
	s_waitcnt lgkmcnt(8)
	ds_read_b64_tr_b16 v[72:73], v210 offset:60928
	ds_read_b64_tr_b16 v[80:81], v210 offset:60960
	ds_read_b64_tr_b16 v[74:75], v210 offset:65280
	ds_read_b64_tr_b16 v[82:83], v210 offset:65312
	v_mfma_f32_16x16x32_bf16 v[140:143], v[88:91], v[52:55], v[140:143]
	v_mfma_f32_16x16x32_bf16 v[24:27], v[88:91], v[116:119], v[24:27]
	v_mfma_f32_16x16x32_bf16 v[144:147], v[96:99], v[52:55], v[144:147]
	v_mfma_f32_16x16x32_bf16 v[32:35], v[96:99], v[116:119], v[32:35]
	s_waitcnt lgkmcnt(8)
	ds_read_b64_tr_b16 v[88:89], v210 offset:60992
	ds_read_b64_tr_b16 v[96:97], v210 offset:61024
	ds_read_b64_tr_b16 v[90:91], v210 offset:65344
	ds_read_b64_tr_b16 v[98:99], v210 offset:65376
	v_mfma_f32_16x16x32_bf16 v[148:151], v[104:107], v[52:55], v[148:151]
	v_mfma_f32_16x16x32_bf16 v[40:43], v[104:107], v[116:119], v[40:43]
	v_mfma_f32_16x16x32_bf16 v[152:155], v[112:115], v[52:55], v[152:155]
	v_mfma_f32_16x16x32_bf16 v[48:51], v[112:115], v[116:119], v[48:51]
	s_waitcnt lgkmcnt(8)
	ds_read_b64_tr_b16 v[104:105], v210 offset:61056
	ds_read_b64_tr_b16 v[112:113], v210 offset:61088
	ds_read_b64_tr_b16 v[106:107], v210 offset:65408
	ds_read_b64_tr_b16 v[114:115], v210 offset:65440
	v_mfma_f32_16x16x32_bf16 v[156:159], v[120:123], v[52:55], v[156:159]
	v_mfma_f32_16x16x32_bf16 v[56:59], v[120:123], v[116:119], v[56:59]
	v_mfma_f32_16x16x32_bf16 v[160:163], v[128:131], v[52:55], v[160:163]
	v_mfma_f32_16x16x32_bf16 v[64:67], v[128:131], v[116:119], v[64:67]
	s_waitcnt lgkmcnt(8)
	ds_read_b64_tr_b16 v[120:121], v210 offset:61120
	ds_read_b64_tr_b16 v[128:129], v210 offset:61152
	ds_read_b64_tr_b16 v[122:123], v210 offset:65472
	ds_read_b64_tr_b16 v[130:131], v210 offset:65504
	v_mfma_f32_16x16x32_bf16 v[132:135], v[72:75], v[60:63], v[132:135]
	v_mfma_f32_16x16x32_bf16 v[8:11], v[72:75], v[124:127], v[8:11]
	v_mfma_f32_16x16x32_bf16 v[136:139], v[80:83], v[60:63], v[136:139]
	v_mfma_f32_16x16x32_bf16 v[16:19], v[80:83], v[124:127], v[16:19]
	s_waitcnt lgkmcnt(8)
	v_mfma_f32_16x16x32_bf16 v[140:143], v[88:91], v[60:63], v[140:143]
	v_mfma_f32_16x16x32_bf16 v[24:27], v[88:91], v[124:127], v[24:27]
	v_mfma_f32_16x16x32_bf16 v[144:147], v[96:99], v[60:63], v[144:147]
	v_mfma_f32_16x16x32_bf16 v[32:35], v[96:99], v[124:127], v[32:35]
	s_waitcnt lgkmcnt(4)
	v_mfma_f32_16x16x32_bf16 v[148:151], v[104:107], v[60:63], v[148:151]
	v_mfma_f32_16x16x32_bf16 v[40:43], v[104:107], v[124:127], v[40:43]
	v_mfma_f32_16x16x32_bf16 v[152:155], v[112:115], v[60:63], v[152:155]
	v_mfma_f32_16x16x32_bf16 v[48:51], v[112:115], v[124:127], v[48:51]
	s_waitcnt lgkmcnt(0)
; __device__ __forceinline__ unsigned cvt_pk_bf16(float lo, float hi) { const f32x2v v = {lo, hi}; const b16x2v r = __builtin_convertvector(v, b16x2v); return __builtin_bit_cast(unsigned, r); }
; __device__ void cross_items(const Params& p, LAS unsigned char* lds) {
;     ...
;             for (int c8 = 0; c8 < 8; ++c8) { u32x2 wv; wv.x = cvt_pk_bf16(ot[c8][0] * inv, ot[c8][1] * inv); wv.y = cvt_pk_bf16(ot[c8][2] * inv, ot[c8][3] * inv);
;                 *(u32x2*)(oc + tok * DM + head * 512 + c * 128 + 16 * c8 + 4 * g) = wv; }
;         }
;     }
;     ...
;     asm volatile("s_waitcnt vmcnt(0)" ::: "memory");
;     __syncthreads();
	v_mfma_f32_16x16x32_bf16 v[156:159], v[120:123], v[60:63], v[156:159]
	v_mfma_f32_16x16x32_bf16 v[56:59], v[120:123], v[124:127], v[56:59]
	v_mfma_f32_16x16x32_bf16 v[160:163], v[128:131], v[60:63], v[160:163]
	v_mfma_f32_16x16x32_bf16 v[64:67], v[128:131], v[124:127], v[64:67]
	s_nop 7
	s_nop 7
	v_mul_f32_e32 v230, v244, v132
	v_mul_f32_e32 v231, v244, v133
	v_mul_f32_e32 v232, v244, v134
	v_mul_f32_e32 v233, v244, v135
	v_cvt_pk_bf16_f32 v230, v230, v231
	v_cvt_pk_bf16_f32 v231, v232, v233
	global_store_dwordx2 v248, v[230:231], s[92:93] offset:768
	v_mul_f32_e32 v234, v244, v136
	v_mul_f32_e32 v235, v244, v137
	v_mul_f32_e32 v236, v244, v138
	v_mul_f32_e32 v237, v244, v139
	v_cvt_pk_bf16_f32 v234, v234, v235
	v_cvt_pk_bf16_f32 v235, v236, v237
	global_store_dwordx2 v248, v[234:235], s[92:93] offset:800
	v_mul_f32_e32 v230, v244, v140
	v_mul_f32_e32 v231, v244, v141
	v_mul_f32_e32 v232, v244, v142
	v_mul_f32_e32 v233, v244, v143
	v_cvt_pk_bf16_f32 v230, v230, v231
	v_cvt_pk_bf16_f32 v231, v232, v233
	global_store_dwordx2 v248, v[230:231], s[92:93] offset:832
	v_mul_f32_e32 v234, v244, v144
	v_mul_f32_e32 v235, v244, v145
	v_mul_f32_e32 v236, v244, v146
	v_mul_f32_e32 v237, v244, v147
	v_cvt_pk_bf16_f32 v234, v234, v235
	v_cvt_pk_bf16_f32 v235, v236, v237
	global_store_dwordx2 v248, v[234:235], s[92:93] offset:864
	v_mul_f32_e32 v230, v244, v148
	v_mul_f32_e32 v231, v244, v149
	v_mul_f32_e32 v232, v244, v150
	v_mul_f32_e32 v233, v244, v151
	v_cvt_pk_bf16_f32 v230, v230, v231
	v_cvt_pk_bf16_f32 v231, v232, v233
	global_store_dwordx2 v248, v[230:231], s[92:93] offset:896
	v_mul_f32_e32 v234, v244, v152
	v_mul_f32_e32 v235, v244, v153
	v_mul_f32_e32 v236, v244, v154
	v_mul_f32_e32 v237, v244, v155
	v_cvt_pk_bf16_f32 v234, v234, v235
	v_cvt_pk_bf16_f32 v235, v236, v237
	global_store_dwordx2 v248, v[234:235], s[92:93] offset:928
	v_mul_f32_e32 v230, v244, v156
	v_mul_f32_e32 v231, v244, v157
	v_mul_f32_e32 v232, v244, v158
	v_mul_f32_e32 v233, v244, v159
	v_cvt_pk_bf16_f32 v230, v230, v231
	v_cvt_pk_bf16_f32 v231, v232, v233
	global_store_dwordx2 v248, v[230:231], s[92:93] offset:960
	v_mul_f32_e32 v234, v244, v160
	v_mul_f32_e32 v235, v244, v161
	v_mul_f32_e32 v236, v244, v162
	v_mul_f32_e32 v237, v244, v163
	v_cvt_pk_bf16_f32 v234, v234, v235
	v_cvt_pk_bf16_f32 v235, v236, v237
	global_store_dwordx2 v248, v[234:235], s[92:93] offset:992
	v_mul_f32_e32 v230, v245, v8
	v_mul_f32_e32 v231, v245, v9
	v_mul_f32_e32 v232, v245, v10
	v_mul_f32_e32 v233, v245, v11
	v_cvt_pk_bf16_f32 v230, v230, v231
	v_cvt_pk_bf16_f32 v231, v232, v233
	global_store_dwordx2 v249, v[230:231], s[92:93] offset:768
	v_mul_f32_e32 v234, v245, v16
	v_mul_f32_e32 v235, v245, v17
	v_mul_f32_e32 v236, v245, v18
	v_mul_f32_e32 v237, v245, v19
	v_cvt_pk_bf16_f32 v234, v234, v235
	v_cvt_pk_bf16_f32 v235, v236, v237
	global_store_dwordx2 v249, v[234:235], s[92:93] offset:800
	v_mul_f32_e32 v230, v245, v24
	v_mul_f32_e32 v231, v245, v25
	v_mul_f32_e32 v232, v245, v26
	v_mul_f32_e32 v233, v245, v27
	v_cvt_pk_bf16_f32 v230, v230, v231
	v_cvt_pk_bf16_f32 v231, v232, v233
	global_store_dwordx2 v249, v[230:231], s[92:93] offset:832
	v_mul_f32_e32 v234, v245, v32
	v_mul_f32_e32 v235, v245, v33
	v_mul_f32_e32 v236, v245, v34
	v_mul_f32_e32 v237, v245, v35
	v_cvt_pk_bf16_f32 v234, v234, v235
	v_cvt_pk_bf16_f32 v235, v236, v237
	global_store_dwordx2 v249, v[234:235], s[92:93] offset:864
	v_mul_f32_e32 v230, v245, v40
	v_mul_f32_e32 v231, v245, v41
	v_mul_f32_e32 v232, v245, v42
	v_mul_f32_e32 v233, v245, v43
	v_cvt_pk_bf16_f32 v230, v230, v231
	v_cvt_pk_bf16_f32 v231, v232, v233
	global_store_dwordx2 v249, v[230:231], s[92:93] offset:896
	v_mul_f32_e32 v234, v245, v48
	v_mul_f32_e32 v235, v245, v49
	v_mul_f32_e32 v236, v245, v50
	v_mul_f32_e32 v237, v245, v51
	v_cvt_pk_bf16_f32 v234, v234, v235
	v_cvt_pk_bf16_f32 v235, v236, v237
	global_store_dwordx2 v249, v[234:235], s[92:93] offset:928
	v_mul_f32_e32 v230, v245, v56
	v_mul_f32_e32 v231, v245, v57
	v_mul_f32_e32 v232, v245, v58
	v_mul_f32_e32 v233, v245, v59
	v_cvt_pk_bf16_f32 v230, v230, v231
	v_cvt_pk_bf16_f32 v231, v232, v233
	global_store_dwordx2 v249, v[230:231], s[92:93] offset:960
	v_mul_f32_e32 v234, v245, v64
	v_mul_f32_e32 v235, v245, v65
	v_mul_f32_e32 v236, v245, v66
	v_mul_f32_e32 v237, v245, v67
	v_cvt_pk_bf16_f32 v234, v234, v235
	v_cvt_pk_bf16_f32 v235, v236, v237
	global_store_dwordx2 v249, v[234:235], s[92:93] offset:992
	s_waitcnt vmcnt(0)
	s_waitcnt lgkmcnt(0)
	s_barrier

; __device__ __forceinline__ unsigned xb_ld(unsigned* p)              { return __hip_atomic_load(p, __ATOMIC_RELAXED, __HIP_MEMORY_SCOPE_AGENT); }
; __device__ __forceinline__ void xcd_barrier_complete(unsigned* bar, unsigned x, unsigned& nloc, unsigned& nx) {
;     ...
;     for (;;) {
;         sum = 0u; cnt = 0u; mine = 0u;
; #pragma unroll
;         for (unsigned j = 0; j < 16; ++j) { const unsigned c = xb_ld(&bar[XB_XCNT(j)]); sum += c; cnt += (c > 0u) ? 1u : 0u; mine = (j == x) ? c : mine; }
;         if (sum == G) break;
.LBB0_489:
	v_readlane_b32 s6, v253, 55
	s_waitcnt lgkmcnt(0)
	v_readlane_b32 s4, v252, 25
	v_readlane_b32 s5, v252, 26
	s_nop 4
	global_load_dword v0, v3, s[4:5] sc1
	v_readlane_b32 s4, v252, 27
	v_readlane_b32 s5, v252, 28
	s_nop 4
	global_load_dword v1, v3, s[4:5] sc1
	v_readlane_b32 s4, v252, 29
	v_readlane_b32 s5, v252, 30
	s_nop 4
	global_load_dword v2, v3, s[4:5] sc1
	v_readlane_b32 s4, v252, 31
	v_readlane_b32 s5, v252, 32
	s_nop 4
	global_load_dword v4, v3, s[4:5] sc1
	v_readlane_b32 s4, v252, 33
	v_readlane_b32 s5, v252, 34
	s_nop 4
	global_load_dword v5, v3, s[4:5] sc1
	v_readlane_b32 s4, v252, 35
	v_readlane_b32 s5, v252, 36
	s_nop 4
	global_load_dword v6, v3, s[4:5] sc1
	v_readlane_b32 s4, v252, 37
	v_readlane_b32 s5, v252, 38
	s_nop 4
	global_load_dword v7, v3, s[4:5] sc1
	v_readlane_b32 s4, v252, 39
	v_readlane_b32 s5, v252, 40
	s_nop 4
	global_load_dword v8, v3, s[4:5] sc1
	v_readlane_b32 s4, v252, 41
	v_readlane_b32 s5, v252, 42
	s_nop 4
	global_load_dword v9, v3, s[4:5] sc1
	v_readlane_b32 s4, v252, 43
	v_readlane_b32 s5, v252, 44
	s_nop 4
	global_load_dword v10, v3, s[4:5] sc1
	v_readlane_b32 s4, v252, 45
	v_readlane_b32 s5, v252, 46
	s_nop 4
	global_load_dword v11, v3, s[4:5] sc1
	v_readlane_b32 s4, v252, 47
	v_readlane_b32 s5, v252, 48
	s_nop 4
	global_load_dword v12, v3, s[4:5] sc1
	v_readlane_b32 s4, v252, 49
	v_readlane_b32 s5, v252, 50
	s_nop 4
	global_load_dword v13, v3, s[4:5] sc1
	v_readlane_b32 s4, v252, 51
	v_readlane_b32 s5, v252, 52
	s_nop 4
	global_load_dword v14, v3, s[4:5] sc1
	v_readlane_b32 s4, v252, 53
	v_readlane_b32 s5, v252, 54
	s_nop 4
	global_load_dword v15, v3, s[4:5] sc1
	v_readlane_b32 s4, v252, 55
	v_readlane_b32 s5, v252, 56
	s_nop 4
	global_load_dword v16, v3, s[4:5] sc1
	s_mov_b64 s[4:5], -1
	s_waitcnt vmcnt(0)
	v_add_u32_e32 v17, v1, v0
	v_add_u32_e32 v17, v17, v2
	v_add_u32_e32 v17, v17, v4
	v_add_u32_e32 v17, v17, v5
	v_add_u32_e32 v17, v17, v6
	v_add_u32_e32 v17, v17, v7
	v_add_u32_e32 v17, v17, v8
	v_add_u32_e32 v17, v17, v9
	v_add_u32_e32 v17, v17, v10
	v_add_u32_e32 v17, v17, v11
	v_add_u32_e32 v17, v17, v12
	v_add_u32_e32 v17, v17, v13
	v_add_u32_e32 v17, v17, v14
	v_add_u32_e32 v17, v17, v15
	v_add_u32_e32 v17, v17, v16
	v_cmp_eq_u32_e32 vcc, s6, v17
	s_mov_b64 s[6:7], -1
	s_cbranch_vccnz .LBB0_488
	s_and_b32 s4, s10, 0xff
	s_cmp_eq_u32 s4, 0
	s_mov_b64 s[4:5], -1
	s_mov_b64 s[8:9], -1
	s_sleep 1
	s_cbranch_scc0 .LBB0_493
	v_readlane_b32 s4, v252, 23
	v_readlane_b32 s5, v252, 24
	s_nop 4
	global_load_dword v17, v3, s[4:5] sc1
	s_waitcnt vmcnt(0)
	v_cmp_eq_u32_e32 vcc, 0, v17
	s_cbranch_vccnz .LBB0_495
	s_mov_b64 s[8:9], 0
	s_mov_b64 s[4:5], -1
